# context-projection GEMM units moved from phase 1 (32 lone WGs beside the streaming rmsnorm) to phase 2 via the ProbIn<2> unit path; phase-1 ctx rows and x rows rmsnorm loops rewritten by hand (params
# speedup vs baseline: 1.0709x; 1.0225x over previous
.LBB0_156:
	s_or_b64 exec, exec, s[0:1]
	s_cmpk_eq_i32 s82, 0x100
	s_cselect_b64 s[2:3], -1, 0
	s_cmpk_lg_i32 s82, 0x100
	s_cselect_b64 s[0:1], -1, 0
	v_writelane_b32 v240, s0, 11
	s_cmp_lt_i32 s81, 32
	v_lshrrev_b32_e32 v205, 6, v193
	v_writelane_b32 v240, s1, 12
	s_cselect_b64 s[0:1], -1, 0
	v_writelane_b32 v240, s2, 23
	v_and_b32_e32 v192, 63, v193
	v_mbcnt_lo_u32_b32 v207, -1, 0
	v_writelane_b32 v240, s3, 24
	s_and_b64 s[2:3], s[0:1], s[2:3]
	s_andn2_b64 vcc, exec, s[2:3]
	s_waitcnt lgkmcnt(0)
	s_barrier
	s_cbranch_vccnz .LBB0_168
	v_readfirstlane_b32 s3, v205
	v_lshlrev_b32_e32 v194, 4, v192
	v_lshlrev_b32_e32 v196, 3, v192
	v_mbcnt_hi_u32_b32 v197, -1, v207
	v_readlane_b32 s18, v241, 2
	v_readlane_b32 s19, v241, 3
	v_add_u32_e32 v195, 0x1000, v194
	v_xor_b32_e32 v198, 32, v197
	v_lshlrev_b32_e32 v198, 2, v198
	v_xor_b32_e32 v199, 16, v197
	v_lshlrev_b32_e32 v199, 2, v199
	v_xor_b32_e32 v200, 8, v197
	v_lshlrev_b32_e32 v200, 2, v200
	v_xor_b32_e32 v201, 4, v197
	v_lshlrev_b32_e32 v201, 2, v201
	v_xor_b32_e32 v202, 2, v197
	v_lshlrev_b32_e32 v202, 2, v202
	v_xor_b32_e32 v203, 1, v197
	v_lshlrev_b32_e32 v203, 2, v203
	v_mov_b32_e32 v208, 0x358637bd
	s_mov_b32 s27, 0x800000
	s_lshr_b32 s2, s81, 2
	s_lshl_b32 s2, s2, 8
	s_lshl_b32 s3, s3, 5
	s_add_u32 s2, s2, s3
	s_lshl_b32 s4, s2, 12
	s_add_u32 s14, s56, s4
	s_addc_u32 s15, s57, 0
	s_add_u32 s2, s2, 0x8000
	s_lshl_b32 s4, s2, 11
	s_add_u32 s10, s94, s4
	s_addc_u32 s11, s95, 0
	s_add_u32 s16, s18, 0x18000
	s_addc_u32 s17, s19, 0
	global_load_dwordx4 v[0:3], v194, s[60:61]
	global_load_dwordx4 v[4:7], v194, s[60:61] offset:1024
	global_load_dwordx4 v[8:11], v194, s[60:61] offset:2048
	global_load_dwordx4 v[12:15], v194, s[60:61] offset:3072
	global_load_dwordx4 v[160:163], v194, s[16:17]
	global_load_dwordx4 v[164:167], v194, s[16:17] offset:1024
	global_load_dwordx4 v[168:171], v194, s[16:17] offset:2048
	global_load_dwordx4 v[172:175], v194, s[16:17] offset:3072
	global_load_dwordx4 v[144:147], v195, s[16:17]
	global_load_dwordx4 v[148:151], v195, s[16:17] offset:1024
	global_load_dwordx4 v[152:155], v195, s[16:17] offset:2048
	global_load_dwordx4 v[156:159], v195, s[16:17] offset:3072
	global_load_dwordx4 v[16:19], v194, s[14:15]
	global_load_dwordx4 v[20:23], v194, s[14:15] offset:1024
	global_load_dwordx4 v[24:27], v194, s[14:15] offset:2048
	global_load_dwordx4 v[28:31], v194, s[14:15] offset:3072
	global_load_dwordx4 v[32:35], v195, s[14:15]
	global_load_dwordx4 v[36:39], v195, s[14:15] offset:1024
	global_load_dwordx4 v[40:43], v195, s[14:15] offset:2048
	global_load_dwordx4 v[44:47], v195, s[14:15] offset:3072
	s_add_u32 s14, s14, 0x2000
	s_addc_u32 s15, s15, 0
	global_load_dwordx4 v[48:51], v194, s[14:15]
	global_load_dwordx4 v[52:55], v194, s[14:15] offset:1024
	global_load_dwordx4 v[56:59], v194, s[14:15] offset:2048
	global_load_dwordx4 v[60:63], v194, s[14:15] offset:3072
	global_load_dwordx4 v[64:67], v195, s[14:15]
	global_load_dwordx4 v[68:71], v195, s[14:15] offset:1024
	global_load_dwordx4 v[72:75], v195, s[14:15] offset:2048
	global_load_dwordx4 v[76:79], v195, s[14:15] offset:3072
	s_add_u32 s14, s14, 0x2000
	s_addc_u32 s15, s15, 0
	global_load_dwordx4 v[80:83], v194, s[14:15]
	global_load_dwordx4 v[84:87], v194, s[14:15] offset:1024
	global_load_dwordx4 v[88:91], v194, s[14:15] offset:2048
	global_load_dwordx4 v[92:95], v194, s[14:15] offset:3072
	global_load_dwordx4 v[96:99], v195, s[14:15]
	global_load_dwordx4 v[100:103], v195, s[14:15] offset:1024
	global_load_dwordx4 v[104:107], v195, s[14:15] offset:2048
	global_load_dwordx4 v[108:111], v195, s[14:15] offset:3072
	s_add_u32 s14, s14, 0x2000
	s_addc_u32 s15, s15, 0
	global_load_dwordx4 v[112:115], v194, s[14:15]
	global_load_dwordx4 v[116:119], v194, s[14:15] offset:1024
	global_load_dwordx4 v[120:123], v194, s[14:15] offset:2048
	global_load_dwordx4 v[124:127], v194, s[14:15] offset:3072
	global_load_dwordx4 v[128:131], v195, s[14:15]
	global_load_dwordx4 v[132:135], v195, s[14:15] offset:1024
	global_load_dwordx4 v[136:139], v195, s[14:15] offset:2048
	global_load_dwordx4 v[140:143], v195, s[14:15] offset:3072
	s_waitcnt vmcnt(32)
	v_add_f32_e32 v144, 1.0, v144
	v_add_f32_e32 v145, 1.0, v145
	v_add_f32_e32 v146, 1.0, v146
	v_add_f32_e32 v147, 1.0, v147
	v_add_f32_e32 v148, 1.0, v148
	v_add_f32_e32 v149, 1.0, v149
	v_add_f32_e32 v150, 1.0, v150
	v_add_f32_e32 v151, 1.0, v151
	v_add_f32_e32 v152, 1.0, v152
	v_add_f32_e32 v153, 1.0, v153
	v_add_f32_e32 v154, 1.0, v154
	v_add_f32_e32 v155, 1.0, v155
	v_add_f32_e32 v156, 1.0, v156
	v_add_f32_e32 v157, 1.0, v157
	v_add_f32_e32 v158, 1.0, v158
	v_add_f32_e32 v159, 1.0, v159
	s_waitcnt vmcnt(24)
	v_pk_mul_f32 v[178:179], v[16:17], v[16:17]
	v_pk_fma_f32 v[178:179], v[18:19], v[18:19], v[178:179]
	v_pk_fma_f32 v[178:179], v[20:21], v[20:21], v[178:179]
	v_pk_fma_f32 v[178:179], v[22:23], v[22:23], v[178:179]
	v_pk_fma_f32 v[178:179], v[24:25], v[24:25], v[178:179]
	v_pk_fma_f32 v[178:179], v[26:27], v[26:27], v[178:179]
	v_pk_fma_f32 v[178:179], v[28:29], v[28:29], v[178:179]
	v_pk_fma_f32 v[178:179], v[30:31], v[30:31], v[178:179]
	v_pk_mul_f32 v[180:181], v[32:33], v[32:33]
	v_pk_fma_f32 v[180:181], v[34:35], v[34:35], v[180:181]
	v_pk_fma_f32 v[180:181], v[36:37], v[36:37], v[180:181]
	v_pk_fma_f32 v[180:181], v[38:39], v[38:39], v[180:181]
	v_pk_fma_f32 v[180:181], v[40:41], v[40:41], v[180:181]
	v_pk_fma_f32 v[180:181], v[42:43], v[42:43], v[180:181]
	v_pk_fma_f32 v[180:181], v[44:45], v[44:45], v[180:181]
	v_pk_fma_f32 v[180:181], v[46:47], v[46:47], v[180:181]
	v_add_f32_e32 v176, v178, v179
	v_add_f32_e32 v177, v180, v181
	ds_bpermute_b32 v178, v198, v176
	ds_bpermute_b32 v179, v198, v177
	s_waitcnt lgkmcnt(0)
	v_add_f32_e32 v176, v176, v178
	v_add_f32_e32 v177, v177, v179
	ds_bpermute_b32 v178, v199, v176
	ds_bpermute_b32 v179, v199, v177
	s_waitcnt lgkmcnt(0)
	v_add_f32_e32 v176, v176, v178
	v_add_f32_e32 v177, v177, v179
	ds_bpermute_b32 v178, v200, v176
	ds_bpermute_b32 v179, v200, v177
	s_waitcnt lgkmcnt(0)
	v_add_f32_e32 v176, v176, v178
	v_add_f32_e32 v177, v177, v179
	ds_bpermute_b32 v178, v201, v176
	ds_bpermute_b32 v179, v201, v177
	s_waitcnt lgkmcnt(0)
	v_add_f32_e32 v176, v176, v178
	v_add_f32_e32 v177, v177, v179
	ds_bpermute_b32 v178, v202, v176
	ds_bpermute_b32 v179, v202, v177
	s_waitcnt lgkmcnt(0)
	v_add_f32_e32 v176, v176, v178
	v_add_f32_e32 v177, v177, v179
	ds_bpermute_b32 v178, v203, v176
	ds_bpermute_b32 v179, v203, v177
	s_waitcnt lgkmcnt(0)
	v_add_f32_e32 v176, v176, v178
	v_add_f32_e32 v177, v177, v179
	v_fmamk_f32 v176, v176, 0x3a800000, v208
	v_mul_f32_e32 v178, 0x4b800000, v176
	v_cmp_gt_f32_e32 vcc, s27, v176
	s_nop 1
	v_cndmask_b32_e32 v176, v176, v178, vcc
	v_rsq_f32_e32 v209, v176
	s_nop 0
	v_mul_f32_e32 v178, 0x45800000, v209
	v_cndmask_b32_e32 v209, v209, v178, vcc
	v_fmamk_f32 v177, v177, 0x3a800000, v208
	v_mul_f32_e32 v178, 0x4b800000, v177
	v_cmp_gt_f32_e32 vcc, s27, v177
	s_nop 1
	v_cndmask_b32_e32 v177, v177, v178, vcc
	v_rsq_f32_e32 v210, v177
	s_nop 0
	v_mul_f32_e32 v178, 0x45800000, v210
	v_cndmask_b32_e32 v210, v210, v178, vcc
	v_mul_f32_e32 v16, v16, v209
	v_mul_f32_e32 v16, v0, v16
	v_fma_f32 v16, v144, v16, v160
	v_mul_f32_e32 v17, v17, v209
	v_mul_f32_e32 v17, v1, v17
	v_fma_f32 v17, v145, v17, v161
	v_mul_f32_e32 v18, v18, v209
	v_mul_f32_e32 v18, v2, v18
	v_fma_f32 v18, v146, v18, v162
	v_mul_f32_e32 v19, v19, v209
	v_mul_f32_e32 v19, v3, v19
	v_fma_f32 v19, v147, v19, v163
	v_cvt_pk_bf16_f32 v180, v16, v17
	v_cvt_pk_bf16_f32 v181, v18, v19
	global_store_dwordx2 v196, v[180:181], s[10:11]
	s_nop 0
	v_mul_f32_e32 v20, v20, v209
	v_mul_f32_e32 v20, v4, v20
	v_fma_f32 v20, v148, v20, v164
	v_mul_f32_e32 v21, v21, v209
	v_mul_f32_e32 v21, v5, v21
	v_fma_f32 v21, v149, v21, v165
	v_mul_f32_e32 v22, v22, v209
	v_mul_f32_e32 v22, v6, v22
	v_fma_f32 v22, v150, v22, v166
	v_mul_f32_e32 v23, v23, v209
	v_mul_f32_e32 v23, v7, v23
	v_fma_f32 v23, v151, v23, v167
	v_cvt_pk_bf16_f32 v180, v20, v21
	v_cvt_pk_bf16_f32 v181, v22, v23
	global_store_dwordx2 v196, v[180:181], s[10:11] offset:512
	s_nop 0
	v_mul_f32_e32 v24, v24, v209
	v_mul_f32_e32 v24, v8, v24
	v_fma_f32 v24, v152, v24, v168
	v_mul_f32_e32 v25, v25, v209
	v_mul_f32_e32 v25, v9, v25
	v_fma_f32 v25, v153, v25, v169
	v_mul_f32_e32 v26, v26, v209
	v_mul_f32_e32 v26, v10, v26
	v_fma_f32 v26, v154, v26, v170
	v_mul_f32_e32 v27, v27, v209
	v_mul_f32_e32 v27, v11, v27
	v_fma_f32 v27, v155, v27, v171
	v_cvt_pk_bf16_f32 v180, v24, v25
	v_cvt_pk_bf16_f32 v181, v26, v27
	global_store_dwordx2 v196, v[180:181], s[10:11] offset:1024
	s_nop 0
	v_mul_f32_e32 v28, v28, v209
	v_mul_f32_e32 v28, v12, v28
	v_fma_f32 v28, v156, v28, v172
	v_mul_f32_e32 v29, v29, v209
	v_mul_f32_e32 v29, v13, v29
	v_fma_f32 v29, v157, v29, v173
	v_mul_f32_e32 v30, v30, v209
	v_mul_f32_e32 v30, v14, v30
	v_fma_f32 v30, v158, v30, v174
	v_mul_f32_e32 v31, v31, v209
	v_mul_f32_e32 v31, v15, v31
	v_fma_f32 v31, v159, v31, v175
	v_cvt_pk_bf16_f32 v180, v28, v29
	v_cvt_pk_bf16_f32 v181, v30, v31
	global_store_dwordx2 v196, v[180:181], s[10:11] offset:1536
	s_nop 0
	v_mul_f32_e32 v32, v32, v210
	v_mul_f32_e32 v32, v0, v32
	v_fma_f32 v32, v144, v32, v160
	v_mul_f32_e32 v33, v33, v210
	v_mul_f32_e32 v33, v1, v33
	v_fma_f32 v33, v145, v33, v161
	v_mul_f32_e32 v34, v34, v210
	v_mul_f32_e32 v34, v2, v34
	v_fma_f32 v34, v146, v34, v162
	v_mul_f32_e32 v35, v35, v210
	v_mul_f32_e32 v35, v3, v35
	v_fma_f32 v35, v147, v35, v163
	v_cvt_pk_bf16_f32 v180, v32, v33
	v_cvt_pk_bf16_f32 v181, v34, v35
	global_store_dwordx2 v196, v[180:181], s[10:11] offset:2048
	s_nop 0
	v_mul_f32_e32 v36, v36, v210
	v_mul_f32_e32 v36, v4, v36
	v_fma_f32 v36, v148, v36, v164
	v_mul_f32_e32 v37, v37, v210
	v_mul_f32_e32 v37, v5, v37
	v_fma_f32 v37, v149, v37, v165
	v_mul_f32_e32 v38, v38, v210
	v_mul_f32_e32 v38, v6, v38
	v_fma_f32 v38, v150, v38, v166
	v_mul_f32_e32 v39, v39, v210
	v_mul_f32_e32 v39, v7, v39
	v_fma_f32 v39, v151, v39, v167
	v_cvt_pk_bf16_f32 v180, v36, v37
	v_cvt_pk_bf16_f32 v181, v38, v39
	global_store_dwordx2 v196, v[180:181], s[10:11] offset:2560
	s_nop 0
	v_mul_f32_e32 v40, v40, v210
	v_mul_f32_e32 v40, v8, v40
	v_fma_f32 v40, v152, v40, v168
	v_mul_f32_e32 v41, v41, v210
	v_mul_f32_e32 v41, v9, v41
	v_fma_f32 v41, v153, v41, v169
	v_mul_f32_e32 v42, v42, v210
	v_mul_f32_e32 v42, v10, v42
	v_fma_f32 v42, v154, v42, v170
	v_mul_f32_e32 v43, v43, v210
	v_mul_f32_e32 v43, v11, v43
	v_fma_f32 v43, v155, v43, v171
	v_cvt_pk_bf16_f32 v180, v40, v41
	v_cvt_pk_bf16_f32 v181, v42, v43
	global_store_dwordx2 v196, v[180:181], s[10:11] offset:3072
	s_nop 0
	v_mul_f32_e32 v44, v44, v210
	v_mul_f32_e32 v44, v12, v44
	v_fma_f32 v44, v156, v44, v172
	v_mul_f32_e32 v45, v45, v210
	v_mul_f32_e32 v45, v13, v45
	v_fma_f32 v45, v157, v45, v173
	v_mul_f32_e32 v46, v46, v210
	v_mul_f32_e32 v46, v14, v46
	v_fma_f32 v46, v158, v46, v174
	v_mul_f32_e32 v47, v47, v210
	v_mul_f32_e32 v47, v15, v47
	v_fma_f32 v47, v159, v47, v175
	v_cvt_pk_bf16_f32 v180, v44, v45
	v_cvt_pk_bf16_f32 v181, v46, v47
	global_store_dwordx2 v196, v[180:181], s[10:11] offset:3584
	s_nop 0
	s_add_u32 s14, s14, 0x2000
	s_addc_u32 s15, s15, 0
	global_load_dwordx4 v[16:19], v194, s[14:15]
	global_load_dwordx4 v[20:23], v194, s[14:15] offset:1024
	global_load_dwordx4 v[24:27], v194, s[14:15] offset:2048
	global_load_dwordx4 v[28:31], v194, s[14:15] offset:3072
	global_load_dwordx4 v[32:35], v195, s[14:15]
	global_load_dwordx4 v[36:39], v195, s[14:15] offset:1024
	global_load_dwordx4 v[40:43], v195, s[14:15] offset:2048
	global_load_dwordx4 v[44:47], v195, s[14:15] offset:3072
	s_waitcnt vmcnt(32)
	v_pk_mul_f32 v[178:179], v[48:49], v[48:49]
	v_pk_fma_f32 v[178:179], v[50:51], v[50:51], v[178:179]
	v_pk_fma_f32 v[178:179], v[52:53], v[52:53], v[178:179]
	v_pk_fma_f32 v[178:179], v[54:55], v[54:55], v[178:179]
	v_pk_fma_f32 v[178:179], v[56:57], v[56:57], v[178:179]
	v_pk_fma_f32 v[178:179], v[58:59], v[58:59], v[178:179]
	v_pk_fma_f32 v[178:179], v[60:61], v[60:61], v[178:179]
	v_pk_fma_f32 v[178:179], v[62:63], v[62:63], v[178:179]
	v_pk_mul_f32 v[180:181], v[64:65], v[64:65]
	v_pk_fma_f32 v[180:181], v[66:67], v[66:67], v[180:181]
	v_pk_fma_f32 v[180:181], v[68:69], v[68:69], v[180:181]
	v_pk_fma_f32 v[180:181], v[70:71], v[70:71], v[180:181]
	v_pk_fma_f32 v[180:181], v[72:73], v[72:73], v[180:181]
	v_pk_fma_f32 v[180:181], v[74:75], v[74:75], v[180:181]
	v_pk_fma_f32 v[180:181], v[76:77], v[76:77], v[180:181]
	v_pk_fma_f32 v[180:181], v[78:79], v[78:79], v[180:181]
	v_add_f32_e32 v176, v178, v179
	v_add_f32_e32 v177, v180, v181
	ds_bpermute_b32 v178, v198, v176
	ds_bpermute_b32 v179, v198, v177
	s_waitcnt lgkmcnt(0)
	v_add_f32_e32 v176, v176, v178
	v_add_f32_e32 v177, v177, v179
	ds_bpermute_b32 v178, v199, v176
	ds_bpermute_b32 v179, v199, v177
	s_waitcnt lgkmcnt(0)
	v_add_f32_e32 v176, v176, v178
	v_add_f32_e32 v177, v177, v179
	ds_bpermute_b32 v178, v200, v176
	ds_bpermute_b32 v179, v200, v177
	s_waitcnt lgkmcnt(0)
	v_add_f32_e32 v176, v176, v178
	v_add_f32_e32 v177, v177, v179
	ds_bpermute_b32 v178, v201, v176
	ds_bpermute_b32 v179, v201, v177
	s_waitcnt lgkmcnt(0)
	v_add_f32_e32 v176, v176, v178
	v_add_f32_e32 v177, v177, v179
	ds_bpermute_b32 v178, v202, v176
	ds_bpermute_b32 v179, v202, v177
	s_waitcnt lgkmcnt(0)
	v_add_f32_e32 v176, v176, v178
	v_add_f32_e32 v177, v177, v179
	ds_bpermute_b32 v178, v203, v176
	ds_bpermute_b32 v179, v203, v177
	s_waitcnt lgkmcnt(0)
	v_add_f32_e32 v176, v176, v178
	v_add_f32_e32 v177, v177, v179
	v_fmamk_f32 v176, v176, 0x3a800000, v208
	v_mul_f32_e32 v178, 0x4b800000, v176
	v_cmp_gt_f32_e32 vcc, s27, v176
	s_nop 1
	v_cndmask_b32_e32 v176, v176, v178, vcc
	v_rsq_f32_e32 v209, v176
	s_nop 0
	v_mul_f32_e32 v178, 0x45800000, v209
	v_cndmask_b32_e32 v209, v209, v178, vcc
	v_fmamk_f32 v177, v177, 0x3a800000, v208
	v_mul_f32_e32 v178, 0x4b800000, v177
	v_cmp_gt_f32_e32 vcc, s27, v177
	s_nop 1
	v_cndmask_b32_e32 v177, v177, v178, vcc
	v_rsq_f32_e32 v210, v177
	s_nop 0
	v_mul_f32_e32 v178, 0x45800000, v210
	v_cndmask_b32_e32 v210, v210, v178, vcc
	s_add_u32 s10, s10, 0x1000
	s_addc_u32 s11, s11, 0
	v_mul_f32_e32 v48, v48, v209
	v_mul_f32_e32 v48, v0, v48
	v_fma_f32 v48, v144, v48, v160
	v_mul_f32_e32 v49, v49, v209
	v_mul_f32_e32 v49, v1, v49
	v_fma_f32 v49, v145, v49, v161
	v_mul_f32_e32 v50, v50, v209
	v_mul_f32_e32 v50, v2, v50
	v_fma_f32 v50, v146, v50, v162
	v_mul_f32_e32 v51, v51, v209
	v_mul_f32_e32 v51, v3, v51
	v_fma_f32 v51, v147, v51, v163
	v_cvt_pk_bf16_f32 v180, v48, v49
	v_cvt_pk_bf16_f32 v181, v50, v51
	global_store_dwordx2 v196, v[180:181], s[10:11]
	s_nop 0
	v_mul_f32_e32 v52, v52, v209
	v_mul_f32_e32 v52, v4, v52
	v_fma_f32 v52, v148, v52, v164
	v_mul_f32_e32 v53, v53, v209
	v_mul_f32_e32 v53, v5, v53
	v_fma_f32 v53, v149, v53, v165
	v_mul_f32_e32 v54, v54, v209
	v_mul_f32_e32 v54, v6, v54
	v_fma_f32 v54, v150, v54, v166
	v_mul_f32_e32 v55, v55, v209
	v_mul_f32_e32 v55, v7, v55
	v_fma_f32 v55, v151, v55, v167
	v_cvt_pk_bf16_f32 v180, v52, v53
	v_cvt_pk_bf16_f32 v181, v54, v55
	global_store_dwordx2 v196, v[180:181], s[10:11] offset:512
	s_nop 0
	v_mul_f32_e32 v56, v56, v209
	v_mul_f32_e32 v56, v8, v56
	v_fma_f32 v56, v152, v56, v168
	v_mul_f32_e32 v57, v57, v209
	v_mul_f32_e32 v57, v9, v57
	v_fma_f32 v57, v153, v57, v169
	v_mul_f32_e32 v58, v58, v209
	v_mul_f32_e32 v58, v10, v58
	v_fma_f32 v58, v154, v58, v170
	v_mul_f32_e32 v59, v59, v209
	v_mul_f32_e32 v59, v11, v59
	v_fma_f32 v59, v155, v59, v171
	v_cvt_pk_bf16_f32 v180, v56, v57
	v_cvt_pk_bf16_f32 v181, v58, v59
	global_store_dwordx2 v196, v[180:181], s[10:11] offset:1024
	s_nop 0
	v_mul_f32_e32 v60, v60, v209
	v_mul_f32_e32 v60, v12, v60
	v_fma_f32 v60, v156, v60, v172
	v_mul_f32_e32 v61, v61, v209
	v_mul_f32_e32 v61, v13, v61
	v_fma_f32 v61, v157, v61, v173
	v_mul_f32_e32 v62, v62, v209
	v_mul_f32_e32 v62, v14, v62
	v_fma_f32 v62, v158, v62, v174
	v_mul_f32_e32 v63, v63, v209
	v_mul_f32_e32 v63, v15, v63
	v_fma_f32 v63, v159, v63, v175
	v_cvt_pk_bf16_f32 v180, v60, v61
	v_cvt_pk_bf16_f32 v181, v62, v63
	global_store_dwordx2 v196, v[180:181], s[10:11] offset:1536
	s_nop 0
	v_mul_f32_e32 v64, v64, v210
	v_mul_f32_e32 v64, v0, v64
	v_fma_f32 v64, v144, v64, v160
	v_mul_f32_e32 v65, v65, v210
	v_mul_f32_e32 v65, v1, v65
	v_fma_f32 v65, v145, v65, v161
	v_mul_f32_e32 v66, v66, v210
	v_mul_f32_e32 v66, v2, v66
	v_fma_f32 v66, v146, v66, v162
	v_mul_f32_e32 v67, v67, v210
	v_mul_f32_e32 v67, v3, v67
	v_fma_f32 v67, v147, v67, v163
	v_cvt_pk_bf16_f32 v180, v64, v65
	v_cvt_pk_bf16_f32 v181, v66, v67
	global_store_dwordx2 v196, v[180:181], s[10:11] offset:2048
	s_nop 0
	v_mul_f32_e32 v68, v68, v210
	v_mul_f32_e32 v68, v4, v68
	v_fma_f32 v68, v148, v68, v164
	v_mul_f32_e32 v69, v69, v210
	v_mul_f32_e32 v69, v5, v69
	v_fma_f32 v69, v149, v69, v165
	v_mul_f32_e32 v70, v70, v210
	v_mul_f32_e32 v70, v6, v70
	v_fma_f32 v70, v150, v70, v166
	v_mul_f32_e32 v71, v71, v210
	v_mul_f32_e32 v71, v7, v71
	v_fma_f32 v71, v151, v71, v167
	v_cvt_pk_bf16_f32 v180, v68, v69
	v_cvt_pk_bf16_f32 v181, v70, v71
	global_store_dwordx2 v196, v[180:181], s[10:11] offset:2560
	s_nop 0
	v_mul_f32_e32 v72, v72, v210
	v_mul_f32_e32 v72, v8, v72
	v_fma_f32 v72, v152, v72, v168
	v_mul_f32_e32 v73, v73, v210
	v_mul_f32_e32 v73, v9, v73
	v_fma_f32 v73, v153, v73, v169
	v_mul_f32_e32 v74, v74, v210
	v_mul_f32_e32 v74, v10, v74
	v_fma_f32 v74, v154, v74, v170
	v_mul_f32_e32 v75, v75, v210
	v_mul_f32_e32 v75, v11, v75
	v_fma_f32 v75, v155, v75, v171
	v_cvt_pk_bf16_f32 v180, v72, v73
	v_cvt_pk_bf16_f32 v181, v74, v75
	global_store_dwordx2 v196, v[180:181], s[10:11] offset:3072
	s_nop 0
	v_mul_f32_e32 v76, v76, v210
	v_mul_f32_e32 v76, v12, v76
	v_fma_f32 v76, v156, v76, v172
	v_mul_f32_e32 v77, v77, v210
	v_mul_f32_e32 v77, v13, v77
	v_fma_f32 v77, v157, v77, v173
	v_mul_f32_e32 v78, v78, v210
	v_mul_f32_e32 v78, v14, v78
	v_fma_f32 v78, v158, v78, v174
	v_mul_f32_e32 v79, v79, v210
	v_mul_f32_e32 v79, v15, v79
	v_fma_f32 v79, v159, v79, v175
	v_cvt_pk_bf16_f32 v180, v76, v77
	v_cvt_pk_bf16_f32 v181, v78, v79
	global_store_dwordx2 v196, v[180:181], s[10:11] offset:3584
	s_nop 0
	s_add_u32 s14, s14, 0x2000
	s_addc_u32 s15, s15, 0
	global_load_dwordx4 v[48:51], v194, s[14:15]
	global_load_dwordx4 v[52:55], v194, s[14:15] offset:1024
	global_load_dwordx4 v[56:59], v194, s[14:15] offset:2048
	global_load_dwordx4 v[60:63], v194, s[14:15] offset:3072
	global_load_dwordx4 v[64:67], v195, s[14:15]
	global_load_dwordx4 v[68:71], v195, s[14:15] offset:1024
	global_load_dwordx4 v[72:75], v195, s[14:15] offset:2048
	global_load_dwordx4 v[76:79], v195, s[14:15] offset:3072
	s_waitcnt vmcnt(40)
	v_pk_mul_f32 v[178:179], v[80:81], v[80:81]
	v_pk_fma_f32 v[178:179], v[82:83], v[82:83], v[178:179]
	v_pk_fma_f32 v[178:179], v[84:85], v[84:85], v[178:179]
	v_pk_fma_f32 v[178:179], v[86:87], v[86:87], v[178:179]
	v_pk_fma_f32 v[178:179], v[88:89], v[88:89], v[178:179]
	v_pk_fma_f32 v[178:179], v[90:91], v[90:91], v[178:179]
	v_pk_fma_f32 v[178:179], v[92:93], v[92:93], v[178:179]
	v_pk_fma_f32 v[178:179], v[94:95], v[94:95], v[178:179]
	v_pk_mul_f32 v[180:181], v[96:97], v[96:97]
	v_pk_fma_f32 v[180:181], v[98:99], v[98:99], v[180:181]
	v_pk_fma_f32 v[180:181], v[100:101], v[100:101], v[180:181]
	v_pk_fma_f32 v[180:181], v[102:103], v[102:103], v[180:181]
	v_pk_fma_f32 v[180:181], v[104:105], v[104:105], v[180:181]
	v_pk_fma_f32 v[180:181], v[106:107], v[106:107], v[180:181]
	v_pk_fma_f32 v[180:181], v[108:109], v[108:109], v[180:181]
	v_pk_fma_f32 v[180:181], v[110:111], v[110:111], v[180:181]
	v_add_f32_e32 v176, v178, v179
	v_add_f32_e32 v177, v180, v181
	ds_bpermute_b32 v178, v198, v176
	ds_bpermute_b32 v179, v198, v177
	s_waitcnt lgkmcnt(0)
	v_add_f32_e32 v176, v176, v178
	v_add_f32_e32 v177, v177, v179
	ds_bpermute_b32 v178, v199, v176
	ds_bpermute_b32 v179, v199, v177
	s_waitcnt lgkmcnt(0)
	v_add_f32_e32 v176, v176, v178
	v_add_f32_e32 v177, v177, v179
	ds_bpermute_b32 v178, v200, v176
	ds_bpermute_b32 v179, v200, v177
	s_waitcnt lgkmcnt(0)
	v_add_f32_e32 v176, v176, v178
	v_add_f32_e32 v177, v177, v179
	ds_bpermute_b32 v178, v201, v176
	ds_bpermute_b32 v179, v201, v177
	s_waitcnt lgkmcnt(0)
	v_add_f32_e32 v176, v176, v178
	v_add_f32_e32 v177, v177, v179
	ds_bpermute_b32 v178, v202, v176
	ds_bpermute_b32 v179, v202, v177
	s_waitcnt lgkmcnt(0)
	v_add_f32_e32 v176, v176, v178
	v_add_f32_e32 v177, v177, v179
	ds_bpermute_b32 v178, v203, v176
	ds_bpermute_b32 v179, v203, v177
	s_waitcnt lgkmcnt(0)
	v_add_f32_e32 v176, v176, v178
	v_add_f32_e32 v177, v177, v179
	v_fmamk_f32 v176, v176, 0x3a800000, v208
	v_mul_f32_e32 v178, 0x4b800000, v176
	v_cmp_gt_f32_e32 vcc, s27, v176
	s_nop 1
	v_cndmask_b32_e32 v176, v176, v178, vcc
	v_rsq_f32_e32 v209, v176
	s_nop 0
	v_mul_f32_e32 v178, 0x45800000, v209
	v_cndmask_b32_e32 v209, v209, v178, vcc
	v_fmamk_f32 v177, v177, 0x3a800000, v208
	v_mul_f32_e32 v178, 0x4b800000, v177
	v_cmp_gt_f32_e32 vcc, s27, v177
	s_nop 1
	v_cndmask_b32_e32 v177, v177, v178, vcc
	v_rsq_f32_e32 v210, v177
	s_nop 0
	v_mul_f32_e32 v178, 0x45800000, v210
	v_cndmask_b32_e32 v210, v210, v178, vcc
	s_add_u32 s10, s10, 0x1000
	s_addc_u32 s11, s11, 0
	v_mul_f32_e32 v80, v80, v209
	v_mul_f32_e32 v80, v0, v80
	v_fma_f32 v80, v144, v80, v160
	v_mul_f32_e32 v81, v81, v209
	v_mul_f32_e32 v81, v1, v81
	v_fma_f32 v81, v145, v81, v161
	v_mul_f32_e32 v82, v82, v209
	v_mul_f32_e32 v82, v2, v82
	v_fma_f32 v82, v146, v82, v162
	v_mul_f32_e32 v83, v83, v209
	v_mul_f32_e32 v83, v3, v83
	v_fma_f32 v83, v147, v83, v163
	v_cvt_pk_bf16_f32 v180, v80, v81
	v_cvt_pk_bf16_f32 v181, v82, v83
	global_store_dwordx2 v196, v[180:181], s[10:11]
	s_nop 0
	v_mul_f32_e32 v84, v84, v209
	v_mul_f32_e32 v84, v4, v84
	v_fma_f32 v84, v148, v84, v164
	v_mul_f32_e32 v85, v85, v209
	v_mul_f32_e32 v85, v5, v85
	v_fma_f32 v85, v149, v85, v165
	v_mul_f32_e32 v86, v86, v209
	v_mul_f32_e32 v86, v6, v86
	v_fma_f32 v86, v150, v86, v166
	v_mul_f32_e32 v87, v87, v209
	v_mul_f32_e32 v87, v7, v87
	v_fma_f32 v87, v151, v87, v167
	v_cvt_pk_bf16_f32 v180, v84, v85
	v_cvt_pk_bf16_f32 v181, v86, v87
	global_store_dwordx2 v196, v[180:181], s[10:11] offset:512
	s_nop 0
	v_mul_f32_e32 v88, v88, v209
	v_mul_f32_e32 v88, v8, v88
	v_fma_f32 v88, v152, v88, v168
	v_mul_f32_e32 v89, v89, v209
	v_mul_f32_e32 v89, v9, v89
	v_fma_f32 v89, v153, v89, v169
	v_mul_f32_e32 v90, v90, v209
	v_mul_f32_e32 v90, v10, v90
	v_fma_f32 v90, v154, v90, v170
	v_mul_f32_e32 v91, v91, v209
	v_mul_f32_e32 v91, v11, v91
	v_fma_f32 v91, v155, v91, v171
	v_cvt_pk_bf16_f32 v180, v88, v89
	v_cvt_pk_bf16_f32 v181, v90, v91
	global_store_dwordx2 v196, v[180:181], s[10:11] offset:1024
	s_nop 0
	v_mul_f32_e32 v92, v92, v209
	v_mul_f32_e32 v92, v12, v92
	v_fma_f32 v92, v156, v92, v172
	v_mul_f32_e32 v93, v93, v209
	v_mul_f32_e32 v93, v13, v93
	v_fma_f32 v93, v157, v93, v173
	v_mul_f32_e32 v94, v94, v209
	v_mul_f32_e32 v94, v14, v94
	v_fma_f32 v94, v158, v94, v174
	v_mul_f32_e32 v95, v95, v209
	v_mul_f32_e32 v95, v15, v95
	v_fma_f32 v95, v159, v95, v175
	v_cvt_pk_bf16_f32 v180, v92, v93
	v_cvt_pk_bf16_f32 v181, v94, v95
	global_store_dwordx2 v196, v[180:181], s[10:11] offset:1536
	s_nop 0
	v_mul_f32_e32 v96, v96, v210
	v_mul_f32_e32 v96, v0, v96
	v_fma_f32 v96, v144, v96, v160
	v_mul_f32_e32 v97, v97, v210
	v_mul_f32_e32 v97, v1, v97
	v_fma_f32 v97, v145, v97, v161
	v_mul_f32_e32 v98, v98, v210
	v_mul_f32_e32 v98, v2, v98
	v_fma_f32 v98, v146, v98, v162
	v_mul_f32_e32 v99, v99, v210
	v_mul_f32_e32 v99, v3, v99
	v_fma_f32 v99, v147, v99, v163
	v_cvt_pk_bf16_f32 v180, v96, v97
	v_cvt_pk_bf16_f32 v181, v98, v99
	global_store_dwordx2 v196, v[180:181], s[10:11] offset:2048
	s_nop 0
	v_mul_f32_e32 v100, v100, v210
	v_mul_f32_e32 v100, v4, v100
	v_fma_f32 v100, v148, v100, v164
	v_mul_f32_e32 v101, v101, v210
	v_mul_f32_e32 v101, v5, v101
	v_fma_f32 v101, v149, v101, v165
	v_mul_f32_e32 v102, v102, v210
	v_mul_f32_e32 v102, v6, v102
	v_fma_f32 v102, v150, v102, v166
	v_mul_f32_e32 v103, v103, v210
	v_mul_f32_e32 v103, v7, v103
	v_fma_f32 v103, v151, v103, v167
	v_cvt_pk_bf16_f32 v180, v100, v101
	v_cvt_pk_bf16_f32 v181, v102, v103
	global_store_dwordx2 v196, v[180:181], s[10:11] offset:2560
	s_nop 0
	v_mul_f32_e32 v104, v104, v210
	v_mul_f32_e32 v104, v8, v104
	v_fma_f32 v104, v152, v104, v168
	v_mul_f32_e32 v105, v105, v210
	v_mul_f32_e32 v105, v9, v105
	v_fma_f32 v105, v153, v105, v169
	v_mul_f32_e32 v106, v106, v210
	v_mul_f32_e32 v106, v10, v106
	v_fma_f32 v106, v154, v106, v170
	v_mul_f32_e32 v107, v107, v210
	v_mul_f32_e32 v107, v11, v107
	v_fma_f32 v107, v155, v107, v171
	v_cvt_pk_bf16_f32 v180, v104, v105
	v_cvt_pk_bf16_f32 v181, v106, v107
	global_store_dwordx2 v196, v[180:181], s[10:11] offset:3072
	s_nop 0
	v_mul_f32_e32 v108, v108, v210
	v_mul_f32_e32 v108, v12, v108
	v_fma_f32 v108, v156, v108, v172
	v_mul_f32_e32 v109, v109, v210
	v_mul_f32_e32 v109, v13, v109
	v_fma_f32 v109, v157, v109, v173
	v_mul_f32_e32 v110, v110, v210
	v_mul_f32_e32 v110, v14, v110
	v_fma_f32 v110, v158, v110, v174
	v_mul_f32_e32 v111, v111, v210
	v_mul_f32_e32 v111, v15, v111
	v_fma_f32 v111, v159, v111, v175
	v_cvt_pk_bf16_f32 v180, v108, v109
	v_cvt_pk_bf16_f32 v181, v110, v111
	global_store_dwordx2 v196, v[180:181], s[10:11] offset:3584
	s_nop 0
	s_add_u32 s14, s14, 0x2000
	s_addc_u32 s15, s15, 0
	global_load_dwordx4 v[80:83], v194, s[14:15]
	global_load_dwordx4 v[84:87], v194, s[14:15] offset:1024
	global_load_dwordx4 v[88:91], v194, s[14:15] offset:2048
	global_load_dwordx4 v[92:95], v194, s[14:15] offset:3072
	global_load_dwordx4 v[96:99], v195, s[14:15]
	global_load_dwordx4 v[100:103], v195, s[14:15] offset:1024
	global_load_dwordx4 v[104:107], v195, s[14:15] offset:2048
	global_load_dwordx4 v[108:111], v195, s[14:15] offset:3072
	s_waitcnt vmcnt(48)
	v_pk_mul_f32 v[178:179], v[112:113], v[112:113]
	v_pk_fma_f32 v[178:179], v[114:115], v[114:115], v[178:179]
	v_pk_fma_f32 v[178:179], v[116:117], v[116:117], v[178:179]
	v_pk_fma_f32 v[178:179], v[118:119], v[118:119], v[178:179]
	v_pk_fma_f32 v[178:179], v[120:121], v[120:121], v[178:179]
	v_pk_fma_f32 v[178:179], v[122:123], v[122:123], v[178:179]
	v_pk_fma_f32 v[178:179], v[124:125], v[124:125], v[178:179]
	v_pk_fma_f32 v[178:179], v[126:127], v[126:127], v[178:179]
	v_pk_mul_f32 v[180:181], v[128:129], v[128:129]
	v_pk_fma_f32 v[180:181], v[130:131], v[130:131], v[180:181]
	v_pk_fma_f32 v[180:181], v[132:133], v[132:133], v[180:181]
	v_pk_fma_f32 v[180:181], v[134:135], v[134:135], v[180:181]
	v_pk_fma_f32 v[180:181], v[136:137], v[136:137], v[180:181]
	v_pk_fma_f32 v[180:181], v[138:139], v[138:139], v[180:181]
	v_pk_fma_f32 v[180:181], v[140:141], v[140:141], v[180:181]
	v_pk_fma_f32 v[180:181], v[142:143], v[142:143], v[180:181]
	v_add_f32_e32 v176, v178, v179
	v_add_f32_e32 v177, v180, v181
	ds_bpermute_b32 v178, v198, v176
	ds_bpermute_b32 v179, v198, v177
	s_waitcnt lgkmcnt(0)
	v_add_f32_e32 v176, v176, v178
	v_add_f32_e32 v177, v177, v179
	ds_bpermute_b32 v178, v199, v176
	ds_bpermute_b32 v179, v199, v177
	s_waitcnt lgkmcnt(0)
	v_add_f32_e32 v176, v176, v178
	v_add_f32_e32 v177, v177, v179
	ds_bpermute_b32 v178, v200, v176
	ds_bpermute_b32 v179, v200, v177
	s_waitcnt lgkmcnt(0)
	v_add_f32_e32 v176, v176, v178
	v_add_f32_e32 v177, v177, v179
	ds_bpermute_b32 v178, v201, v176
	ds_bpermute_b32 v179, v201, v177
	s_waitcnt lgkmcnt(0)
	v_add_f32_e32 v176, v176, v178
	v_add_f32_e32 v177, v177, v179
	ds_bpermute_b32 v178, v202, v176
	ds_bpermute_b32 v179, v202, v177
	s_waitcnt lgkmcnt(0)
	v_add_f32_e32 v176, v176, v178
	v_add_f32_e32 v177, v177, v179
	ds_bpermute_b32 v178, v203, v176
	ds_bpermute_b32 v179, v203, v177
	s_waitcnt lgkmcnt(0)
	v_add_f32_e32 v176, v176, v178
	v_add_f32_e32 v177, v177, v179
	v_fmamk_f32 v176, v176, 0x3a800000, v208
	v_mul_f32_e32 v178, 0x4b800000, v176
	v_cmp_gt_f32_e32 vcc, s27, v176
	s_nop 1
	v_cndmask_b32_e32 v176, v176, v178, vcc
	v_rsq_f32_e32 v209, v176
	s_nop 0
	v_mul_f32_e32 v178, 0x45800000, v209
	v_cndmask_b32_e32 v209, v209, v178, vcc
	v_fmamk_f32 v177, v177, 0x3a800000, v208
	v_mul_f32_e32 v178, 0x4b800000, v177
	v_cmp_gt_f32_e32 vcc, s27, v177
	s_nop 1
	v_cndmask_b32_e32 v177, v177, v178, vcc
	v_rsq_f32_e32 v210, v177
	s_nop 0
	v_mul_f32_e32 v178, 0x45800000, v210
	v_cndmask_b32_e32 v210, v210, v178, vcc
	s_add_u32 s10, s10, 0x1000
	s_addc_u32 s11, s11, 0
	v_mul_f32_e32 v112, v112, v209
	v_mul_f32_e32 v112, v0, v112
	v_fma_f32 v112, v144, v112, v160
	v_mul_f32_e32 v113, v113, v209
	v_mul_f32_e32 v113, v1, v113
	v_fma_f32 v113, v145, v113, v161
	v_mul_f32_e32 v114, v114, v209
	v_mul_f32_e32 v114, v2, v114
	v_fma_f32 v114, v146, v114, v162
	v_mul_f32_e32 v115, v115, v209
	v_mul_f32_e32 v115, v3, v115
	v_fma_f32 v115, v147, v115, v163
	v_cvt_pk_bf16_f32 v180, v112, v113
	v_cvt_pk_bf16_f32 v181, v114, v115
	global_store_dwordx2 v196, v[180:181], s[10:11]
	s_nop 0
	v_mul_f32_e32 v116, v116, v209
	v_mul_f32_e32 v116, v4, v116
	v_fma_f32 v116, v148, v116, v164
	v_mul_f32_e32 v117, v117, v209
	v_mul_f32_e32 v117, v5, v117
	v_fma_f32 v117, v149, v117, v165
	v_mul_f32_e32 v118, v118, v209
	v_mul_f32_e32 v118, v6, v118
	v_fma_f32 v118, v150, v118, v166
	v_mul_f32_e32 v119, v119, v209
	v_mul_f32_e32 v119, v7, v119
	v_fma_f32 v119, v151, v119, v167
	v_cvt_pk_bf16_f32 v180, v116, v117
	v_cvt_pk_bf16_f32 v181, v118, v119
	global_store_dwordx2 v196, v[180:181], s[10:11] offset:512
	s_nop 0
	v_mul_f32_e32 v120, v120, v209
	v_mul_f32_e32 v120, v8, v120
	v_fma_f32 v120, v152, v120, v168
	v_mul_f32_e32 v121, v121, v209
	v_mul_f32_e32 v121, v9, v121
	v_fma_f32 v121, v153, v121, v169
	v_mul_f32_e32 v122, v122, v209
	v_mul_f32_e32 v122, v10, v122
	v_fma_f32 v122, v154, v122, v170
	v_mul_f32_e32 v123, v123, v209
	v_mul_f32_e32 v123, v11, v123
	v_fma_f32 v123, v155, v123, v171
	v_cvt_pk_bf16_f32 v180, v120, v121
	v_cvt_pk_bf16_f32 v181, v122, v123
	global_store_dwordx2 v196, v[180:181], s[10:11] offset:1024
	s_nop 0
	v_mul_f32_e32 v124, v124, v209
	v_mul_f32_e32 v124, v12, v124
	v_fma_f32 v124, v156, v124, v172
	v_mul_f32_e32 v125, v125, v209
	v_mul_f32_e32 v125, v13, v125
	v_fma_f32 v125, v157, v125, v173
	v_mul_f32_e32 v126, v126, v209
	v_mul_f32_e32 v126, v14, v126
	v_fma_f32 v126, v158, v126, v174
	v_mul_f32_e32 v127, v127, v209
	v_mul_f32_e32 v127, v15, v127
	v_fma_f32 v127, v159, v127, v175
	v_cvt_pk_bf16_f32 v180, v124, v125
	v_cvt_pk_bf16_f32 v181, v126, v127
	global_store_dwordx2 v196, v[180:181], s[10:11] offset:1536
	s_nop 0
	v_mul_f32_e32 v128, v128, v210
	v_mul_f32_e32 v128, v0, v128
	v_fma_f32 v128, v144, v128, v160
	v_mul_f32_e32 v129, v129, v210
	v_mul_f32_e32 v129, v1, v129
	v_fma_f32 v129, v145, v129, v161
	v_mul_f32_e32 v130, v130, v210
	v_mul_f32_e32 v130, v2, v130
	v_fma_f32 v130, v146, v130, v162
	v_mul_f32_e32 v131, v131, v210
	v_mul_f32_e32 v131, v3, v131
	v_fma_f32 v131, v147, v131, v163
	v_cvt_pk_bf16_f32 v180, v128, v129
	v_cvt_pk_bf16_f32 v181, v130, v131
	global_store_dwordx2 v196, v[180:181], s[10:11] offset:2048
	s_nop 0
	v_mul_f32_e32 v132, v132, v210
	v_mul_f32_e32 v132, v4, v132
	v_fma_f32 v132, v148, v132, v164
	v_mul_f32_e32 v133, v133, v210
	v_mul_f32_e32 v133, v5, v133
	v_fma_f32 v133, v149, v133, v165
	v_mul_f32_e32 v134, v134, v210
	v_mul_f32_e32 v134, v6, v134
	v_fma_f32 v134, v150, v134, v166
	v_mul_f32_e32 v135, v135, v210
	v_mul_f32_e32 v135, v7, v135
	v_fma_f32 v135, v151, v135, v167
	v_cvt_pk_bf16_f32 v180, v132, v133
	v_cvt_pk_bf16_f32 v181, v134, v135
	global_store_dwordx2 v196, v[180:181], s[10:11] offset:2560
	s_nop 0
	v_mul_f32_e32 v136, v136, v210
	v_mul_f32_e32 v136, v8, v136
	v_fma_f32 v136, v152, v136, v168
	v_mul_f32_e32 v137, v137, v210
	v_mul_f32_e32 v137, v9, v137
	v_fma_f32 v137, v153, v137, v169
	v_mul_f32_e32 v138, v138, v210
	v_mul_f32_e32 v138, v10, v138
	v_fma_f32 v138, v154, v138, v170
	v_mul_f32_e32 v139, v139, v210
	v_mul_f32_e32 v139, v11, v139
	v_fma_f32 v139, v155, v139, v171
	v_cvt_pk_bf16_f32 v180, v136, v137
	v_cvt_pk_bf16_f32 v181, v138, v139
	global_store_dwordx2 v196, v[180:181], s[10:11] offset:3072
	s_nop 0
	v_mul_f32_e32 v140, v140, v210
	v_mul_f32_e32 v140, v12, v140
	v_fma_f32 v140, v156, v140, v172
	v_mul_f32_e32 v141, v141, v210
	v_mul_f32_e32 v141, v13, v141
	v_fma_f32 v141, v157, v141, v173
	v_mul_f32_e32 v142, v142, v210
	v_mul_f32_e32 v142, v14, v142
	v_fma_f32 v142, v158, v142, v174
	v_mul_f32_e32 v143, v143, v210
	v_mul_f32_e32 v143, v15, v143
	v_fma_f32 v143, v159, v143, v175
	v_cvt_pk_bf16_f32 v180, v140, v141
	v_cvt_pk_bf16_f32 v181, v142, v143
	global_store_dwordx2 v196, v[180:181], s[10:11] offset:3584
	s_nop 0
	s_add_u32 s14, s14, 0x2000
	s_addc_u32 s15, s15, 0
	global_load_dwordx4 v[112:115], v194, s[14:15]
	global_load_dwordx4 v[116:119], v194, s[14:15] offset:1024
	global_load_dwordx4 v[120:123], v194, s[14:15] offset:2048
	global_load_dwordx4 v[124:127], v194, s[14:15] offset:3072
	global_load_dwordx4 v[128:131], v195, s[14:15]
	global_load_dwordx4 v[132:135], v195, s[14:15] offset:1024
	global_load_dwordx4 v[136:139], v195, s[14:15] offset:2048
	global_load_dwordx4 v[140:143], v195, s[14:15] offset:3072
	s_waitcnt vmcnt(48)
	v_pk_mul_f32 v[178:179], v[16:17], v[16:17]
	v_pk_fma_f32 v[178:179], v[18:19], v[18:19], v[178:179]
	v_pk_fma_f32 v[178:179], v[20:21], v[20:21], v[178:179]
	v_pk_fma_f32 v[178:179], v[22:23], v[22:23], v[178:179]
	v_pk_fma_f32 v[178:179], v[24:25], v[24:25], v[178:179]
	v_pk_fma_f32 v[178:179], v[26:27], v[26:27], v[178:179]
	v_pk_fma_f32 v[178:179], v[28:29], v[28:29], v[178:179]
	v_pk_fma_f32 v[178:179], v[30:31], v[30:31], v[178:179]
	v_pk_mul_f32 v[180:181], v[32:33], v[32:33]
	v_pk_fma_f32 v[180:181], v[34:35], v[34:35], v[180:181]
	v_pk_fma_f32 v[180:181], v[36:37], v[36:37], v[180:181]
	v_pk_fma_f32 v[180:181], v[38:39], v[38:39], v[180:181]
	v_pk_fma_f32 v[180:181], v[40:41], v[40:41], v[180:181]
	v_pk_fma_f32 v[180:181], v[42:43], v[42:43], v[180:181]
	v_pk_fma_f32 v[180:181], v[44:45], v[44:45], v[180:181]
	v_pk_fma_f32 v[180:181], v[46:47], v[46:47], v[180:181]
	v_add_f32_e32 v176, v178, v179
	v_add_f32_e32 v177, v180, v181
	ds_bpermute_b32 v178, v198, v176
	ds_bpermute_b32 v179, v198, v177
	s_waitcnt lgkmcnt(0)
	v_add_f32_e32 v176, v176, v178
	v_add_f32_e32 v177, v177, v179
	ds_bpermute_b32 v178, v199, v176
	ds_bpermute_b32 v179, v199, v177
	s_waitcnt lgkmcnt(0)
	v_add_f32_e32 v176, v176, v178
	v_add_f32_e32 v177, v177, v179
	ds_bpermute_b32 v178, v200, v176
	ds_bpermute_b32 v179, v200, v177
	s_waitcnt lgkmcnt(0)
	v_add_f32_e32 v176, v176, v178
	v_add_f32_e32 v177, v177, v179
	ds_bpermute_b32 v178, v201, v176
	ds_bpermute_b32 v179, v201, v177
	s_waitcnt lgkmcnt(0)
	v_add_f32_e32 v176, v176, v178
	v_add_f32_e32 v177, v177, v179
	ds_bpermute_b32 v178, v202, v176
	ds_bpermute_b32 v179, v202, v177
	s_waitcnt lgkmcnt(0)
	v_add_f32_e32 v176, v176, v178
	v_add_f32_e32 v177, v177, v179
	ds_bpermute_b32 v178, v203, v176
	ds_bpermute_b32 v179, v203, v177
	s_waitcnt lgkmcnt(0)
	v_add_f32_e32 v176, v176, v178
	v_add_f32_e32 v177, v177, v179
	v_fmamk_f32 v176, v176, 0x3a800000, v208
	v_mul_f32_e32 v178, 0x4b800000, v176
	v_cmp_gt_f32_e32 vcc, s27, v176
	s_nop 1
	v_cndmask_b32_e32 v176, v176, v178, vcc
	v_rsq_f32_e32 v209, v176
	s_nop 0
	v_mul_f32_e32 v178, 0x45800000, v209
	v_cndmask_b32_e32 v209, v209, v178, vcc
	v_fmamk_f32 v177, v177, 0x3a800000, v208
	v_mul_f32_e32 v178, 0x4b800000, v177
	v_cmp_gt_f32_e32 vcc, s27, v177
	s_nop 1
	v_cndmask_b32_e32 v177, v177, v178, vcc
	v_rsq_f32_e32 v210, v177
	s_nop 0
	v_mul_f32_e32 v178, 0x45800000, v210
	v_cndmask_b32_e32 v210, v210, v178, vcc
	s_add_u32 s10, s10, 0x1000
	s_addc_u32 s11, s11, 0
	v_mul_f32_e32 v16, v16, v209
	v_mul_f32_e32 v16, v0, v16
	v_fma_f32 v16, v144, v16, v160
	v_mul_f32_e32 v17, v17, v209
	v_mul_f32_e32 v17, v1, v17
	v_fma_f32 v17, v145, v17, v161
	v_mul_f32_e32 v18, v18, v209
	v_mul_f32_e32 v18, v2, v18
	v_fma_f32 v18, v146, v18, v162
	v_mul_f32_e32 v19, v19, v209
	v_mul_f32_e32 v19, v3, v19
	v_fma_f32 v19, v147, v19, v163
	v_cvt_pk_bf16_f32 v180, v16, v17
	v_cvt_pk_bf16_f32 v181, v18, v19
	global_store_dwordx2 v196, v[180:181], s[10:11]
	s_nop 0
	v_mul_f32_e32 v20, v20, v209
	v_mul_f32_e32 v20, v4, v20
	v_fma_f32 v20, v148, v20, v164
	v_mul_f32_e32 v21, v21, v209
	v_mul_f32_e32 v21, v5, v21
	v_fma_f32 v21, v149, v21, v165
	v_mul_f32_e32 v22, v22, v209
	v_mul_f32_e32 v22, v6, v22
	v_fma_f32 v22, v150, v22, v166
	v_mul_f32_e32 v23, v23, v209
	v_mul_f32_e32 v23, v7, v23
	v_fma_f32 v23, v151, v23, v167
	v_cvt_pk_bf16_f32 v180, v20, v21
	v_cvt_pk_bf16_f32 v181, v22, v23
	global_store_dwordx2 v196, v[180:181], s[10:11] offset:512
	s_nop 0
	v_mul_f32_e32 v24, v24, v209
	v_mul_f32_e32 v24, v8, v24
	v_fma_f32 v24, v152, v24, v168
	v_mul_f32_e32 v25, v25, v209
	v_mul_f32_e32 v25, v9, v25
	v_fma_f32 v25, v153, v25, v169
	v_mul_f32_e32 v26, v26, v209
	v_mul_f32_e32 v26, v10, v26
	v_fma_f32 v26, v154, v26, v170
	v_mul_f32_e32 v27, v27, v209
	v_mul_f32_e32 v27, v11, v27
	v_fma_f32 v27, v155, v27, v171
	v_cvt_pk_bf16_f32 v180, v24, v25
	v_cvt_pk_bf16_f32 v181, v26, v27
	global_store_dwordx2 v196, v[180:181], s[10:11] offset:1024
	s_nop 0
	v_mul_f32_e32 v28, v28, v209
	v_mul_f32_e32 v28, v12, v28
	v_fma_f32 v28, v156, v28, v172
	v_mul_f32_e32 v29, v29, v209
	v_mul_f32_e32 v29, v13, v29
	v_fma_f32 v29, v157, v29, v173
	v_mul_f32_e32 v30, v30, v209
	v_mul_f32_e32 v30, v14, v30
	v_fma_f32 v30, v158, v30, v174
	v_mul_f32_e32 v31, v31, v209
	v_mul_f32_e32 v31, v15, v31
	v_fma_f32 v31, v159, v31, v175
	v_cvt_pk_bf16_f32 v180, v28, v29
	v_cvt_pk_bf16_f32 v181, v30, v31
	global_store_dwordx2 v196, v[180:181], s[10:11] offset:1536
	s_nop 0
	v_mul_f32_e32 v32, v32, v210
	v_mul_f32_e32 v32, v0, v32
	v_fma_f32 v32, v144, v32, v160
	v_mul_f32_e32 v33, v33, v210
	v_mul_f32_e32 v33, v1, v33
	v_fma_f32 v33, v145, v33, v161
	v_mul_f32_e32 v34, v34, v210
	v_mul_f32_e32 v34, v2, v34
	v_fma_f32 v34, v146, v34, v162
	v_mul_f32_e32 v35, v35, v210
	v_mul_f32_e32 v35, v3, v35
	v_fma_f32 v35, v147, v35, v163
	v_cvt_pk_bf16_f32 v180, v32, v33
	v_cvt_pk_bf16_f32 v181, v34, v35
	global_store_dwordx2 v196, v[180:181], s[10:11] offset:2048
	s_nop 0
	v_mul_f32_e32 v36, v36, v210
	v_mul_f32_e32 v36, v4, v36
	v_fma_f32 v36, v148, v36, v164
	v_mul_f32_e32 v37, v37, v210
	v_mul_f32_e32 v37, v5, v37
	v_fma_f32 v37, v149, v37, v165
	v_mul_f32_e32 v38, v38, v210
	v_mul_f32_e32 v38, v6, v38
	v_fma_f32 v38, v150, v38, v166
	v_mul_f32_e32 v39, v39, v210
	v_mul_f32_e32 v39, v7, v39
	v_fma_f32 v39, v151, v39, v167
	v_cvt_pk_bf16_f32 v180, v36, v37
	v_cvt_pk_bf16_f32 v181, v38, v39
	global_store_dwordx2 v196, v[180:181], s[10:11] offset:2560
	s_nop 0
	v_mul_f32_e32 v40, v40, v210
	v_mul_f32_e32 v40, v8, v40
	v_fma_f32 v40, v152, v40, v168
	v_mul_f32_e32 v41, v41, v210
	v_mul_f32_e32 v41, v9, v41
	v_fma_f32 v41, v153, v41, v169
	v_mul_f32_e32 v42, v42, v210
	v_mul_f32_e32 v42, v10, v42
	v_fma_f32 v42, v154, v42, v170
	v_mul_f32_e32 v43, v43, v210
	v_mul_f32_e32 v43, v11, v43
	v_fma_f32 v43, v155, v43, v171
	v_cvt_pk_bf16_f32 v180, v40, v41
	v_cvt_pk_bf16_f32 v181, v42, v43
	global_store_dwordx2 v196, v[180:181], s[10:11] offset:3072
	s_nop 0
	v_mul_f32_e32 v44, v44, v210
	v_mul_f32_e32 v44, v12, v44
	v_fma_f32 v44, v156, v44, v172
	v_mul_f32_e32 v45, v45, v210
	v_mul_f32_e32 v45, v13, v45
	v_fma_f32 v45, v157, v45, v173
	v_mul_f32_e32 v46, v46, v210
	v_mul_f32_e32 v46, v14, v46
	v_fma_f32 v46, v158, v46, v174
	v_mul_f32_e32 v47, v47, v210
	v_mul_f32_e32 v47, v15, v47
	v_fma_f32 v47, v159, v47, v175
	v_cvt_pk_bf16_f32 v180, v44, v45
	v_cvt_pk_bf16_f32 v181, v46, v47
	global_store_dwordx2 v196, v[180:181], s[10:11] offset:3584
	s_nop 0
	s_add_u32 s14, s14, 0x2000
	s_addc_u32 s15, s15, 0
	global_load_dwordx4 v[16:19], v194, s[14:15]
	global_load_dwordx4 v[20:23], v194, s[14:15] offset:1024
	global_load_dwordx4 v[24:27], v194, s[14:15] offset:2048
	global_load_dwordx4 v[28:31], v194, s[14:15] offset:3072
	global_load_dwordx4 v[32:35], v195, s[14:15]
	global_load_dwordx4 v[36:39], v195, s[14:15] offset:1024
	global_load_dwordx4 v[40:43], v195, s[14:15] offset:2048
	global_load_dwordx4 v[44:47], v195, s[14:15] offset:3072
	s_waitcnt vmcnt(48)
	v_pk_mul_f32 v[178:179], v[48:49], v[48:49]
	v_pk_fma_f32 v[178:179], v[50:51], v[50:51], v[178:179]
	v_pk_fma_f32 v[178:179], v[52:53], v[52:53], v[178:179]
	v_pk_fma_f32 v[178:179], v[54:55], v[54:55], v[178:179]
	v_pk_fma_f32 v[178:179], v[56:57], v[56:57], v[178:179]
	v_pk_fma_f32 v[178:179], v[58:59], v[58:59], v[178:179]
	v_pk_fma_f32 v[178:179], v[60:61], v[60:61], v[178:179]
	v_pk_fma_f32 v[178:179], v[62:63], v[62:63], v[178:179]
	v_pk_mul_f32 v[180:181], v[64:65], v[64:65]
	v_pk_fma_f32 v[180:181], v[66:67], v[66:67], v[180:181]
	v_pk_fma_f32 v[180:181], v[68:69], v[68:69], v[180:181]
	v_pk_fma_f32 v[180:181], v[70:71], v[70:71], v[180:181]
	v_pk_fma_f32 v[180:181], v[72:73], v[72:73], v[180:181]
	v_pk_fma_f32 v[180:181], v[74:75], v[74:75], v[180:181]
	v_pk_fma_f32 v[180:181], v[76:77], v[76:77], v[180:181]
	v_pk_fma_f32 v[180:181], v[78:79], v[78:79], v[180:181]
	v_add_f32_e32 v176, v178, v179
	v_add_f32_e32 v177, v180, v181
	ds_bpermute_b32 v178, v198, v176
	ds_bpermute_b32 v179, v198, v177
	s_waitcnt lgkmcnt(0)
	v_add_f32_e32 v176, v176, v178
	v_add_f32_e32 v177, v177, v179
	ds_bpermute_b32 v178, v199, v176
	ds_bpermute_b32 v179, v199, v177
	s_waitcnt lgkmcnt(0)
	v_add_f32_e32 v176, v176, v178
	v_add_f32_e32 v177, v177, v179
	ds_bpermute_b32 v178, v200, v176
	ds_bpermute_b32 v179, v200, v177
	s_waitcnt lgkmcnt(0)
	v_add_f32_e32 v176, v176, v178
	v_add_f32_e32 v177, v177, v179
	ds_bpermute_b32 v178, v201, v176
	ds_bpermute_b32 v179, v201, v177
	s_waitcnt lgkmcnt(0)
	v_add_f32_e32 v176, v176, v178
	v_add_f32_e32 v177, v177, v179
	ds_bpermute_b32 v178, v202, v176
	ds_bpermute_b32 v179, v202, v177
	s_waitcnt lgkmcnt(0)
	v_add_f32_e32 v176, v176, v178
	v_add_f32_e32 v177, v177, v179
	ds_bpermute_b32 v178, v203, v176
	ds_bpermute_b32 v179, v203, v177
	s_waitcnt lgkmcnt(0)
	v_add_f32_e32 v176, v176, v178
	v_add_f32_e32 v177, v177, v179
	v_fmamk_f32 v176, v176, 0x3a800000, v208
	v_mul_f32_e32 v178, 0x4b800000, v176
	v_cmp_gt_f32_e32 vcc, s27, v176
	s_nop 1
	v_cndmask_b32_e32 v176, v176, v178, vcc
	v_rsq_f32_e32 v209, v176
	s_nop 0
	v_mul_f32_e32 v178, 0x45800000, v209
	v_cndmask_b32_e32 v209, v209, v178, vcc
	v_fmamk_f32 v177, v177, 0x3a800000, v208
	v_mul_f32_e32 v178, 0x4b800000, v177
	v_cmp_gt_f32_e32 vcc, s27, v177
	s_nop 1
	v_cndmask_b32_e32 v177, v177, v178, vcc
	v_rsq_f32_e32 v210, v177
	s_nop 0
	v_mul_f32_e32 v178, 0x45800000, v210
	v_cndmask_b32_e32 v210, v210, v178, vcc
	s_add_u32 s10, s10, 0x1000
	s_addc_u32 s11, s11, 0
	v_mul_f32_e32 v48, v48, v209
	v_mul_f32_e32 v48, v0, v48
	v_fma_f32 v48, v144, v48, v160
	v_mul_f32_e32 v49, v49, v209
	v_mul_f32_e32 v49, v1, v49
	v_fma_f32 v49, v145, v49, v161
	v_mul_f32_e32 v50, v50, v209
	v_mul_f32_e32 v50, v2, v50
	v_fma_f32 v50, v146, v50, v162
	v_mul_f32_e32 v51, v51, v209
	v_mul_f32_e32 v51, v3, v51
	v_fma_f32 v51, v147, v51, v163
	v_cvt_pk_bf16_f32 v180, v48, v49
	v_cvt_pk_bf16_f32 v181, v50, v51
	global_store_dwordx2 v196, v[180:181], s[10:11]
	s_nop 0
	v_mul_f32_e32 v52, v52, v209
	v_mul_f32_e32 v52, v4, v52
	v_fma_f32 v52, v148, v52, v164
	v_mul_f32_e32 v53, v53, v209
	v_mul_f32_e32 v53, v5, v53
	v_fma_f32 v53, v149, v53, v165
	v_mul_f32_e32 v54, v54, v209
	v_mul_f32_e32 v54, v6, v54
	v_fma_f32 v54, v150, v54, v166
	v_mul_f32_e32 v55, v55, v209
	v_mul_f32_e32 v55, v7, v55
	v_fma_f32 v55, v151, v55, v167
	v_cvt_pk_bf16_f32 v180, v52, v53
	v_cvt_pk_bf16_f32 v181, v54, v55
	global_store_dwordx2 v196, v[180:181], s[10:11] offset:512
	s_nop 0
	v_mul_f32_e32 v56, v56, v209
	v_mul_f32_e32 v56, v8, v56
	v_fma_f32 v56, v152, v56, v168
	v_mul_f32_e32 v57, v57, v209
	v_mul_f32_e32 v57, v9, v57
	v_fma_f32 v57, v153, v57, v169
	v_mul_f32_e32 v58, v58, v209
	v_mul_f32_e32 v58, v10, v58
	v_fma_f32 v58, v154, v58, v170
	v_mul_f32_e32 v59, v59, v209
	v_mul_f32_e32 v59, v11, v59
	v_fma_f32 v59, v155, v59, v171
	v_cvt_pk_bf16_f32 v180, v56, v57
	v_cvt_pk_bf16_f32 v181, v58, v59
	global_store_dwordx2 v196, v[180:181], s[10:11] offset:1024
	s_nop 0
	v_mul_f32_e32 v60, v60, v209
	v_mul_f32_e32 v60, v12, v60
	v_fma_f32 v60, v156, v60, v172
	v_mul_f32_e32 v61, v61, v209
	v_mul_f32_e32 v61, v13, v61
	v_fma_f32 v61, v157, v61, v173
	v_mul_f32_e32 v62, v62, v209
	v_mul_f32_e32 v62, v14, v62
	v_fma_f32 v62, v158, v62, v174
	v_mul_f32_e32 v63, v63, v209
	v_mul_f32_e32 v63, v15, v63
	v_fma_f32 v63, v159, v63, v175
	v_cvt_pk_bf16_f32 v180, v60, v61
	v_cvt_pk_bf16_f32 v181, v62, v63
	global_store_dwordx2 v196, v[180:181], s[10:11] offset:1536
	s_nop 0
	v_mul_f32_e32 v64, v64, v210
	v_mul_f32_e32 v64, v0, v64
	v_fma_f32 v64, v144, v64, v160
	v_mul_f32_e32 v65, v65, v210
	v_mul_f32_e32 v65, v1, v65
	v_fma_f32 v65, v145, v65, v161
	v_mul_f32_e32 v66, v66, v210
	v_mul_f32_e32 v66, v2, v66
	v_fma_f32 v66, v146, v66, v162
	v_mul_f32_e32 v67, v67, v210
	v_mul_f32_e32 v67, v3, v67
	v_fma_f32 v67, v147, v67, v163
	v_cvt_pk_bf16_f32 v180, v64, v65
	v_cvt_pk_bf16_f32 v181, v66, v67
	global_store_dwordx2 v196, v[180:181], s[10:11] offset:2048
	s_nop 0
	v_mul_f32_e32 v68, v68, v210
	v_mul_f32_e32 v68, v4, v68
	v_fma_f32 v68, v148, v68, v164
	v_mul_f32_e32 v69, v69, v210
	v_mul_f32_e32 v69, v5, v69
	v_fma_f32 v69, v149, v69, v165
	v_mul_f32_e32 v70, v70, v210
	v_mul_f32_e32 v70, v6, v70
	v_fma_f32 v70, v150, v70, v166
	v_mul_f32_e32 v71, v71, v210
	v_mul_f32_e32 v71, v7, v71
	v_fma_f32 v71, v151, v71, v167
	v_cvt_pk_bf16_f32 v180, v68, v69
	v_cvt_pk_bf16_f32 v181, v70, v71
	global_store_dwordx2 v196, v[180:181], s[10:11] offset:2560
	s_nop 0
	v_mul_f32_e32 v72, v72, v210
	v_mul_f32_e32 v72, v8, v72
	v_fma_f32 v72, v152, v72, v168
	v_mul_f32_e32 v73, v73, v210
	v_mul_f32_e32 v73, v9, v73
	v_fma_f32 v73, v153, v73, v169
	v_mul_f32_e32 v74, v74, v210
	v_mul_f32_e32 v74, v10, v74
	v_fma_f32 v74, v154, v74, v170
	v_mul_f32_e32 v75, v75, v210
	v_mul_f32_e32 v75, v11, v75
	v_fma_f32 v75, v155, v75, v171
	v_cvt_pk_bf16_f32 v180, v72, v73
	v_cvt_pk_bf16_f32 v181, v74, v75
	global_store_dwordx2 v196, v[180:181], s[10:11] offset:3072
	s_nop 0
	v_mul_f32_e32 v76, v76, v210
	v_mul_f32_e32 v76, v12, v76
	v_fma_f32 v76, v156, v76, v172
	v_mul_f32_e32 v77, v77, v210
	v_mul_f32_e32 v77, v13, v77
	v_fma_f32 v77, v157, v77, v173
	v_mul_f32_e32 v78, v78, v210
	v_mul_f32_e32 v78, v14, v78
	v_fma_f32 v78, v158, v78, v174
	v_mul_f32_e32 v79, v79, v210
	v_mul_f32_e32 v79, v15, v79
	v_fma_f32 v79, v159, v79, v175
	v_cvt_pk_bf16_f32 v180, v76, v77
	v_cvt_pk_bf16_f32 v181, v78, v79
	global_store_dwordx2 v196, v[180:181], s[10:11] offset:3584
	s_nop 0
	s_add_u32 s14, s14, 0x2000
	s_addc_u32 s15, s15, 0
	global_load_dwordx4 v[48:51], v194, s[14:15]
	global_load_dwordx4 v[52:55], v194, s[14:15] offset:1024
	global_load_dwordx4 v[56:59], v194, s[14:15] offset:2048
	global_load_dwordx4 v[60:63], v194, s[14:15] offset:3072
	global_load_dwordx4 v[64:67], v195, s[14:15]
	global_load_dwordx4 v[68:71], v195, s[14:15] offset:1024
	global_load_dwordx4 v[72:75], v195, s[14:15] offset:2048
	global_load_dwordx4 v[76:79], v195, s[14:15] offset:3072
	s_waitcnt vmcnt(48)
	v_pk_mul_f32 v[178:179], v[80:81], v[80:81]
	v_pk_fma_f32 v[178:179], v[82:83], v[82:83], v[178:179]
	v_pk_fma_f32 v[178:179], v[84:85], v[84:85], v[178:179]
	v_pk_fma_f32 v[178:179], v[86:87], v[86:87], v[178:179]
	v_pk_fma_f32 v[178:179], v[88:89], v[88:89], v[178:179]
	v_pk_fma_f32 v[178:179], v[90:91], v[90:91], v[178:179]
	v_pk_fma_f32 v[178:179], v[92:93], v[92:93], v[178:179]
	v_pk_fma_f32 v[178:179], v[94:95], v[94:95], v[178:179]
	v_pk_mul_f32 v[180:181], v[96:97], v[96:97]
	v_pk_fma_f32 v[180:181], v[98:99], v[98:99], v[180:181]
	v_pk_fma_f32 v[180:181], v[100:101], v[100:101], v[180:181]
	v_pk_fma_f32 v[180:181], v[102:103], v[102:103], v[180:181]
	v_pk_fma_f32 v[180:181], v[104:105], v[104:105], v[180:181]
	v_pk_fma_f32 v[180:181], v[106:107], v[106:107], v[180:181]
	v_pk_fma_f32 v[180:181], v[108:109], v[108:109], v[180:181]
	v_pk_fma_f32 v[180:181], v[110:111], v[110:111], v[180:181]
	v_add_f32_e32 v176, v178, v179
	v_add_f32_e32 v177, v180, v181
	ds_bpermute_b32 v178, v198, v176
	ds_bpermute_b32 v179, v198, v177
	s_waitcnt lgkmcnt(0)
	v_add_f32_e32 v176, v176, v178
	v_add_f32_e32 v177, v177, v179
	ds_bpermute_b32 v178, v199, v176
	ds_bpermute_b32 v179, v199, v177
	s_waitcnt lgkmcnt(0)
	v_add_f32_e32 v176, v176, v178
	v_add_f32_e32 v177, v177, v179
	ds_bpermute_b32 v178, v200, v176
	ds_bpermute_b32 v179, v200, v177
	s_waitcnt lgkmcnt(0)
	v_add_f32_e32 v176, v176, v178
	v_add_f32_e32 v177, v177, v179
	ds_bpermute_b32 v178, v201, v176
	ds_bpermute_b32 v179, v201, v177
	s_waitcnt lgkmcnt(0)
	v_add_f32_e32 v176, v176, v178
	v_add_f32_e32 v177, v177, v179
	ds_bpermute_b32 v178, v202, v176
	ds_bpermute_b32 v179, v202, v177
	s_waitcnt lgkmcnt(0)
	v_add_f32_e32 v176, v176, v178
	v_add_f32_e32 v177, v177, v179
	ds_bpermute_b32 v178, v203, v176
	ds_bpermute_b32 v179, v203, v177
	s_waitcnt lgkmcnt(0)
	v_add_f32_e32 v176, v176, v178
	v_add_f32_e32 v177, v177, v179
	v_fmamk_f32 v176, v176, 0x3a800000, v208
	v_mul_f32_e32 v178, 0x4b800000, v176
	v_cmp_gt_f32_e32 vcc, s27, v176
	s_nop 1
	v_cndmask_b32_e32 v176, v176, v178, vcc
	v_rsq_f32_e32 v209, v176
	s_nop 0
	v_mul_f32_e32 v178, 0x45800000, v209
	v_cndmask_b32_e32 v209, v209, v178, vcc
	v_fmamk_f32 v177, v177, 0x3a800000, v208
	v_mul_f32_e32 v178, 0x4b800000, v177
	v_cmp_gt_f32_e32 vcc, s27, v177
	s_nop 1
	v_cndmask_b32_e32 v177, v177, v178, vcc
	v_rsq_f32_e32 v210, v177
	s_nop 0
	v_mul_f32_e32 v178, 0x45800000, v210
	v_cndmask_b32_e32 v210, v210, v178, vcc
	s_add_u32 s10, s10, 0x1000
	s_addc_u32 s11, s11, 0
	v_mul_f32_e32 v80, v80, v209
	v_mul_f32_e32 v80, v0, v80
	v_fma_f32 v80, v144, v80, v160
	v_mul_f32_e32 v81, v81, v209
	v_mul_f32_e32 v81, v1, v81
	v_fma_f32 v81, v145, v81, v161
	v_mul_f32_e32 v82, v82, v209
	v_mul_f32_e32 v82, v2, v82
	v_fma_f32 v82, v146, v82, v162
	v_mul_f32_e32 v83, v83, v209
	v_mul_f32_e32 v83, v3, v83
	v_fma_f32 v83, v147, v83, v163
	v_cvt_pk_bf16_f32 v180, v80, v81
	v_cvt_pk_bf16_f32 v181, v82, v83
	global_store_dwordx2 v196, v[180:181], s[10:11]
	s_nop 0
	v_mul_f32_e32 v84, v84, v209
	v_mul_f32_e32 v84, v4, v84
	v_fma_f32 v84, v148, v84, v164
	v_mul_f32_e32 v85, v85, v209
	v_mul_f32_e32 v85, v5, v85
	v_fma_f32 v85, v149, v85, v165
	v_mul_f32_e32 v86, v86, v209
	v_mul_f32_e32 v86, v6, v86
	v_fma_f32 v86, v150, v86, v166
	v_mul_f32_e32 v87, v87, v209
	v_mul_f32_e32 v87, v7, v87
	v_fma_f32 v87, v151, v87, v167
	v_cvt_pk_bf16_f32 v180, v84, v85
	v_cvt_pk_bf16_f32 v181, v86, v87
	global_store_dwordx2 v196, v[180:181], s[10:11] offset:512
	s_nop 0
	v_mul_f32_e32 v88, v88, v209
	v_mul_f32_e32 v88, v8, v88
	v_fma_f32 v88, v152, v88, v168
	v_mul_f32_e32 v89, v89, v209
	v_mul_f32_e32 v89, v9, v89
	v_fma_f32 v89, v153, v89, v169
	v_mul_f32_e32 v90, v90, v209
	v_mul_f32_e32 v90, v10, v90
	v_fma_f32 v90, v154, v90, v170
	v_mul_f32_e32 v91, v91, v209
	v_mul_f32_e32 v91, v11, v91
	v_fma_f32 v91, v155, v91, v171
	v_cvt_pk_bf16_f32 v180, v88, v89
	v_cvt_pk_bf16_f32 v181, v90, v91
	global_store_dwordx2 v196, v[180:181], s[10:11] offset:1024
	s_nop 0
	v_mul_f32_e32 v92, v92, v209
	v_mul_f32_e32 v92, v12, v92
	v_fma_f32 v92, v156, v92, v172
	v_mul_f32_e32 v93, v93, v209
	v_mul_f32_e32 v93, v13, v93
	v_fma_f32 v93, v157, v93, v173
	v_mul_f32_e32 v94, v94, v209
	v_mul_f32_e32 v94, v14, v94
	v_fma_f32 v94, v158, v94, v174
	v_mul_f32_e32 v95, v95, v209
	v_mul_f32_e32 v95, v15, v95
	v_fma_f32 v95, v159, v95, v175
	v_cvt_pk_bf16_f32 v180, v92, v93
	v_cvt_pk_bf16_f32 v181, v94, v95
	global_store_dwordx2 v196, v[180:181], s[10:11] offset:1536
	s_nop 0
	v_mul_f32_e32 v96, v96, v210
	v_mul_f32_e32 v96, v0, v96
	v_fma_f32 v96, v144, v96, v160
	v_mul_f32_e32 v97, v97, v210
	v_mul_f32_e32 v97, v1, v97
	v_fma_f32 v97, v145, v97, v161
	v_mul_f32_e32 v98, v98, v210
	v_mul_f32_e32 v98, v2, v98
	v_fma_f32 v98, v146, v98, v162
	v_mul_f32_e32 v99, v99, v210
	v_mul_f32_e32 v99, v3, v99
	v_fma_f32 v99, v147, v99, v163
	v_cvt_pk_bf16_f32 v180, v96, v97
	v_cvt_pk_bf16_f32 v181, v98, v99
	global_store_dwordx2 v196, v[180:181], s[10:11] offset:2048
	s_nop 0
	v_mul_f32_e32 v100, v100, v210
	v_mul_f32_e32 v100, v4, v100
	v_fma_f32 v100, v148, v100, v164
	v_mul_f32_e32 v101, v101, v210
	v_mul_f32_e32 v101, v5, v101
	v_fma_f32 v101, v149, v101, v165
	v_mul_f32_e32 v102, v102, v210
	v_mul_f32_e32 v102, v6, v102
	v_fma_f32 v102, v150, v102, v166
	v_mul_f32_e32 v103, v103, v210
	v_mul_f32_e32 v103, v7, v103
	v_fma_f32 v103, v151, v103, v167
	v_cvt_pk_bf16_f32 v180, v100, v101
	v_cvt_pk_bf16_f32 v181, v102, v103
	global_store_dwordx2 v196, v[180:181], s[10:11] offset:2560
	s_nop 0
	v_mul_f32_e32 v104, v104, v210
	v_mul_f32_e32 v104, v8, v104
	v_fma_f32 v104, v152, v104, v168
	v_mul_f32_e32 v105, v105, v210
	v_mul_f32_e32 v105, v9, v105
	v_fma_f32 v105, v153, v105, v169
	v_mul_f32_e32 v106, v106, v210
	v_mul_f32_e32 v106, v10, v106
	v_fma_f32 v106, v154, v106, v170
	v_mul_f32_e32 v107, v107, v210
	v_mul_f32_e32 v107, v11, v107
	v_fma_f32 v107, v155, v107, v171
	v_cvt_pk_bf16_f32 v180, v104, v105
	v_cvt_pk_bf16_f32 v181, v106, v107
	global_store_dwordx2 v196, v[180:181], s[10:11] offset:3072
	s_nop 0
	v_mul_f32_e32 v108, v108, v210
	v_mul_f32_e32 v108, v12, v108
	v_fma_f32 v108, v156, v108, v172
	v_mul_f32_e32 v109, v109, v210
	v_mul_f32_e32 v109, v13, v109
	v_fma_f32 v109, v157, v109, v173
	v_mul_f32_e32 v110, v110, v210
	v_mul_f32_e32 v110, v14, v110
	v_fma_f32 v110, v158, v110, v174
	v_mul_f32_e32 v111, v111, v210
	v_mul_f32_e32 v111, v15, v111
	v_fma_f32 v111, v159, v111, v175
	v_cvt_pk_bf16_f32 v180, v108, v109
	v_cvt_pk_bf16_f32 v181, v110, v111
	global_store_dwordx2 v196, v[180:181], s[10:11] offset:3584
	s_nop 0
	s_add_u32 s14, s14, 0x2000
	s_addc_u32 s15, s15, 0
	global_load_dwordx4 v[80:83], v194, s[14:15]
	global_load_dwordx4 v[84:87], v194, s[14:15] offset:1024
	global_load_dwordx4 v[88:91], v194, s[14:15] offset:2048
	global_load_dwordx4 v[92:95], v194, s[14:15] offset:3072
	global_load_dwordx4 v[96:99], v195, s[14:15]
	global_load_dwordx4 v[100:103], v195, s[14:15] offset:1024
	global_load_dwordx4 v[104:107], v195, s[14:15] offset:2048
	global_load_dwordx4 v[108:111], v195, s[14:15] offset:3072
	s_waitcnt vmcnt(48)
	v_pk_mul_f32 v[178:179], v[112:113], v[112:113]
	v_pk_fma_f32 v[178:179], v[114:115], v[114:115], v[178:179]
	v_pk_fma_f32 v[178:179], v[116:117], v[116:117], v[178:179]
	v_pk_fma_f32 v[178:179], v[118:119], v[118:119], v[178:179]
	v_pk_fma_f32 v[178:179], v[120:121], v[120:121], v[178:179]
	v_pk_fma_f32 v[178:179], v[122:123], v[122:123], v[178:179]
	v_pk_fma_f32 v[178:179], v[124:125], v[124:125], v[178:179]
	v_pk_fma_f32 v[178:179], v[126:127], v[126:127], v[178:179]
	v_pk_mul_f32 v[180:181], v[128:129], v[128:129]
	v_pk_fma_f32 v[180:181], v[130:131], v[130:131], v[180:181]
	v_pk_fma_f32 v[180:181], v[132:133], v[132:133], v[180:181]
	v_pk_fma_f32 v[180:181], v[134:135], v[134:135], v[180:181]
	v_pk_fma_f32 v[180:181], v[136:137], v[136:137], v[180:181]
	v_pk_fma_f32 v[180:181], v[138:139], v[138:139], v[180:181]
	v_pk_fma_f32 v[180:181], v[140:141], v[140:141], v[180:181]
	v_pk_fma_f32 v[180:181], v[142:143], v[142:143], v[180:181]
	v_add_f32_e32 v176, v178, v179
	v_add_f32_e32 v177, v180, v181
	ds_bpermute_b32 v178, v198, v176
	ds_bpermute_b32 v179, v198, v177
	s_waitcnt lgkmcnt(0)
	v_add_f32_e32 v176, v176, v178
	v_add_f32_e32 v177, v177, v179
	ds_bpermute_b32 v178, v199, v176
	ds_bpermute_b32 v179, v199, v177
	s_waitcnt lgkmcnt(0)
	v_add_f32_e32 v176, v176, v178
	v_add_f32_e32 v177, v177, v179
	ds_bpermute_b32 v178, v200, v176
	ds_bpermute_b32 v179, v200, v177
	s_waitcnt lgkmcnt(0)
	v_add_f32_e32 v176, v176, v178
	v_add_f32_e32 v177, v177, v179
	ds_bpermute_b32 v178, v201, v176
	ds_bpermute_b32 v179, v201, v177
	s_waitcnt lgkmcnt(0)
	v_add_f32_e32 v176, v176, v178
	v_add_f32_e32 v177, v177, v179
	ds_bpermute_b32 v178, v202, v176
	ds_bpermute_b32 v179, v202, v177
	s_waitcnt lgkmcnt(0)
	v_add_f32_e32 v176, v176, v178
	v_add_f32_e32 v177, v177, v179
	ds_bpermute_b32 v178, v203, v176
	ds_bpermute_b32 v179, v203, v177
	s_waitcnt lgkmcnt(0)
	v_add_f32_e32 v176, v176, v178
	v_add_f32_e32 v177, v177, v179
	v_fmamk_f32 v176, v176, 0x3a800000, v208
	v_mul_f32_e32 v178, 0x4b800000, v176
	v_cmp_gt_f32_e32 vcc, s27, v176
	s_nop 1
	v_cndmask_b32_e32 v176, v176, v178, vcc
	v_rsq_f32_e32 v209, v176
	s_nop 0
	v_mul_f32_e32 v178, 0x45800000, v209
	v_cndmask_b32_e32 v209, v209, v178, vcc
	v_fmamk_f32 v177, v177, 0x3a800000, v208
	v_mul_f32_e32 v178, 0x4b800000, v177
	v_cmp_gt_f32_e32 vcc, s27, v177
	s_nop 1
	v_cndmask_b32_e32 v177, v177, v178, vcc
	v_rsq_f32_e32 v210, v177
	s_nop 0
	v_mul_f32_e32 v178, 0x45800000, v210
	v_cndmask_b32_e32 v210, v210, v178, vcc
	s_add_u32 s10, s10, 0x1000
	s_addc_u32 s11, s11, 0
	v_mul_f32_e32 v112, v112, v209
	v_mul_f32_e32 v112, v0, v112
	v_fma_f32 v112, v144, v112, v160
	v_mul_f32_e32 v113, v113, v209
	v_mul_f32_e32 v113, v1, v113
	v_fma_f32 v113, v145, v113, v161
	v_mul_f32_e32 v114, v114, v209
	v_mul_f32_e32 v114, v2, v114
	v_fma_f32 v114, v146, v114, v162
	v_mul_f32_e32 v115, v115, v209
	v_mul_f32_e32 v115, v3, v115
	v_fma_f32 v115, v147, v115, v163
	v_cvt_pk_bf16_f32 v180, v112, v113
	v_cvt_pk_bf16_f32 v181, v114, v115
	global_store_dwordx2 v196, v[180:181], s[10:11]
	s_nop 0
	v_mul_f32_e32 v116, v116, v209
	v_mul_f32_e32 v116, v4, v116
	v_fma_f32 v116, v148, v116, v164
	v_mul_f32_e32 v117, v117, v209
	v_mul_f32_e32 v117, v5, v117
	v_fma_f32 v117, v149, v117, v165
	v_mul_f32_e32 v118, v118, v209
	v_mul_f32_e32 v118, v6, v118
	v_fma_f32 v118, v150, v118, v166
	v_mul_f32_e32 v119, v119, v209
	v_mul_f32_e32 v119, v7, v119
	v_fma_f32 v119, v151, v119, v167
	v_cvt_pk_bf16_f32 v180, v116, v117
	v_cvt_pk_bf16_f32 v181, v118, v119
	global_store_dwordx2 v196, v[180:181], s[10:11] offset:512
	s_nop 0
	v_mul_f32_e32 v120, v120, v209
	v_mul_f32_e32 v120, v8, v120
	v_fma_f32 v120, v152, v120, v168
	v_mul_f32_e32 v121, v121, v209
	v_mul_f32_e32 v121, v9, v121
	v_fma_f32 v121, v153, v121, v169
	v_mul_f32_e32 v122, v122, v209
	v_mul_f32_e32 v122, v10, v122
	v_fma_f32 v122, v154, v122, v170
	v_mul_f32_e32 v123, v123, v209
	v_mul_f32_e32 v123, v11, v123
	v_fma_f32 v123, v155, v123, v171
	v_cvt_pk_bf16_f32 v180, v120, v121
	v_cvt_pk_bf16_f32 v181, v122, v123
	global_store_dwordx2 v196, v[180:181], s[10:11] offset:1024
	s_nop 0
	v_mul_f32_e32 v124, v124, v209
	v_mul_f32_e32 v124, v12, v124
	v_fma_f32 v124, v156, v124, v172
	v_mul_f32_e32 v125, v125, v209
	v_mul_f32_e32 v125, v13, v125
	v_fma_f32 v125, v157, v125, v173
	v_mul_f32_e32 v126, v126, v209
	v_mul_f32_e32 v126, v14, v126
	v_fma_f32 v126, v158, v126, v174
	v_mul_f32_e32 v127, v127, v209
	v_mul_f32_e32 v127, v15, v127
	v_fma_f32 v127, v159, v127, v175
	v_cvt_pk_bf16_f32 v180, v124, v125
	v_cvt_pk_bf16_f32 v181, v126, v127
	global_store_dwordx2 v196, v[180:181], s[10:11] offset:1536
	s_nop 0
	v_mul_f32_e32 v128, v128, v210
	v_mul_f32_e32 v128, v0, v128
	v_fma_f32 v128, v144, v128, v160
	v_mul_f32_e32 v129, v129, v210
	v_mul_f32_e32 v129, v1, v129
	v_fma_f32 v129, v145, v129, v161
	v_mul_f32_e32 v130, v130, v210
	v_mul_f32_e32 v130, v2, v130
	v_fma_f32 v130, v146, v130, v162
	v_mul_f32_e32 v131, v131, v210
	v_mul_f32_e32 v131, v3, v131
	v_fma_f32 v131, v147, v131, v163
	v_cvt_pk_bf16_f32 v180, v128, v129
	v_cvt_pk_bf16_f32 v181, v130, v131
	global_store_dwordx2 v196, v[180:181], s[10:11] offset:2048
	s_nop 0
	v_mul_f32_e32 v132, v132, v210
	v_mul_f32_e32 v132, v4, v132
	v_fma_f32 v132, v148, v132, v164
	v_mul_f32_e32 v133, v133, v210
	v_mul_f32_e32 v133, v5, v133
	v_fma_f32 v133, v149, v133, v165
	v_mul_f32_e32 v134, v134, v210
	v_mul_f32_e32 v134, v6, v134
	v_fma_f32 v134, v150, v134, v166
	v_mul_f32_e32 v135, v135, v210
	v_mul_f32_e32 v135, v7, v135
	v_fma_f32 v135, v151, v135, v167
	v_cvt_pk_bf16_f32 v180, v132, v133
	v_cvt_pk_bf16_f32 v181, v134, v135
	global_store_dwordx2 v196, v[180:181], s[10:11] offset:2560
	s_nop 0
	v_mul_f32_e32 v136, v136, v210
	v_mul_f32_e32 v136, v8, v136
	v_fma_f32 v136, v152, v136, v168
	v_mul_f32_e32 v137, v137, v210
	v_mul_f32_e32 v137, v9, v137
	v_fma_f32 v137, v153, v137, v169
	v_mul_f32_e32 v138, v138, v210
	v_mul_f32_e32 v138, v10, v138
	v_fma_f32 v138, v154, v138, v170
	v_mul_f32_e32 v139, v139, v210
	v_mul_f32_e32 v139, v11, v139
	v_fma_f32 v139, v155, v139, v171
	v_cvt_pk_bf16_f32 v180, v136, v137
	v_cvt_pk_bf16_f32 v181, v138, v139
	global_store_dwordx2 v196, v[180:181], s[10:11] offset:3072
	s_nop 0
	v_mul_f32_e32 v140, v140, v210
	v_mul_f32_e32 v140, v12, v140
	v_fma_f32 v140, v156, v140, v172
	v_mul_f32_e32 v141, v141, v210
	v_mul_f32_e32 v141, v13, v141
	v_fma_f32 v141, v157, v141, v173
	v_mul_f32_e32 v142, v142, v210
	v_mul_f32_e32 v142, v14, v142
	v_fma_f32 v142, v158, v142, v174
	v_mul_f32_e32 v143, v143, v210
	v_mul_f32_e32 v143, v15, v143
	v_fma_f32 v143, v159, v143, v175
	v_cvt_pk_bf16_f32 v180, v140, v141
	v_cvt_pk_bf16_f32 v181, v142, v143
	global_store_dwordx2 v196, v[180:181], s[10:11] offset:3584
	s_nop 0
	s_add_u32 s14, s14, 0x2000
	s_addc_u32 s15, s15, 0
	global_load_dwordx4 v[112:115], v194, s[14:15]
	global_load_dwordx4 v[116:119], v194, s[14:15] offset:1024
	global_load_dwordx4 v[120:123], v194, s[14:15] offset:2048
	global_load_dwordx4 v[124:127], v194, s[14:15] offset:3072
	global_load_dwordx4 v[128:131], v195, s[14:15]
	global_load_dwordx4 v[132:135], v195, s[14:15] offset:1024
	global_load_dwordx4 v[136:139], v195, s[14:15] offset:2048
	global_load_dwordx4 v[140:143], v195, s[14:15] offset:3072
	s_waitcnt vmcnt(48)
	v_pk_mul_f32 v[178:179], v[16:17], v[16:17]
	v_pk_fma_f32 v[178:179], v[18:19], v[18:19], v[178:179]
	v_pk_fma_f32 v[178:179], v[20:21], v[20:21], v[178:179]
	v_pk_fma_f32 v[178:179], v[22:23], v[22:23], v[178:179]
	v_pk_fma_f32 v[178:179], v[24:25], v[24:25], v[178:179]
	v_pk_fma_f32 v[178:179], v[26:27], v[26:27], v[178:179]
	v_pk_fma_f32 v[178:179], v[28:29], v[28:29], v[178:179]
	v_pk_fma_f32 v[178:179], v[30:31], v[30:31], v[178:179]
	v_pk_mul_f32 v[180:181], v[32:33], v[32:33]
	v_pk_fma_f32 v[180:181], v[34:35], v[34:35], v[180:181]
	v_pk_fma_f32 v[180:181], v[36:37], v[36:37], v[180:181]
	v_pk_fma_f32 v[180:181], v[38:39], v[38:39], v[180:181]
	v_pk_fma_f32 v[180:181], v[40:41], v[40:41], v[180:181]
	v_pk_fma_f32 v[180:181], v[42:43], v[42:43], v[180:181]
	v_pk_fma_f32 v[180:181], v[44:45], v[44:45], v[180:181]
	v_pk_fma_f32 v[180:181], v[46:47], v[46:47], v[180:181]
	v_add_f32_e32 v176, v178, v179
	v_add_f32_e32 v177, v180, v181
	ds_bpermute_b32 v178, v198, v176
	ds_bpermute_b32 v179, v198, v177
	s_waitcnt lgkmcnt(0)
	v_add_f32_e32 v176, v176, v178
	v_add_f32_e32 v177, v177, v179
	ds_bpermute_b32 v178, v199, v176
	ds_bpermute_b32 v179, v199, v177
	s_waitcnt lgkmcnt(0)
	v_add_f32_e32 v176, v176, v178
	v_add_f32_e32 v177, v177, v179
	ds_bpermute_b32 v178, v200, v176
	ds_bpermute_b32 v179, v200, v177
	s_waitcnt lgkmcnt(0)
	v_add_f32_e32 v176, v176, v178
	v_add_f32_e32 v177, v177, v179
	ds_bpermute_b32 v178, v201, v176
	ds_bpermute_b32 v179, v201, v177
	s_waitcnt lgkmcnt(0)
	v_add_f32_e32 v176, v176, v178
	v_add_f32_e32 v177, v177, v179
	ds_bpermute_b32 v178, v202, v176
	ds_bpermute_b32 v179, v202, v177
	s_waitcnt lgkmcnt(0)
	v_add_f32_e32 v176, v176, v178
	v_add_f32_e32 v177, v177, v179
	ds_bpermute_b32 v178, v203, v176
	ds_bpermute_b32 v179, v203, v177
	s_waitcnt lgkmcnt(0)
	v_add_f32_e32 v176, v176, v178
	v_add_f32_e32 v177, v177, v179
	v_fmamk_f32 v176, v176, 0x3a800000, v208
	v_mul_f32_e32 v178, 0x4b800000, v176
	v_cmp_gt_f32_e32 vcc, s27, v176
	s_nop 1
	v_cndmask_b32_e32 v176, v176, v178, vcc
	v_rsq_f32_e32 v209, v176
	s_nop 0
	v_mul_f32_e32 v178, 0x45800000, v209
	v_cndmask_b32_e32 v209, v209, v178, vcc
	v_fmamk_f32 v177, v177, 0x3a800000, v208
	v_mul_f32_e32 v178, 0x4b800000, v177
	v_cmp_gt_f32_e32 vcc, s27, v177
	s_nop 1
	v_cndmask_b32_e32 v177, v177, v178, vcc
	v_rsq_f32_e32 v210, v177
	s_nop 0
	v_mul_f32_e32 v178, 0x45800000, v210
	v_cndmask_b32_e32 v210, v210, v178, vcc
	s_add_u32 s10, s10, 0x1000
	s_addc_u32 s11, s11, 0
	v_mul_f32_e32 v16, v16, v209
	v_mul_f32_e32 v16, v0, v16
	v_fma_f32 v16, v144, v16, v160
	v_mul_f32_e32 v17, v17, v209
	v_mul_f32_e32 v17, v1, v17
	v_fma_f32 v17, v145, v17, v161
	v_mul_f32_e32 v18, v18, v209
	v_mul_f32_e32 v18, v2, v18
	v_fma_f32 v18, v146, v18, v162
	v_mul_f32_e32 v19, v19, v209
	v_mul_f32_e32 v19, v3, v19
	v_fma_f32 v19, v147, v19, v163
	v_cvt_pk_bf16_f32 v180, v16, v17
	v_cvt_pk_bf16_f32 v181, v18, v19
	global_store_dwordx2 v196, v[180:181], s[10:11]
	s_nop 0
	v_mul_f32_e32 v20, v20, v209
	v_mul_f32_e32 v20, v4, v20
	v_fma_f32 v20, v148, v20, v164
	v_mul_f32_e32 v21, v21, v209
	v_mul_f32_e32 v21, v5, v21
	v_fma_f32 v21, v149, v21, v165
	v_mul_f32_e32 v22, v22, v209
	v_mul_f32_e32 v22, v6, v22
	v_fma_f32 v22, v150, v22, v166
	v_mul_f32_e32 v23, v23, v209
	v_mul_f32_e32 v23, v7, v23
	v_fma_f32 v23, v151, v23, v167
	v_cvt_pk_bf16_f32 v180, v20, v21
	v_cvt_pk_bf16_f32 v181, v22, v23
	global_store_dwordx2 v196, v[180:181], s[10:11] offset:512
	s_nop 0
	v_mul_f32_e32 v24, v24, v209
	v_mul_f32_e32 v24, v8, v24
	v_fma_f32 v24, v152, v24, v168
	v_mul_f32_e32 v25, v25, v209
	v_mul_f32_e32 v25, v9, v25
	v_fma_f32 v25, v153, v25, v169
	v_mul_f32_e32 v26, v26, v209
	v_mul_f32_e32 v26, v10, v26
	v_fma_f32 v26, v154, v26, v170
	v_mul_f32_e32 v27, v27, v209
	v_mul_f32_e32 v27, v11, v27
	v_fma_f32 v27, v155, v27, v171
	v_cvt_pk_bf16_f32 v180, v24, v25
	v_cvt_pk_bf16_f32 v181, v26, v27
	global_store_dwordx2 v196, v[180:181], s[10:11] offset:1024
	s_nop 0
	v_mul_f32_e32 v28, v28, v209
	v_mul_f32_e32 v28, v12, v28
	v_fma_f32 v28, v156, v28, v172
	v_mul_f32_e32 v29, v29, v209
	v_mul_f32_e32 v29, v13, v29
	v_fma_f32 v29, v157, v29, v173
	v_mul_f32_e32 v30, v30, v209
	v_mul_f32_e32 v30, v14, v30
	v_fma_f32 v30, v158, v30, v174
	v_mul_f32_e32 v31, v31, v209
	v_mul_f32_e32 v31, v15, v31
	v_fma_f32 v31, v159, v31, v175
	v_cvt_pk_bf16_f32 v180, v28, v29
	v_cvt_pk_bf16_f32 v181, v30, v31
	global_store_dwordx2 v196, v[180:181], s[10:11] offset:1536
	s_nop 0
	v_mul_f32_e32 v32, v32, v210
	v_mul_f32_e32 v32, v0, v32
	v_fma_f32 v32, v144, v32, v160
	v_mul_f32_e32 v33, v33, v210
	v_mul_f32_e32 v33, v1, v33
	v_fma_f32 v33, v145, v33, v161
	v_mul_f32_e32 v34, v34, v210
	v_mul_f32_e32 v34, v2, v34
	v_fma_f32 v34, v146, v34, v162
	v_mul_f32_e32 v35, v35, v210
	v_mul_f32_e32 v35, v3, v35
	v_fma_f32 v35, v147, v35, v163
	v_cvt_pk_bf16_f32 v180, v32, v33
	v_cvt_pk_bf16_f32 v181, v34, v35
	global_store_dwordx2 v196, v[180:181], s[10:11] offset:2048
	s_nop 0
	v_mul_f32_e32 v36, v36, v210
	v_mul_f32_e32 v36, v4, v36
	v_fma_f32 v36, v148, v36, v164
	v_mul_f32_e32 v37, v37, v210
	v_mul_f32_e32 v37, v5, v37
	v_fma_f32 v37, v149, v37, v165
	v_mul_f32_e32 v38, v38, v210
	v_mul_f32_e32 v38, v6, v38
	v_fma_f32 v38, v150, v38, v166
	v_mul_f32_e32 v39, v39, v210
	v_mul_f32_e32 v39, v7, v39
	v_fma_f32 v39, v151, v39, v167
	v_cvt_pk_bf16_f32 v180, v36, v37
	v_cvt_pk_bf16_f32 v181, v38, v39
	global_store_dwordx2 v196, v[180:181], s[10:11] offset:2560
	s_nop 0
	v_mul_f32_e32 v40, v40, v210
	v_mul_f32_e32 v40, v8, v40
	v_fma_f32 v40, v152, v40, v168
	v_mul_f32_e32 v41, v41, v210
	v_mul_f32_e32 v41, v9, v41
	v_fma_f32 v41, v153, v41, v169
	v_mul_f32_e32 v42, v42, v210
	v_mul_f32_e32 v42, v10, v42
	v_fma_f32 v42, v154, v42, v170
	v_mul_f32_e32 v43, v43, v210
	v_mul_f32_e32 v43, v11, v43
	v_fma_f32 v43, v155, v43, v171
	v_cvt_pk_bf16_f32 v180, v40, v41
	v_cvt_pk_bf16_f32 v181, v42, v43
	global_store_dwordx2 v196, v[180:181], s[10:11] offset:3072
	s_nop 0
	v_mul_f32_e32 v44, v44, v210
	v_mul_f32_e32 v44, v12, v44
	v_fma_f32 v44, v156, v44, v172
	v_mul_f32_e32 v45, v45, v210
	v_mul_f32_e32 v45, v13, v45
	v_fma_f32 v45, v157, v45, v173
	v_mul_f32_e32 v46, v46, v210
	v_mul_f32_e32 v46, v14, v46
	v_fma_f32 v46, v158, v46, v174
	v_mul_f32_e32 v47, v47, v210
	v_mul_f32_e32 v47, v15, v47
	v_fma_f32 v47, v159, v47, v175
	v_cvt_pk_bf16_f32 v180, v44, v45
	v_cvt_pk_bf16_f32 v181, v46, v47
	global_store_dwordx2 v196, v[180:181], s[10:11] offset:3584
	s_nop 0
	s_add_u32 s14, s14, 0x2000
	s_addc_u32 s15, s15, 0
	global_load_dwordx4 v[16:19], v194, s[14:15]
	global_load_dwordx4 v[20:23], v194, s[14:15] offset:1024
	global_load_dwordx4 v[24:27], v194, s[14:15] offset:2048
	global_load_dwordx4 v[28:31], v194, s[14:15] offset:3072
	global_load_dwordx4 v[32:35], v195, s[14:15]
	global_load_dwordx4 v[36:39], v195, s[14:15] offset:1024
	global_load_dwordx4 v[40:43], v195, s[14:15] offset:2048
	global_load_dwordx4 v[44:47], v195, s[14:15] offset:3072
	s_waitcnt vmcnt(48)
	v_pk_mul_f32 v[178:179], v[48:49], v[48:49]
	v_pk_fma_f32 v[178:179], v[50:51], v[50:51], v[178:179]
	v_pk_fma_f32 v[178:179], v[52:53], v[52:53], v[178:179]
	v_pk_fma_f32 v[178:179], v[54:55], v[54:55], v[178:179]
	v_pk_fma_f32 v[178:179], v[56:57], v[56:57], v[178:179]
	v_pk_fma_f32 v[178:179], v[58:59], v[58:59], v[178:179]
	v_pk_fma_f32 v[178:179], v[60:61], v[60:61], v[178:179]
	v_pk_fma_f32 v[178:179], v[62:63], v[62:63], v[178:179]
	v_pk_mul_f32 v[180:181], v[64:65], v[64:65]
	v_pk_fma_f32 v[180:181], v[66:67], v[66:67], v[180:181]
	v_pk_fma_f32 v[180:181], v[68:69], v[68:69], v[180:181]
	v_pk_fma_f32 v[180:181], v[70:71], v[70:71], v[180:181]
	v_pk_fma_f32 v[180:181], v[72:73], v[72:73], v[180:181]
	v_pk_fma_f32 v[180:181], v[74:75], v[74:75], v[180:181]
	v_pk_fma_f32 v[180:181], v[76:77], v[76:77], v[180:181]
	v_pk_fma_f32 v[180:181], v[78:79], v[78:79], v[180:181]
	v_add_f32_e32 v176, v178, v179
	v_add_f32_e32 v177, v180, v181
	ds_bpermute_b32 v178, v198, v176
	ds_bpermute_b32 v179, v198, v177
	s_waitcnt lgkmcnt(0)
	v_add_f32_e32 v176, v176, v178
	v_add_f32_e32 v177, v177, v179
	ds_bpermute_b32 v178, v199, v176
	ds_bpermute_b32 v179, v199, v177
	s_waitcnt lgkmcnt(0)
	v_add_f32_e32 v176, v176, v178
	v_add_f32_e32 v177, v177, v179
	ds_bpermute_b32 v178, v200, v176
	ds_bpermute_b32 v179, v200, v177
	s_waitcnt lgkmcnt(0)
	v_add_f32_e32 v176, v176, v178
	v_add_f32_e32 v177, v177, v179
	ds_bpermute_b32 v178, v201, v176
	ds_bpermute_b32 v179, v201, v177
	s_waitcnt lgkmcnt(0)
	v_add_f32_e32 v176, v176, v178
	v_add_f32_e32 v177, v177, v179
	ds_bpermute_b32 v178, v202, v176
	ds_bpermute_b32 v179, v202, v177
	s_waitcnt lgkmcnt(0)
	v_add_f32_e32 v176, v176, v178
	v_add_f32_e32 v177, v177, v179
	ds_bpermute_b32 v178, v203, v176
	ds_bpermute_b32 v179, v203, v177
	s_waitcnt lgkmcnt(0)
	v_add_f32_e32 v176, v176, v178
	v_add_f32_e32 v177, v177, v179
	v_fmamk_f32 v176, v176, 0x3a800000, v208
	v_mul_f32_e32 v178, 0x4b800000, v176
	v_cmp_gt_f32_e32 vcc, s27, v176
	s_nop 1
	v_cndmask_b32_e32 v176, v176, v178, vcc
	v_rsq_f32_e32 v209, v176
	s_nop 0
	v_mul_f32_e32 v178, 0x45800000, v209
	v_cndmask_b32_e32 v209, v209, v178, vcc
	v_fmamk_f32 v177, v177, 0x3a800000, v208
	v_mul_f32_e32 v178, 0x4b800000, v177
	v_cmp_gt_f32_e32 vcc, s27, v177
	s_nop 1
	v_cndmask_b32_e32 v177, v177, v178, vcc
	v_rsq_f32_e32 v210, v177
	s_nop 0
	v_mul_f32_e32 v178, 0x45800000, v210
	v_cndmask_b32_e32 v210, v210, v178, vcc
	s_add_u32 s10, s10, 0x1000
	s_addc_u32 s11, s11, 0
	v_mul_f32_e32 v48, v48, v209
	v_mul_f32_e32 v48, v0, v48
	v_fma_f32 v48, v144, v48, v160
	v_mul_f32_e32 v49, v49, v209
	v_mul_f32_e32 v49, v1, v49
	v_fma_f32 v49, v145, v49, v161
	v_mul_f32_e32 v50, v50, v209
	v_mul_f32_e32 v50, v2, v50
	v_fma_f32 v50, v146, v50, v162
	v_mul_f32_e32 v51, v51, v209
	v_mul_f32_e32 v51, v3, v51
	v_fma_f32 v51, v147, v51, v163
	v_cvt_pk_bf16_f32 v180, v48, v49
	v_cvt_pk_bf16_f32 v181, v50, v51
	global_store_dwordx2 v196, v[180:181], s[10:11]
	s_nop 0
	v_mul_f32_e32 v52, v52, v209
	v_mul_f32_e32 v52, v4, v52
	v_fma_f32 v52, v148, v52, v164
	v_mul_f32_e32 v53, v53, v209
	v_mul_f32_e32 v53, v5, v53
	v_fma_f32 v53, v149, v53, v165
	v_mul_f32_e32 v54, v54, v209
	v_mul_f32_e32 v54, v6, v54
	v_fma_f32 v54, v150, v54, v166
	v_mul_f32_e32 v55, v55, v209
	v_mul_f32_e32 v55, v7, v55
	v_fma_f32 v55, v151, v55, v167
	v_cvt_pk_bf16_f32 v180, v52, v53
	v_cvt_pk_bf16_f32 v181, v54, v55
	global_store_dwordx2 v196, v[180:181], s[10:11] offset:512
	s_nop 0
	v_mul_f32_e32 v56, v56, v209
	v_mul_f32_e32 v56, v8, v56
	v_fma_f32 v56, v152, v56, v168
	v_mul_f32_e32 v57, v57, v209
	v_mul_f32_e32 v57, v9, v57
	v_fma_f32 v57, v153, v57, v169
	v_mul_f32_e32 v58, v58, v209
	v_mul_f32_e32 v58, v10, v58
	v_fma_f32 v58, v154, v58, v170
	v_mul_f32_e32 v59, v59, v209
	v_mul_f32_e32 v59, v11, v59
	v_fma_f32 v59, v155, v59, v171
	v_cvt_pk_bf16_f32 v180, v56, v57
	v_cvt_pk_bf16_f32 v181, v58, v59
	global_store_dwordx2 v196, v[180:181], s[10:11] offset:1024
	s_nop 0
	v_mul_f32_e32 v60, v60, v209
	v_mul_f32_e32 v60, v12, v60
	v_fma_f32 v60, v156, v60, v172
	v_mul_f32_e32 v61, v61, v209
	v_mul_f32_e32 v61, v13, v61
	v_fma_f32 v61, v157, v61, v173
	v_mul_f32_e32 v62, v62, v209
	v_mul_f32_e32 v62, v14, v62
	v_fma_f32 v62, v158, v62, v174
	v_mul_f32_e32 v63, v63, v209
	v_mul_f32_e32 v63, v15, v63
	v_fma_f32 v63, v159, v63, v175
	v_cvt_pk_bf16_f32 v180, v60, v61
	v_cvt_pk_bf16_f32 v181, v62, v63
	global_store_dwordx2 v196, v[180:181], s[10:11] offset:1536
	s_nop 0
	v_mul_f32_e32 v64, v64, v210
	v_mul_f32_e32 v64, v0, v64
	v_fma_f32 v64, v144, v64, v160
	v_mul_f32_e32 v65, v65, v210
	v_mul_f32_e32 v65, v1, v65
	v_fma_f32 v65, v145, v65, v161
	v_mul_f32_e32 v66, v66, v210
	v_mul_f32_e32 v66, v2, v66
	v_fma_f32 v66, v146, v66, v162
	v_mul_f32_e32 v67, v67, v210
	v_mul_f32_e32 v67, v3, v67
	v_fma_f32 v67, v147, v67, v163
	v_cvt_pk_bf16_f32 v180, v64, v65
	v_cvt_pk_bf16_f32 v181, v66, v67
	global_store_dwordx2 v196, v[180:181], s[10:11] offset:2048
	s_nop 0
	v_mul_f32_e32 v68, v68, v210
	v_mul_f32_e32 v68, v4, v68
	v_fma_f32 v68, v148, v68, v164
	v_mul_f32_e32 v69, v69, v210
	v_mul_f32_e32 v69, v5, v69
	v_fma_f32 v69, v149, v69, v165
	v_mul_f32_e32 v70, v70, v210
	v_mul_f32_e32 v70, v6, v70
	v_fma_f32 v70, v150, v70, v166
	v_mul_f32_e32 v71, v71, v210
	v_mul_f32_e32 v71, v7, v71
	v_fma_f32 v71, v151, v71, v167
	v_cvt_pk_bf16_f32 v180, v68, v69
	v_cvt_pk_bf16_f32 v181, v70, v71
	global_store_dwordx2 v196, v[180:181], s[10:11] offset:2560
	s_nop 0
	v_mul_f32_e32 v72, v72, v210
	v_mul_f32_e32 v72, v8, v72
	v_fma_f32 v72, v152, v72, v168
	v_mul_f32_e32 v73, v73, v210
	v_mul_f32_e32 v73, v9, v73
	v_fma_f32 v73, v153, v73, v169
	v_mul_f32_e32 v74, v74, v210
	v_mul_f32_e32 v74, v10, v74
	v_fma_f32 v74, v154, v74, v170
	v_mul_f32_e32 v75, v75, v210
	v_mul_f32_e32 v75, v11, v75
	v_fma_f32 v75, v155, v75, v171
	v_cvt_pk_bf16_f32 v180, v72, v73
	v_cvt_pk_bf16_f32 v181, v74, v75
	global_store_dwordx2 v196, v[180:181], s[10:11] offset:3072
	s_nop 0
	v_mul_f32_e32 v76, v76, v210
	v_mul_f32_e32 v76, v12, v76
	v_fma_f32 v76, v156, v76, v172
	v_mul_f32_e32 v77, v77, v210
	v_mul_f32_e32 v77, v13, v77
	v_fma_f32 v77, v157, v77, v173
	v_mul_f32_e32 v78, v78, v210
	v_mul_f32_e32 v78, v14, v78
	v_fma_f32 v78, v158, v78, v174
	v_mul_f32_e32 v79, v79, v210
	v_mul_f32_e32 v79, v15, v79
	v_fma_f32 v79, v159, v79, v175
	v_cvt_pk_bf16_f32 v180, v76, v77
	v_cvt_pk_bf16_f32 v181, v78, v79
	global_store_dwordx2 v196, v[180:181], s[10:11] offset:3584
	s_nop 0
	s_add_u32 s14, s14, 0x2000
	s_addc_u32 s15, s15, 0
	global_load_dwordx4 v[48:51], v194, s[14:15]
	global_load_dwordx4 v[52:55], v194, s[14:15] offset:1024
	global_load_dwordx4 v[56:59], v194, s[14:15] offset:2048
	global_load_dwordx4 v[60:63], v194, s[14:15] offset:3072
	global_load_dwordx4 v[64:67], v195, s[14:15]
	global_load_dwordx4 v[68:71], v195, s[14:15] offset:1024
	global_load_dwordx4 v[72:75], v195, s[14:15] offset:2048
	global_load_dwordx4 v[76:79], v195, s[14:15] offset:3072
	s_waitcnt vmcnt(48)
	v_pk_mul_f32 v[178:179], v[80:81], v[80:81]
	v_pk_fma_f32 v[178:179], v[82:83], v[82:83], v[178:179]
	v_pk_fma_f32 v[178:179], v[84:85], v[84:85], v[178:179]
	v_pk_fma_f32 v[178:179], v[86:87], v[86:87], v[178:179]
	v_pk_fma_f32 v[178:179], v[88:89], v[88:89], v[178:179]
	v_pk_fma_f32 v[178:179], v[90:91], v[90:91], v[178:179]
	v_pk_fma_f32 v[178:179], v[92:93], v[92:93], v[178:179]
	v_pk_fma_f32 v[178:179], v[94:95], v[94:95], v[178:179]
	v_pk_mul_f32 v[180:181], v[96:97], v[96:97]
	v_pk_fma_f32 v[180:181], v[98:99], v[98:99], v[180:181]
	v_pk_fma_f32 v[180:181], v[100:101], v[100:101], v[180:181]
	v_pk_fma_f32 v[180:181], v[102:103], v[102:103], v[180:181]
	v_pk_fma_f32 v[180:181], v[104:105], v[104:105], v[180:181]
	v_pk_fma_f32 v[180:181], v[106:107], v[106:107], v[180:181]
	v_pk_fma_f32 v[180:181], v[108:109], v[108:109], v[180:181]
	v_pk_fma_f32 v[180:181], v[110:111], v[110:111], v[180:181]
	v_add_f32_e32 v176, v178, v179
	v_add_f32_e32 v177, v180, v181
	ds_bpermute_b32 v178, v198, v176
	ds_bpermute_b32 v179, v198, v177
	s_waitcnt lgkmcnt(0)
	v_add_f32_e32 v176, v176, v178
	v_add_f32_e32 v177, v177, v179
	ds_bpermute_b32 v178, v199, v176
	ds_bpermute_b32 v179, v199, v177
	s_waitcnt lgkmcnt(0)
	v_add_f32_e32 v176, v176, v178
	v_add_f32_e32 v177, v177, v179
	ds_bpermute_b32 v178, v200, v176
	ds_bpermute_b32 v179, v200, v177
	s_waitcnt lgkmcnt(0)
	v_add_f32_e32 v176, v176, v178
	v_add_f32_e32 v177, v177, v179
	ds_bpermute_b32 v178, v201, v176
	ds_bpermute_b32 v179, v201, v177
	s_waitcnt lgkmcnt(0)
	v_add_f32_e32 v176, v176, v178
	v_add_f32_e32 v177, v177, v179
	ds_bpermute_b32 v178, v202, v176
	ds_bpermute_b32 v179, v202, v177
	s_waitcnt lgkmcnt(0)
	v_add_f32_e32 v176, v176, v178
	v_add_f32_e32 v177, v177, v179
	ds_bpermute_b32 v178, v203, v176
	ds_bpermute_b32 v179, v203, v177
	s_waitcnt lgkmcnt(0)
	v_add_f32_e32 v176, v176, v178
	v_add_f32_e32 v177, v177, v179
	v_fmamk_f32 v176, v176, 0x3a800000, v208
	v_mul_f32_e32 v178, 0x4b800000, v176
	v_cmp_gt_f32_e32 vcc, s27, v176
	s_nop 1
	v_cndmask_b32_e32 v176, v176, v178, vcc
	v_rsq_f32_e32 v209, v176
	s_nop 0
	v_mul_f32_e32 v178, 0x45800000, v209
	v_cndmask_b32_e32 v209, v209, v178, vcc
	v_fmamk_f32 v177, v177, 0x3a800000, v208
	v_mul_f32_e32 v178, 0x4b800000, v177
	v_cmp_gt_f32_e32 vcc, s27, v177
	s_nop 1
	v_cndmask_b32_e32 v177, v177, v178, vcc
	v_rsq_f32_e32 v210, v177
	s_nop 0
	v_mul_f32_e32 v178, 0x45800000, v210
	v_cndmask_b32_e32 v210, v210, v178, vcc
	s_add_u32 s10, s10, 0x1000
	s_addc_u32 s11, s11, 0
	v_mul_f32_e32 v80, v80, v209
	v_mul_f32_e32 v80, v0, v80
	v_fma_f32 v80, v144, v80, v160
	v_mul_f32_e32 v81, v81, v209
	v_mul_f32_e32 v81, v1, v81
	v_fma_f32 v81, v145, v81, v161
	v_mul_f32_e32 v82, v82, v209
	v_mul_f32_e32 v82, v2, v82
	v_fma_f32 v82, v146, v82, v162
	v_mul_f32_e32 v83, v83, v209
	v_mul_f32_e32 v83, v3, v83
	v_fma_f32 v83, v147, v83, v163
	v_cvt_pk_bf16_f32 v180, v80, v81
	v_cvt_pk_bf16_f32 v181, v82, v83
	global_store_dwordx2 v196, v[180:181], s[10:11]
	s_nop 0
	v_mul_f32_e32 v84, v84, v209
	v_mul_f32_e32 v84, v4, v84
	v_fma_f32 v84, v148, v84, v164
	v_mul_f32_e32 v85, v85, v209
	v_mul_f32_e32 v85, v5, v85
	v_fma_f32 v85, v149, v85, v165
	v_mul_f32_e32 v86, v86, v209
	v_mul_f32_e32 v86, v6, v86
	v_fma_f32 v86, v150, v86, v166
	v_mul_f32_e32 v87, v87, v209
	v_mul_f32_e32 v87, v7, v87
	v_fma_f32 v87, v151, v87, v167
	v_cvt_pk_bf16_f32 v180, v84, v85
	v_cvt_pk_bf16_f32 v181, v86, v87
	global_store_dwordx2 v196, v[180:181], s[10:11] offset:512
	s_nop 0
	v_mul_f32_e32 v88, v88, v209
	v_mul_f32_e32 v88, v8, v88
	v_fma_f32 v88, v152, v88, v168
	v_mul_f32_e32 v89, v89, v209
	v_mul_f32_e32 v89, v9, v89
	v_fma_f32 v89, v153, v89, v169
	v_mul_f32_e32 v90, v90, v209
	v_mul_f32_e32 v90, v10, v90
	v_fma_f32 v90, v154, v90, v170
	v_mul_f32_e32 v91, v91, v209
	v_mul_f32_e32 v91, v11, v91
	v_fma_f32 v91, v155, v91, v171
	v_cvt_pk_bf16_f32 v180, v88, v89
	v_cvt_pk_bf16_f32 v181, v90, v91
	global_store_dwordx2 v196, v[180:181], s[10:11] offset:1024
	s_nop 0
	v_mul_f32_e32 v92, v92, v209
	v_mul_f32_e32 v92, v12, v92
	v_fma_f32 v92, v156, v92, v172
	v_mul_f32_e32 v93, v93, v209
	v_mul_f32_e32 v93, v13, v93
	v_fma_f32 v93, v157, v93, v173
	v_mul_f32_e32 v94, v94, v209
	v_mul_f32_e32 v94, v14, v94
	v_fma_f32 v94, v158, v94, v174
	v_mul_f32_e32 v95, v95, v209
	v_mul_f32_e32 v95, v15, v95
	v_fma_f32 v95, v159, v95, v175
	v_cvt_pk_bf16_f32 v180, v92, v93
	v_cvt_pk_bf16_f32 v181, v94, v95
	global_store_dwordx2 v196, v[180:181], s[10:11] offset:1536
	s_nop 0
	v_mul_f32_e32 v96, v96, v210
	v_mul_f32_e32 v96, v0, v96
	v_fma_f32 v96, v144, v96, v160
	v_mul_f32_e32 v97, v97, v210
	v_mul_f32_e32 v97, v1, v97
	v_fma_f32 v97, v145, v97, v161
	v_mul_f32_e32 v98, v98, v210
	v_mul_f32_e32 v98, v2, v98
	v_fma_f32 v98, v146, v98, v162
	v_mul_f32_e32 v99, v99, v210
	v_mul_f32_e32 v99, v3, v99
	v_fma_f32 v99, v147, v99, v163
	v_cvt_pk_bf16_f32 v180, v96, v97
	v_cvt_pk_bf16_f32 v181, v98, v99
	global_store_dwordx2 v196, v[180:181], s[10:11] offset:2048
	s_nop 0
	v_mul_f32_e32 v100, v100, v210
	v_mul_f32_e32 v100, v4, v100
	v_fma_f32 v100, v148, v100, v164
	v_mul_f32_e32 v101, v101, v210
	v_mul_f32_e32 v101, v5, v101
	v_fma_f32 v101, v149, v101, v165
	v_mul_f32_e32 v102, v102, v210
	v_mul_f32_e32 v102, v6, v102
	v_fma_f32 v102, v150, v102, v166
	v_mul_f32_e32 v103, v103, v210
	v_mul_f32_e32 v103, v7, v103
	v_fma_f32 v103, v151, v103, v167
	v_cvt_pk_bf16_f32 v180, v100, v101
	v_cvt_pk_bf16_f32 v181, v102, v103
	global_store_dwordx2 v196, v[180:181], s[10:11] offset:2560
	s_nop 0
	v_mul_f32_e32 v104, v104, v210
	v_mul_f32_e32 v104, v8, v104
	v_fma_f32 v104, v152, v104, v168
	v_mul_f32_e32 v105, v105, v210
	v_mul_f32_e32 v105, v9, v105
	v_fma_f32 v105, v153, v105, v169
	v_mul_f32_e32 v106, v106, v210
	v_mul_f32_e32 v106, v10, v106
	v_fma_f32 v106, v154, v106, v170
	v_mul_f32_e32 v107, v107, v210
	v_mul_f32_e32 v107, v11, v107
	v_fma_f32 v107, v155, v107, v171
	v_cvt_pk_bf16_f32 v180, v104, v105
	v_cvt_pk_bf16_f32 v181, v106, v107
	global_store_dwordx2 v196, v[180:181], s[10:11] offset:3072
	s_nop 0
	v_mul_f32_e32 v108, v108, v210
	v_mul_f32_e32 v108, v12, v108
	v_fma_f32 v108, v156, v108, v172
	v_mul_f32_e32 v109, v109, v210
	v_mul_f32_e32 v109, v13, v109
	v_fma_f32 v109, v157, v109, v173
	v_mul_f32_e32 v110, v110, v210
	v_mul_f32_e32 v110, v14, v110
	v_fma_f32 v110, v158, v110, v174
	v_mul_f32_e32 v111, v111, v210
	v_mul_f32_e32 v111, v15, v111
	v_fma_f32 v111, v159, v111, v175
	v_cvt_pk_bf16_f32 v180, v108, v109
	v_cvt_pk_bf16_f32 v181, v110, v111
	global_store_dwordx2 v196, v[180:181], s[10:11] offset:3584
	s_nop 0
	s_add_u32 s14, s14, 0x2000
	s_addc_u32 s15, s15, 0
	global_load_dwordx4 v[80:83], v194, s[14:15]
	global_load_dwordx4 v[84:87], v194, s[14:15] offset:1024
	global_load_dwordx4 v[88:91], v194, s[14:15] offset:2048
	global_load_dwordx4 v[92:95], v194, s[14:15] offset:3072
	global_load_dwordx4 v[96:99], v195, s[14:15]
	global_load_dwordx4 v[100:103], v195, s[14:15] offset:1024
	global_load_dwordx4 v[104:107], v195, s[14:15] offset:2048
	global_load_dwordx4 v[108:111], v195, s[14:15] offset:3072
	s_waitcnt vmcnt(48)
	v_pk_mul_f32 v[178:179], v[112:113], v[112:113]
	v_pk_fma_f32 v[178:179], v[114:115], v[114:115], v[178:179]
	v_pk_fma_f32 v[178:179], v[116:117], v[116:117], v[178:179]
	v_pk_fma_f32 v[178:179], v[118:119], v[118:119], v[178:179]
	v_pk_fma_f32 v[178:179], v[120:121], v[120:121], v[178:179]
	v_pk_fma_f32 v[178:179], v[122:123], v[122:123], v[178:179]
	v_pk_fma_f32 v[178:179], v[124:125], v[124:125], v[178:179]
	v_pk_fma_f32 v[178:179], v[126:127], v[126:127], v[178:179]
	v_pk_mul_f32 v[180:181], v[128:129], v[128:129]
	v_pk_fma_f32 v[180:181], v[130:131], v[130:131], v[180:181]
	v_pk_fma_f32 v[180:181], v[132:133], v[132:133], v[180:181]
	v_pk_fma_f32 v[180:181], v[134:135], v[134:135], v[180:181]
	v_pk_fma_f32 v[180:181], v[136:137], v[136:137], v[180:181]
	v_pk_fma_f32 v[180:181], v[138:139], v[138:139], v[180:181]
	v_pk_fma_f32 v[180:181], v[140:141], v[140:141], v[180:181]
	v_pk_fma_f32 v[180:181], v[142:143], v[142:143], v[180:181]
	v_add_f32_e32 v176, v178, v179
	v_add_f32_e32 v177, v180, v181
	ds_bpermute_b32 v178, v198, v176
	ds_bpermute_b32 v179, v198, v177
	s_waitcnt lgkmcnt(0)
	v_add_f32_e32 v176, v176, v178
	v_add_f32_e32 v177, v177, v179
	ds_bpermute_b32 v178, v199, v176
	ds_bpermute_b32 v179, v199, v177
	s_waitcnt lgkmcnt(0)
	v_add_f32_e32 v176, v176, v178
	v_add_f32_e32 v177, v177, v179
	ds_bpermute_b32 v178, v200, v176
	ds_bpermute_b32 v179, v200, v177
	s_waitcnt lgkmcnt(0)
	v_add_f32_e32 v176, v176, v178
	v_add_f32_e32 v177, v177, v179
	ds_bpermute_b32 v178, v201, v176
	ds_bpermute_b32 v179, v201, v177
	s_waitcnt lgkmcnt(0)
	v_add_f32_e32 v176, v176, v178
	v_add_f32_e32 v177, v177, v179
	ds_bpermute_b32 v178, v202, v176
	ds_bpermute_b32 v179, v202, v177
	s_waitcnt lgkmcnt(0)
	v_add_f32_e32 v176, v176, v178
	v_add_f32_e32 v177, v177, v179
	ds_bpermute_b32 v178, v203, v176
	ds_bpermute_b32 v179, v203, v177
	s_waitcnt lgkmcnt(0)
	v_add_f32_e32 v176, v176, v178
	v_add_f32_e32 v177, v177, v179
	v_fmamk_f32 v176, v176, 0x3a800000, v208
	v_mul_f32_e32 v178, 0x4b800000, v176
	v_cmp_gt_f32_e32 vcc, s27, v176
	s_nop 1
	v_cndmask_b32_e32 v176, v176, v178, vcc
	v_rsq_f32_e32 v209, v176
	s_nop 0
	v_mul_f32_e32 v178, 0x45800000, v209
	v_cndmask_b32_e32 v209, v209, v178, vcc
	v_fmamk_f32 v177, v177, 0x3a800000, v208
	v_mul_f32_e32 v178, 0x4b800000, v177
	v_cmp_gt_f32_e32 vcc, s27, v177
	s_nop 1
	v_cndmask_b32_e32 v177, v177, v178, vcc
	v_rsq_f32_e32 v210, v177
	s_nop 0
	v_mul_f32_e32 v178, 0x45800000, v210
	v_cndmask_b32_e32 v210, v210, v178, vcc
	s_add_u32 s10, s10, 0x1000
	s_addc_u32 s11, s11, 0
	v_mul_f32_e32 v112, v112, v209
	v_mul_f32_e32 v112, v0, v112
	v_fma_f32 v112, v144, v112, v160
	v_mul_f32_e32 v113, v113, v209
	v_mul_f32_e32 v113, v1, v113
	v_fma_f32 v113, v145, v113, v161
	v_mul_f32_e32 v114, v114, v209
	v_mul_f32_e32 v114, v2, v114
	v_fma_f32 v114, v146, v114, v162
	v_mul_f32_e32 v115, v115, v209
	v_mul_f32_e32 v115, v3, v115
	v_fma_f32 v115, v147, v115, v163
	v_cvt_pk_bf16_f32 v180, v112, v113
	v_cvt_pk_bf16_f32 v181, v114, v115
	global_store_dwordx2 v196, v[180:181], s[10:11]
	s_nop 0
	v_mul_f32_e32 v116, v116, v209
	v_mul_f32_e32 v116, v4, v116
	v_fma_f32 v116, v148, v116, v164
	v_mul_f32_e32 v117, v117, v209
	v_mul_f32_e32 v117, v5, v117
	v_fma_f32 v117, v149, v117, v165
	v_mul_f32_e32 v118, v118, v209
	v_mul_f32_e32 v118, v6, v118
	v_fma_f32 v118, v150, v118, v166
	v_mul_f32_e32 v119, v119, v209
	v_mul_f32_e32 v119, v7, v119
	v_fma_f32 v119, v151, v119, v167
	v_cvt_pk_bf16_f32 v180, v116, v117
	v_cvt_pk_bf16_f32 v181, v118, v119
	global_store_dwordx2 v196, v[180:181], s[10:11] offset:512
	s_nop 0
	v_mul_f32_e32 v120, v120, v209
	v_mul_f32_e32 v120, v8, v120
	v_fma_f32 v120, v152, v120, v168
	v_mul_f32_e32 v121, v121, v209
	v_mul_f32_e32 v121, v9, v121
	v_fma_f32 v121, v153, v121, v169
	v_mul_f32_e32 v122, v122, v209
	v_mul_f32_e32 v122, v10, v122
	v_fma_f32 v122, v154, v122, v170
	v_mul_f32_e32 v123, v123, v209
	v_mul_f32_e32 v123, v11, v123
	v_fma_f32 v123, v155, v123, v171
	v_cvt_pk_bf16_f32 v180, v120, v121
	v_cvt_pk_bf16_f32 v181, v122, v123
	global_store_dwordx2 v196, v[180:181], s[10:11] offset:1024
	s_nop 0
	v_mul_f32_e32 v124, v124, v209
	v_mul_f32_e32 v124, v12, v124
	v_fma_f32 v124, v156, v124, v172
	v_mul_f32_e32 v125, v125, v209
	v_mul_f32_e32 v125, v13, v125
	v_fma_f32 v125, v157, v125, v173
	v_mul_f32_e32 v126, v126, v209
	v_mul_f32_e32 v126, v14, v126
	v_fma_f32 v126, v158, v126, v174
	v_mul_f32_e32 v127, v127, v209
	v_mul_f32_e32 v127, v15, v127
	v_fma_f32 v127, v159, v127, v175
	v_cvt_pk_bf16_f32 v180, v124, v125
	v_cvt_pk_bf16_f32 v181, v126, v127
	global_store_dwordx2 v196, v[180:181], s[10:11] offset:1536
	s_nop 0
	v_mul_f32_e32 v128, v128, v210
	v_mul_f32_e32 v128, v0, v128
	v_fma_f32 v128, v144, v128, v160
	v_mul_f32_e32 v129, v129, v210
	v_mul_f32_e32 v129, v1, v129
	v_fma_f32 v129, v145, v129, v161
	v_mul_f32_e32 v130, v130, v210
	v_mul_f32_e32 v130, v2, v130
	v_fma_f32 v130, v146, v130, v162
	v_mul_f32_e32 v131, v131, v210
	v_mul_f32_e32 v131, v3, v131
	v_fma_f32 v131, v147, v131, v163
	v_cvt_pk_bf16_f32 v180, v128, v129
	v_cvt_pk_bf16_f32 v181, v130, v131
	global_store_dwordx2 v196, v[180:181], s[10:11] offset:2048
	s_nop 0
	v_mul_f32_e32 v132, v132, v210
	v_mul_f32_e32 v132, v4, v132
	v_fma_f32 v132, v148, v132, v164
	v_mul_f32_e32 v133, v133, v210
	v_mul_f32_e32 v133, v5, v133
	v_fma_f32 v133, v149, v133, v165
	v_mul_f32_e32 v134, v134, v210
	v_mul_f32_e32 v134, v6, v134
	v_fma_f32 v134, v150, v134, v166
	v_mul_f32_e32 v135, v135, v210
	v_mul_f32_e32 v135, v7, v135
	v_fma_f32 v135, v151, v135, v167
	v_cvt_pk_bf16_f32 v180, v132, v133
	v_cvt_pk_bf16_f32 v181, v134, v135
	global_store_dwordx2 v196, v[180:181], s[10:11] offset:2560
	s_nop 0
	v_mul_f32_e32 v136, v136, v210
	v_mul_f32_e32 v136, v8, v136
	v_fma_f32 v136, v152, v136, v168
	v_mul_f32_e32 v137, v137, v210
	v_mul_f32_e32 v137, v9, v137
	v_fma_f32 v137, v153, v137, v169
	v_mul_f32_e32 v138, v138, v210
	v_mul_f32_e32 v138, v10, v138
	v_fma_f32 v138, v154, v138, v170
	v_mul_f32_e32 v139, v139, v210
	v_mul_f32_e32 v139, v11, v139
	v_fma_f32 v139, v155, v139, v171
	v_cvt_pk_bf16_f32 v180, v136, v137
	v_cvt_pk_bf16_f32 v181, v138, v139
	global_store_dwordx2 v196, v[180:181], s[10:11] offset:3072
	s_nop 0
	v_mul_f32_e32 v140, v140, v210
	v_mul_f32_e32 v140, v12, v140
	v_fma_f32 v140, v156, v140, v172
	v_mul_f32_e32 v141, v141, v210
	v_mul_f32_e32 v141, v13, v141
	v_fma_f32 v141, v157, v141, v173
	v_mul_f32_e32 v142, v142, v210
	v_mul_f32_e32 v142, v14, v142
	v_fma_f32 v142, v158, v142, v174
	v_mul_f32_e32 v143, v143, v210
	v_mul_f32_e32 v143, v15, v143
	v_fma_f32 v143, v159, v143, v175
	v_cvt_pk_bf16_f32 v180, v140, v141
	v_cvt_pk_bf16_f32 v181, v142, v143
	global_store_dwordx2 v196, v[180:181], s[10:11] offset:3584
	s_nop 0
	s_add_u32 s14, s14, 0x2000
	s_addc_u32 s15, s15, 0
	global_load_dwordx4 v[112:115], v194, s[14:15]
	global_load_dwordx4 v[116:119], v194, s[14:15] offset:1024
	global_load_dwordx4 v[120:123], v194, s[14:15] offset:2048
	global_load_dwordx4 v[124:127], v194, s[14:15] offset:3072
	global_load_dwordx4 v[128:131], v195, s[14:15]
	global_load_dwordx4 v[132:135], v195, s[14:15] offset:1024
	global_load_dwordx4 v[136:139], v195, s[14:15] offset:2048
	global_load_dwordx4 v[140:143], v195, s[14:15] offset:3072
	s_waitcnt vmcnt(48)
	v_pk_mul_f32 v[178:179], v[16:17], v[16:17]
	v_pk_fma_f32 v[178:179], v[18:19], v[18:19], v[178:179]
	v_pk_fma_f32 v[178:179], v[20:21], v[20:21], v[178:179]
	v_pk_fma_f32 v[178:179], v[22:23], v[22:23], v[178:179]
	v_pk_fma_f32 v[178:179], v[24:25], v[24:25], v[178:179]
	v_pk_fma_f32 v[178:179], v[26:27], v[26:27], v[178:179]
	v_pk_fma_f32 v[178:179], v[28:29], v[28:29], v[178:179]
	v_pk_fma_f32 v[178:179], v[30:31], v[30:31], v[178:179]
	v_pk_mul_f32 v[180:181], v[32:33], v[32:33]
	v_pk_fma_f32 v[180:181], v[34:35], v[34:35], v[180:181]
	v_pk_fma_f32 v[180:181], v[36:37], v[36:37], v[180:181]
	v_pk_fma_f32 v[180:181], v[38:39], v[38:39], v[180:181]
	v_pk_fma_f32 v[180:181], v[40:41], v[40:41], v[180:181]
	v_pk_fma_f32 v[180:181], v[42:43], v[42:43], v[180:181]
	v_pk_fma_f32 v[180:181], v[44:45], v[44:45], v[180:181]
	v_pk_fma_f32 v[180:181], v[46:47], v[46:47], v[180:181]
	v_add_f32_e32 v176, v178, v179
	v_add_f32_e32 v177, v180, v181
	ds_bpermute_b32 v178, v198, v176
	ds_bpermute_b32 v179, v198, v177
	s_waitcnt lgkmcnt(0)
	v_add_f32_e32 v176, v176, v178
	v_add_f32_e32 v177, v177, v179
	ds_bpermute_b32 v178, v199, v176
	ds_bpermute_b32 v179, v199, v177
	s_waitcnt lgkmcnt(0)
	v_add_f32_e32 v176, v176, v178
	v_add_f32_e32 v177, v177, v179
	ds_bpermute_b32 v178, v200, v176
	ds_bpermute_b32 v179, v200, v177
	s_waitcnt lgkmcnt(0)
	v_add_f32_e32 v176, v176, v178
	v_add_f32_e32 v177, v177, v179
	ds_bpermute_b32 v178, v201, v176
	ds_bpermute_b32 v179, v201, v177
	s_waitcnt lgkmcnt(0)
	v_add_f32_e32 v176, v176, v178
	v_add_f32_e32 v177, v177, v179
	ds_bpermute_b32 v178, v202, v176
	ds_bpermute_b32 v179, v202, v177
	s_waitcnt lgkmcnt(0)
	v_add_f32_e32 v176, v176, v178
	v_add_f32_e32 v177, v177, v179
	ds_bpermute_b32 v178, v203, v176
	ds_bpermute_b32 v179, v203, v177
	s_waitcnt lgkmcnt(0)
	v_add_f32_e32 v176, v176, v178
	v_add_f32_e32 v177, v177, v179
	v_fmamk_f32 v176, v176, 0x3a800000, v208
	v_mul_f32_e32 v178, 0x4b800000, v176
	v_cmp_gt_f32_e32 vcc, s27, v176
	s_nop 1
	v_cndmask_b32_e32 v176, v176, v178, vcc
	v_rsq_f32_e32 v209, v176
	s_nop 0
	v_mul_f32_e32 v178, 0x45800000, v209
	v_cndmask_b32_e32 v209, v209, v178, vcc
	v_fmamk_f32 v177, v177, 0x3a800000, v208
	v_mul_f32_e32 v178, 0x4b800000, v177
	v_cmp_gt_f32_e32 vcc, s27, v177
	s_nop 1
	v_cndmask_b32_e32 v177, v177, v178, vcc
	v_rsq_f32_e32 v210, v177
	s_nop 0
	v_mul_f32_e32 v178, 0x45800000, v210
	v_cndmask_b32_e32 v210, v210, v178, vcc
	s_add_u32 s10, s10, 0x1000
	s_addc_u32 s11, s11, 0
	v_mul_f32_e32 v16, v16, v209
	v_mul_f32_e32 v16, v0, v16
	v_fma_f32 v16, v144, v16, v160
	v_mul_f32_e32 v17, v17, v209
	v_mul_f32_e32 v17, v1, v17
	v_fma_f32 v17, v145, v17, v161
	v_mul_f32_e32 v18, v18, v209
	v_mul_f32_e32 v18, v2, v18
	v_fma_f32 v18, v146, v18, v162
	v_mul_f32_e32 v19, v19, v209
	v_mul_f32_e32 v19, v3, v19
	v_fma_f32 v19, v147, v19, v163
	v_cvt_pk_bf16_f32 v180, v16, v17
	v_cvt_pk_bf16_f32 v181, v18, v19
	global_store_dwordx2 v196, v[180:181], s[10:11]
	s_nop 0
	v_mul_f32_e32 v20, v20, v209
	v_mul_f32_e32 v20, v4, v20
	v_fma_f32 v20, v148, v20, v164
	v_mul_f32_e32 v21, v21, v209
	v_mul_f32_e32 v21, v5, v21
	v_fma_f32 v21, v149, v21, v165
	v_mul_f32_e32 v22, v22, v209
	v_mul_f32_e32 v22, v6, v22
	v_fma_f32 v22, v150, v22, v166
	v_mul_f32_e32 v23, v23, v209
	v_mul_f32_e32 v23, v7, v23
	v_fma_f32 v23, v151, v23, v167
	v_cvt_pk_bf16_f32 v180, v20, v21
	v_cvt_pk_bf16_f32 v181, v22, v23
	global_store_dwordx2 v196, v[180:181], s[10:11] offset:512
	s_nop 0
	v_mul_f32_e32 v24, v24, v209
	v_mul_f32_e32 v24, v8, v24
	v_fma_f32 v24, v152, v24, v168
	v_mul_f32_e32 v25, v25, v209
	v_mul_f32_e32 v25, v9, v25
	v_fma_f32 v25, v153, v25, v169
	v_mul_f32_e32 v26, v26, v209
	v_mul_f32_e32 v26, v10, v26
	v_fma_f32 v26, v154, v26, v170
	v_mul_f32_e32 v27, v27, v209
	v_mul_f32_e32 v27, v11, v27
	v_fma_f32 v27, v155, v27, v171
	v_cvt_pk_bf16_f32 v180, v24, v25
	v_cvt_pk_bf16_f32 v181, v26, v27
	global_store_dwordx2 v196, v[180:181], s[10:11] offset:1024
	s_nop 0
	v_mul_f32_e32 v28, v28, v209
	v_mul_f32_e32 v28, v12, v28
	v_fma_f32 v28, v156, v28, v172
	v_mul_f32_e32 v29, v29, v209
	v_mul_f32_e32 v29, v13, v29
	v_fma_f32 v29, v157, v29, v173
	v_mul_f32_e32 v30, v30, v209
	v_mul_f32_e32 v30, v14, v30
	v_fma_f32 v30, v158, v30, v174
	v_mul_f32_e32 v31, v31, v209
	v_mul_f32_e32 v31, v15, v31
	v_fma_f32 v31, v159, v31, v175
	v_cvt_pk_bf16_f32 v180, v28, v29
	v_cvt_pk_bf16_f32 v181, v30, v31
	global_store_dwordx2 v196, v[180:181], s[10:11] offset:1536
	s_nop 0
	v_mul_f32_e32 v32, v32, v210
	v_mul_f32_e32 v32, v0, v32
	v_fma_f32 v32, v144, v32, v160
	v_mul_f32_e32 v33, v33, v210
	v_mul_f32_e32 v33, v1, v33
	v_fma_f32 v33, v145, v33, v161
	v_mul_f32_e32 v34, v34, v210
	v_mul_f32_e32 v34, v2, v34
	v_fma_f32 v34, v146, v34, v162
	v_mul_f32_e32 v35, v35, v210
	v_mul_f32_e32 v35, v3, v35
	v_fma_f32 v35, v147, v35, v163
	v_cvt_pk_bf16_f32 v180, v32, v33
	v_cvt_pk_bf16_f32 v181, v34, v35
	global_store_dwordx2 v196, v[180:181], s[10:11] offset:2048
	s_nop 0
	v_mul_f32_e32 v36, v36, v210
	v_mul_f32_e32 v36, v4, v36
	v_fma_f32 v36, v148, v36, v164
	v_mul_f32_e32 v37, v37, v210
	v_mul_f32_e32 v37, v5, v37
	v_fma_f32 v37, v149, v37, v165
	v_mul_f32_e32 v38, v38, v210
	v_mul_f32_e32 v38, v6, v38
	v_fma_f32 v38, v150, v38, v166
	v_mul_f32_e32 v39, v39, v210
	v_mul_f32_e32 v39, v7, v39
	v_fma_f32 v39, v151, v39, v167
	v_cvt_pk_bf16_f32 v180, v36, v37
	v_cvt_pk_bf16_f32 v181, v38, v39
	global_store_dwordx2 v196, v[180:181], s[10:11] offset:2560
	s_nop 0
	v_mul_f32_e32 v40, v40, v210
	v_mul_f32_e32 v40, v8, v40
	v_fma_f32 v40, v152, v40, v168
	v_mul_f32_e32 v41, v41, v210
	v_mul_f32_e32 v41, v9, v41
	v_fma_f32 v41, v153, v41, v169
	v_mul_f32_e32 v42, v42, v210
	v_mul_f32_e32 v42, v10, v42
	v_fma_f32 v42, v154, v42, v170
	v_mul_f32_e32 v43, v43, v210
	v_mul_f32_e32 v43, v11, v43
	v_fma_f32 v43, v155, v43, v171
	v_cvt_pk_bf16_f32 v180, v40, v41
	v_cvt_pk_bf16_f32 v181, v42, v43
	global_store_dwordx2 v196, v[180:181], s[10:11] offset:3072
	s_nop 0
	v_mul_f32_e32 v44, v44, v210
	v_mul_f32_e32 v44, v12, v44
	v_fma_f32 v44, v156, v44, v172
	v_mul_f32_e32 v45, v45, v210
	v_mul_f32_e32 v45, v13, v45
	v_fma_f32 v45, v157, v45, v173
	v_mul_f32_e32 v46, v46, v210
	v_mul_f32_e32 v46, v14, v46
	v_fma_f32 v46, v158, v46, v174
	v_mul_f32_e32 v47, v47, v210
	v_mul_f32_e32 v47, v15, v47
	v_fma_f32 v47, v159, v47, v175
	v_cvt_pk_bf16_f32 v180, v44, v45
	v_cvt_pk_bf16_f32 v181, v46, v47
	global_store_dwordx2 v196, v[180:181], s[10:11] offset:3584
	s_nop 0
	s_waitcnt vmcnt(40)
	v_pk_mul_f32 v[178:179], v[48:49], v[48:49]
	v_pk_fma_f32 v[178:179], v[50:51], v[50:51], v[178:179]
	v_pk_fma_f32 v[178:179], v[52:53], v[52:53], v[178:179]
	v_pk_fma_f32 v[178:179], v[54:55], v[54:55], v[178:179]
	v_pk_fma_f32 v[178:179], v[56:57], v[56:57], v[178:179]
	v_pk_fma_f32 v[178:179], v[58:59], v[58:59], v[178:179]
	v_pk_fma_f32 v[178:179], v[60:61], v[60:61], v[178:179]
	v_pk_fma_f32 v[178:179], v[62:63], v[62:63], v[178:179]
	v_pk_mul_f32 v[180:181], v[64:65], v[64:65]
	v_pk_fma_f32 v[180:181], v[66:67], v[66:67], v[180:181]
	v_pk_fma_f32 v[180:181], v[68:69], v[68:69], v[180:181]
	v_pk_fma_f32 v[180:181], v[70:71], v[70:71], v[180:181]
	v_pk_fma_f32 v[180:181], v[72:73], v[72:73], v[180:181]
	v_pk_fma_f32 v[180:181], v[74:75], v[74:75], v[180:181]
	v_pk_fma_f32 v[180:181], v[76:77], v[76:77], v[180:181]
	v_pk_fma_f32 v[180:181], v[78:79], v[78:79], v[180:181]
	v_add_f32_e32 v176, v178, v179
	v_add_f32_e32 v177, v180, v181
	ds_bpermute_b32 v178, v198, v176
	ds_bpermute_b32 v179, v198, v177
	s_waitcnt lgkmcnt(0)
	v_add_f32_e32 v176, v176, v178
	v_add_f32_e32 v177, v177, v179
	ds_bpermute_b32 v178, v199, v176
	ds_bpermute_b32 v179, v199, v177
	s_waitcnt lgkmcnt(0)
	v_add_f32_e32 v176, v176, v178
	v_add_f32_e32 v177, v177, v179
	ds_bpermute_b32 v178, v200, v176
	ds_bpermute_b32 v179, v200, v177
	s_waitcnt lgkmcnt(0)
	v_add_f32_e32 v176, v176, v178
	v_add_f32_e32 v177, v177, v179
	ds_bpermute_b32 v178, v201, v176
	ds_bpermute_b32 v179, v201, v177
	s_waitcnt lgkmcnt(0)
	v_add_f32_e32 v176, v176, v178
	v_add_f32_e32 v177, v177, v179
	ds_bpermute_b32 v178, v202, v176
	ds_bpermute_b32 v179, v202, v177
	s_waitcnt lgkmcnt(0)
	v_add_f32_e32 v176, v176, v178
	v_add_f32_e32 v177, v177, v179
	ds_bpermute_b32 v178, v203, v176
	ds_bpermute_b32 v179, v203, v177
	s_waitcnt lgkmcnt(0)
	v_add_f32_e32 v176, v176, v178
	v_add_f32_e32 v177, v177, v179
	v_fmamk_f32 v176, v176, 0x3a800000, v208
	v_mul_f32_e32 v178, 0x4b800000, v176
	v_cmp_gt_f32_e32 vcc, s27, v176
	s_nop 1
	v_cndmask_b32_e32 v176, v176, v178, vcc
	v_rsq_f32_e32 v209, v176
	s_nop 0
	v_mul_f32_e32 v178, 0x45800000, v209
	v_cndmask_b32_e32 v209, v209, v178, vcc
	v_fmamk_f32 v177, v177, 0x3a800000, v208
	v_mul_f32_e32 v178, 0x4b800000, v177
	v_cmp_gt_f32_e32 vcc, s27, v177
	s_nop 1
	v_cndmask_b32_e32 v177, v177, v178, vcc
	v_rsq_f32_e32 v210, v177
	s_nop 0
	v_mul_f32_e32 v178, 0x45800000, v210
	v_cndmask_b32_e32 v210, v210, v178, vcc
	s_add_u32 s10, s10, 0x1000
	s_addc_u32 s11, s11, 0
	v_mul_f32_e32 v48, v48, v209
	v_mul_f32_e32 v48, v0, v48
	v_fma_f32 v48, v144, v48, v160
	v_mul_f32_e32 v49, v49, v209
	v_mul_f32_e32 v49, v1, v49
	v_fma_f32 v49, v145, v49, v161
	v_mul_f32_e32 v50, v50, v209
	v_mul_f32_e32 v50, v2, v50
	v_fma_f32 v50, v146, v50, v162
	v_mul_f32_e32 v51, v51, v209
	v_mul_f32_e32 v51, v3, v51
	v_fma_f32 v51, v147, v51, v163
	v_cvt_pk_bf16_f32 v180, v48, v49
	v_cvt_pk_bf16_f32 v181, v50, v51
	global_store_dwordx2 v196, v[180:181], s[10:11]
	s_nop 0
	v_mul_f32_e32 v52, v52, v209
	v_mul_f32_e32 v52, v4, v52
	v_fma_f32 v52, v148, v52, v164
	v_mul_f32_e32 v53, v53, v209
	v_mul_f32_e32 v53, v5, v53
	v_fma_f32 v53, v149, v53, v165
	v_mul_f32_e32 v54, v54, v209
	v_mul_f32_e32 v54, v6, v54
	v_fma_f32 v54, v150, v54, v166
	v_mul_f32_e32 v55, v55, v209
	v_mul_f32_e32 v55, v7, v55
	v_fma_f32 v55, v151, v55, v167
	v_cvt_pk_bf16_f32 v180, v52, v53
	v_cvt_pk_bf16_f32 v181, v54, v55
	global_store_dwordx2 v196, v[180:181], s[10:11] offset:512
	s_nop 0
	v_mul_f32_e32 v56, v56, v209
	v_mul_f32_e32 v56, v8, v56
	v_fma_f32 v56, v152, v56, v168
	v_mul_f32_e32 v57, v57, v209
	v_mul_f32_e32 v57, v9, v57
	v_fma_f32 v57, v153, v57, v169
	v_mul_f32_e32 v58, v58, v209
	v_mul_f32_e32 v58, v10, v58
	v_fma_f32 v58, v154, v58, v170
	v_mul_f32_e32 v59, v59, v209
	v_mul_f32_e32 v59, v11, v59
	v_fma_f32 v59, v155, v59, v171
	v_cvt_pk_bf16_f32 v180, v56, v57
	v_cvt_pk_bf16_f32 v181, v58, v59
	global_store_dwordx2 v196, v[180:181], s[10:11] offset:1024
	s_nop 0
	v_mul_f32_e32 v60, v60, v209
	v_mul_f32_e32 v60, v12, v60
	v_fma_f32 v60, v156, v60, v172
	v_mul_f32_e32 v61, v61, v209
	v_mul_f32_e32 v61, v13, v61
	v_fma_f32 v61, v157, v61, v173
	v_mul_f32_e32 v62, v62, v209
	v_mul_f32_e32 v62, v14, v62
	v_fma_f32 v62, v158, v62, v174
	v_mul_f32_e32 v63, v63, v209
	v_mul_f32_e32 v63, v15, v63
	v_fma_f32 v63, v159, v63, v175
	v_cvt_pk_bf16_f32 v180, v60, v61
	v_cvt_pk_bf16_f32 v181, v62, v63
	global_store_dwordx2 v196, v[180:181], s[10:11] offset:1536
	s_nop 0
	v_mul_f32_e32 v64, v64, v210
	v_mul_f32_e32 v64, v0, v64
	v_fma_f32 v64, v144, v64, v160
	v_mul_f32_e32 v65, v65, v210
	v_mul_f32_e32 v65, v1, v65
	v_fma_f32 v65, v145, v65, v161
	v_mul_f32_e32 v66, v66, v210
	v_mul_f32_e32 v66, v2, v66
	v_fma_f32 v66, v146, v66, v162
	v_mul_f32_e32 v67, v67, v210
	v_mul_f32_e32 v67, v3, v67
	v_fma_f32 v67, v147, v67, v163
	v_cvt_pk_bf16_f32 v180, v64, v65
	v_cvt_pk_bf16_f32 v181, v66, v67
	global_store_dwordx2 v196, v[180:181], s[10:11] offset:2048
	s_nop 0
	v_mul_f32_e32 v68, v68, v210
	v_mul_f32_e32 v68, v4, v68
	v_fma_f32 v68, v148, v68, v164
	v_mul_f32_e32 v69, v69, v210
	v_mul_f32_e32 v69, v5, v69
	v_fma_f32 v69, v149, v69, v165
	v_mul_f32_e32 v70, v70, v210
	v_mul_f32_e32 v70, v6, v70
	v_fma_f32 v70, v150, v70, v166
	v_mul_f32_e32 v71, v71, v210
	v_mul_f32_e32 v71, v7, v71
	v_fma_f32 v71, v151, v71, v167
	v_cvt_pk_bf16_f32 v180, v68, v69
	v_cvt_pk_bf16_f32 v181, v70, v71
	global_store_dwordx2 v196, v[180:181], s[10:11] offset:2560
	s_nop 0
	v_mul_f32_e32 v72, v72, v210
	v_mul_f32_e32 v72, v8, v72
	v_fma_f32 v72, v152, v72, v168
	v_mul_f32_e32 v73, v73, v210
	v_mul_f32_e32 v73, v9, v73
	v_fma_f32 v73, v153, v73, v169
	v_mul_f32_e32 v74, v74, v210
	v_mul_f32_e32 v74, v10, v74
	v_fma_f32 v74, v154, v74, v170
	v_mul_f32_e32 v75, v75, v210
	v_mul_f32_e32 v75, v11, v75
	v_fma_f32 v75, v155, v75, v171
	v_cvt_pk_bf16_f32 v180, v72, v73
	v_cvt_pk_bf16_f32 v181, v74, v75
	global_store_dwordx2 v196, v[180:181], s[10:11] offset:3072
	s_nop 0
	v_mul_f32_e32 v76, v76, v210
	v_mul_f32_e32 v76, v12, v76
	v_fma_f32 v76, v156, v76, v172
	v_mul_f32_e32 v77, v77, v210
	v_mul_f32_e32 v77, v13, v77
	v_fma_f32 v77, v157, v77, v173
	v_mul_f32_e32 v78, v78, v210
	v_mul_f32_e32 v78, v14, v78
	v_fma_f32 v78, v158, v78, v174
	v_mul_f32_e32 v79, v79, v210
	v_mul_f32_e32 v79, v15, v79
	v_fma_f32 v79, v159, v79, v175
	v_cvt_pk_bf16_f32 v180, v76, v77
	v_cvt_pk_bf16_f32 v181, v78, v79
	global_store_dwordx2 v196, v[180:181], s[10:11] offset:3584
	s_nop 0
	s_waitcnt vmcnt(32)
	v_pk_mul_f32 v[178:179], v[80:81], v[80:81]
	v_pk_fma_f32 v[178:179], v[82:83], v[82:83], v[178:179]
	v_pk_fma_f32 v[178:179], v[84:85], v[84:85], v[178:179]
	v_pk_fma_f32 v[178:179], v[86:87], v[86:87], v[178:179]
	v_pk_fma_f32 v[178:179], v[88:89], v[88:89], v[178:179]
	v_pk_fma_f32 v[178:179], v[90:91], v[90:91], v[178:179]
	v_pk_fma_f32 v[178:179], v[92:93], v[92:93], v[178:179]
	v_pk_fma_f32 v[178:179], v[94:95], v[94:95], v[178:179]
	v_pk_mul_f32 v[180:181], v[96:97], v[96:97]
	v_pk_fma_f32 v[180:181], v[98:99], v[98:99], v[180:181]
	v_pk_fma_f32 v[180:181], v[100:101], v[100:101], v[180:181]
	v_pk_fma_f32 v[180:181], v[102:103], v[102:103], v[180:181]
	v_pk_fma_f32 v[180:181], v[104:105], v[104:105], v[180:181]
	v_pk_fma_f32 v[180:181], v[106:107], v[106:107], v[180:181]
	v_pk_fma_f32 v[180:181], v[108:109], v[108:109], v[180:181]
	v_pk_fma_f32 v[180:181], v[110:111], v[110:111], v[180:181]
	v_add_f32_e32 v176, v178, v179
	v_add_f32_e32 v177, v180, v181
	ds_bpermute_b32 v178, v198, v176
	ds_bpermute_b32 v179, v198, v177
	s_waitcnt lgkmcnt(0)
	v_add_f32_e32 v176, v176, v178
	v_add_f32_e32 v177, v177, v179
	ds_bpermute_b32 v178, v199, v176
	ds_bpermute_b32 v179, v199, v177
	s_waitcnt lgkmcnt(0)
	v_add_f32_e32 v176, v176, v178
	v_add_f32_e32 v177, v177, v179
	ds_bpermute_b32 v178, v200, v176
	ds_bpermute_b32 v179, v200, v177
	s_waitcnt lgkmcnt(0)
	v_add_f32_e32 v176, v176, v178
	v_add_f32_e32 v177, v177, v179
	ds_bpermute_b32 v178, v201, v176
	ds_bpermute_b32 v179, v201, v177
	s_waitcnt lgkmcnt(0)
	v_add_f32_e32 v176, v176, v178
	v_add_f32_e32 v177, v177, v179
	ds_bpermute_b32 v178, v202, v176
	ds_bpermute_b32 v179, v202, v177
	s_waitcnt lgkmcnt(0)
	v_add_f32_e32 v176, v176, v178
	v_add_f32_e32 v177, v177, v179
	ds_bpermute_b32 v178, v203, v176
	ds_bpermute_b32 v179, v203, v177
	s_waitcnt lgkmcnt(0)
	v_add_f32_e32 v176, v176, v178
	v_add_f32_e32 v177, v177, v179
	v_fmamk_f32 v176, v176, 0x3a800000, v208
	v_mul_f32_e32 v178, 0x4b800000, v176
	v_cmp_gt_f32_e32 vcc, s27, v176
	s_nop 1
	v_cndmask_b32_e32 v176, v176, v178, vcc
	v_rsq_f32_e32 v209, v176
	s_nop 0
	v_mul_f32_e32 v178, 0x45800000, v209
	v_cndmask_b32_e32 v209, v209, v178, vcc
	v_fmamk_f32 v177, v177, 0x3a800000, v208
	v_mul_f32_e32 v178, 0x4b800000, v177
	v_cmp_gt_f32_e32 vcc, s27, v177
	s_nop 1
	v_cndmask_b32_e32 v177, v177, v178, vcc
	v_rsq_f32_e32 v210, v177
	s_nop 0
	v_mul_f32_e32 v178, 0x45800000, v210
	v_cndmask_b32_e32 v210, v210, v178, vcc
	s_add_u32 s10, s10, 0x1000
	s_addc_u32 s11, s11, 0
	v_mul_f32_e32 v80, v80, v209
	v_mul_f32_e32 v80, v0, v80
	v_fma_f32 v80, v144, v80, v160
	v_mul_f32_e32 v81, v81, v209
	v_mul_f32_e32 v81, v1, v81
	v_fma_f32 v81, v145, v81, v161
	v_mul_f32_e32 v82, v82, v209
	v_mul_f32_e32 v82, v2, v82
	v_fma_f32 v82, v146, v82, v162
	v_mul_f32_e32 v83, v83, v209
	v_mul_f32_e32 v83, v3, v83
	v_fma_f32 v83, v147, v83, v163
	v_cvt_pk_bf16_f32 v180, v80, v81
	v_cvt_pk_bf16_f32 v181, v82, v83
	global_store_dwordx2 v196, v[180:181], s[10:11]
	s_nop 0
	v_mul_f32_e32 v84, v84, v209
	v_mul_f32_e32 v84, v4, v84
	v_fma_f32 v84, v148, v84, v164
	v_mul_f32_e32 v85, v85, v209
	v_mul_f32_e32 v85, v5, v85
	v_fma_f32 v85, v149, v85, v165
	v_mul_f32_e32 v86, v86, v209
	v_mul_f32_e32 v86, v6, v86
	v_fma_f32 v86, v150, v86, v166
	v_mul_f32_e32 v87, v87, v209
	v_mul_f32_e32 v87, v7, v87
	v_fma_f32 v87, v151, v87, v167
	v_cvt_pk_bf16_f32 v180, v84, v85
	v_cvt_pk_bf16_f32 v181, v86, v87
	global_store_dwordx2 v196, v[180:181], s[10:11] offset:512
	s_nop 0
	v_mul_f32_e32 v88, v88, v209
	v_mul_f32_e32 v88, v8, v88
	v_fma_f32 v88, v152, v88, v168
	v_mul_f32_e32 v89, v89, v209
	v_mul_f32_e32 v89, v9, v89
	v_fma_f32 v89, v153, v89, v169
	v_mul_f32_e32 v90, v90, v209
	v_mul_f32_e32 v90, v10, v90
	v_fma_f32 v90, v154, v90, v170
	v_mul_f32_e32 v91, v91, v209
	v_mul_f32_e32 v91, v11, v91
	v_fma_f32 v91, v155, v91, v171
	v_cvt_pk_bf16_f32 v180, v88, v89
	v_cvt_pk_bf16_f32 v181, v90, v91
	global_store_dwordx2 v196, v[180:181], s[10:11] offset:1024
	s_nop 0
	v_mul_f32_e32 v92, v92, v209
	v_mul_f32_e32 v92, v12, v92
	v_fma_f32 v92, v156, v92, v172
	v_mul_f32_e32 v93, v93, v209
	v_mul_f32_e32 v93, v13, v93
	v_fma_f32 v93, v157, v93, v173
	v_mul_f32_e32 v94, v94, v209
	v_mul_f32_e32 v94, v14, v94
	v_fma_f32 v94, v158, v94, v174
	v_mul_f32_e32 v95, v95, v209
	v_mul_f32_e32 v95, v15, v95
	v_fma_f32 v95, v159, v95, v175
	v_cvt_pk_bf16_f32 v180, v92, v93
	v_cvt_pk_bf16_f32 v181, v94, v95
	global_store_dwordx2 v196, v[180:181], s[10:11] offset:1536
	s_nop 0
	v_mul_f32_e32 v96, v96, v210
	v_mul_f32_e32 v96, v0, v96
	v_fma_f32 v96, v144, v96, v160
	v_mul_f32_e32 v97, v97, v210
	v_mul_f32_e32 v97, v1, v97
	v_fma_f32 v97, v145, v97, v161
	v_mul_f32_e32 v98, v98, v210
	v_mul_f32_e32 v98, v2, v98
	v_fma_f32 v98, v146, v98, v162
	v_mul_f32_e32 v99, v99, v210
	v_mul_f32_e32 v99, v3, v99
	v_fma_f32 v99, v147, v99, v163
	v_cvt_pk_bf16_f32 v180, v96, v97
	v_cvt_pk_bf16_f32 v181, v98, v99
	global_store_dwordx2 v196, v[180:181], s[10:11] offset:2048
	s_nop 0
	v_mul_f32_e32 v100, v100, v210
	v_mul_f32_e32 v100, v4, v100
	v_fma_f32 v100, v148, v100, v164
	v_mul_f32_e32 v101, v101, v210
	v_mul_f32_e32 v101, v5, v101
	v_fma_f32 v101, v149, v101, v165
	v_mul_f32_e32 v102, v102, v210
	v_mul_f32_e32 v102, v6, v102
	v_fma_f32 v102, v150, v102, v166
	v_mul_f32_e32 v103, v103, v210
	v_mul_f32_e32 v103, v7, v103
	v_fma_f32 v103, v151, v103, v167
	v_cvt_pk_bf16_f32 v180, v100, v101
	v_cvt_pk_bf16_f32 v181, v102, v103
	global_store_dwordx2 v196, v[180:181], s[10:11] offset:2560
	s_nop 0
	v_mul_f32_e32 v104, v104, v210
	v_mul_f32_e32 v104, v8, v104
	v_fma_f32 v104, v152, v104, v168
	v_mul_f32_e32 v105, v105, v210
	v_mul_f32_e32 v105, v9, v105
	v_fma_f32 v105, v153, v105, v169
	v_mul_f32_e32 v106, v106, v210
	v_mul_f32_e32 v106, v10, v106
	v_fma_f32 v106, v154, v106, v170
	v_mul_f32_e32 v107, v107, v210
	v_mul_f32_e32 v107, v11, v107
	v_fma_f32 v107, v155, v107, v171
	v_cvt_pk_bf16_f32 v180, v104, v105
	v_cvt_pk_bf16_f32 v181, v106, v107
	global_store_dwordx2 v196, v[180:181], s[10:11] offset:3072
	s_nop 0
	v_mul_f32_e32 v108, v108, v210
	v_mul_f32_e32 v108, v12, v108
	v_fma_f32 v108, v156, v108, v172
	v_mul_f32_e32 v109, v109, v210
	v_mul_f32_e32 v109, v13, v109
	v_fma_f32 v109, v157, v109, v173
	v_mul_f32_e32 v110, v110, v210
	v_mul_f32_e32 v110, v14, v110
	v_fma_f32 v110, v158, v110, v174
	v_mul_f32_e32 v111, v111, v210
	v_mul_f32_e32 v111, v15, v111
	v_fma_f32 v111, v159, v111, v175
	v_cvt_pk_bf16_f32 v180, v108, v109
	v_cvt_pk_bf16_f32 v181, v110, v111
	global_store_dwordx2 v196, v[180:181], s[10:11] offset:3584
	s_nop 0
	s_waitcnt vmcnt(24)
	v_pk_mul_f32 v[178:179], v[112:113], v[112:113]
	v_pk_fma_f32 v[178:179], v[114:115], v[114:115], v[178:179]
	v_pk_fma_f32 v[178:179], v[116:117], v[116:117], v[178:179]
	v_pk_fma_f32 v[178:179], v[118:119], v[118:119], v[178:179]
	v_pk_fma_f32 v[178:179], v[120:121], v[120:121], v[178:179]
	v_pk_fma_f32 v[178:179], v[122:123], v[122:123], v[178:179]
	v_pk_fma_f32 v[178:179], v[124:125], v[124:125], v[178:179]
	v_pk_fma_f32 v[178:179], v[126:127], v[126:127], v[178:179]
	v_pk_mul_f32 v[180:181], v[128:129], v[128:129]
	v_pk_fma_f32 v[180:181], v[130:131], v[130:131], v[180:181]
	v_pk_fma_f32 v[180:181], v[132:133], v[132:133], v[180:181]
	v_pk_fma_f32 v[180:181], v[134:135], v[134:135], v[180:181]
	v_pk_fma_f32 v[180:181], v[136:137], v[136:137], v[180:181]
	v_pk_fma_f32 v[180:181], v[138:139], v[138:139], v[180:181]
	v_pk_fma_f32 v[180:181], v[140:141], v[140:141], v[180:181]
	v_pk_fma_f32 v[180:181], v[142:143], v[142:143], v[180:181]
	v_add_f32_e32 v176, v178, v179
	v_add_f32_e32 v177, v180, v181
	ds_bpermute_b32 v178, v198, v176
	ds_bpermute_b32 v179, v198, v177
	s_waitcnt lgkmcnt(0)
	v_add_f32_e32 v176, v176, v178
	v_add_f32_e32 v177, v177, v179
	ds_bpermute_b32 v178, v199, v176
	ds_bpermute_b32 v179, v199, v177
	s_waitcnt lgkmcnt(0)
	v_add_f32_e32 v176, v176, v178
	v_add_f32_e32 v177, v177, v179
	ds_bpermute_b32 v178, v200, v176
	ds_bpermute_b32 v179, v200, v177
	s_waitcnt lgkmcnt(0)
	v_add_f32_e32 v176, v176, v178
	v_add_f32_e32 v177, v177, v179
	ds_bpermute_b32 v178, v201, v176
	ds_bpermute_b32 v179, v201, v177
	s_waitcnt lgkmcnt(0)
	v_add_f32_e32 v176, v176, v178
	v_add_f32_e32 v177, v177, v179
	ds_bpermute_b32 v178, v202, v176
	ds_bpermute_b32 v179, v202, v177
	s_waitcnt lgkmcnt(0)
	v_add_f32_e32 v176, v176, v178
	v_add_f32_e32 v177, v177, v179
	ds_bpermute_b32 v178, v203, v176
	ds_bpermute_b32 v179, v203, v177
	s_waitcnt lgkmcnt(0)
	v_add_f32_e32 v176, v176, v178
	v_add_f32_e32 v177, v177, v179
	v_fmamk_f32 v176, v176, 0x3a800000, v208
	v_mul_f32_e32 v178, 0x4b800000, v176
	v_cmp_gt_f32_e32 vcc, s27, v176
	s_nop 1
	v_cndmask_b32_e32 v176, v176, v178, vcc
	v_rsq_f32_e32 v209, v176
	s_nop 0
	v_mul_f32_e32 v178, 0x45800000, v209
	v_cndmask_b32_e32 v209, v209, v178, vcc
	v_fmamk_f32 v177, v177, 0x3a800000, v208
	v_mul_f32_e32 v178, 0x4b800000, v177
	v_cmp_gt_f32_e32 vcc, s27, v177
	s_nop 1
	v_cndmask_b32_e32 v177, v177, v178, vcc
	v_rsq_f32_e32 v210, v177
	s_nop 0
	v_mul_f32_e32 v178, 0x45800000, v210
	v_cndmask_b32_e32 v210, v210, v178, vcc
	s_add_u32 s10, s10, 0x1000
	s_addc_u32 s11, s11, 0
	v_mul_f32_e32 v112, v112, v209
	v_mul_f32_e32 v112, v0, v112
	v_fma_f32 v112, v144, v112, v160
	v_mul_f32_e32 v113, v113, v209
	v_mul_f32_e32 v113, v1, v113
	v_fma_f32 v113, v145, v113, v161
	v_mul_f32_e32 v114, v114, v209
	v_mul_f32_e32 v114, v2, v114
	v_fma_f32 v114, v146, v114, v162
	v_mul_f32_e32 v115, v115, v209
	v_mul_f32_e32 v115, v3, v115
	v_fma_f32 v115, v147, v115, v163
	v_cvt_pk_bf16_f32 v180, v112, v113
	v_cvt_pk_bf16_f32 v181, v114, v115
	global_store_dwordx2 v196, v[180:181], s[10:11]
	s_nop 0
	v_mul_f32_e32 v116, v116, v209
	v_mul_f32_e32 v116, v4, v116
	v_fma_f32 v116, v148, v116, v164
	v_mul_f32_e32 v117, v117, v209
	v_mul_f32_e32 v117, v5, v117
	v_fma_f32 v117, v149, v117, v165
	v_mul_f32_e32 v118, v118, v209
	v_mul_f32_e32 v118, v6, v118
	v_fma_f32 v118, v150, v118, v166
	v_mul_f32_e32 v119, v119, v209
	v_mul_f32_e32 v119, v7, v119
	v_fma_f32 v119, v151, v119, v167
	v_cvt_pk_bf16_f32 v180, v116, v117
	v_cvt_pk_bf16_f32 v181, v118, v119
	global_store_dwordx2 v196, v[180:181], s[10:11] offset:512
	s_nop 0
	v_mul_f32_e32 v120, v120, v209
	v_mul_f32_e32 v120, v8, v120
	v_fma_f32 v120, v152, v120, v168
	v_mul_f32_e32 v121, v121, v209
	v_mul_f32_e32 v121, v9, v121
	v_fma_f32 v121, v153, v121, v169
	v_mul_f32_e32 v122, v122, v209
	v_mul_f32_e32 v122, v10, v122
	v_fma_f32 v122, v154, v122, v170
	v_mul_f32_e32 v123, v123, v209
	v_mul_f32_e32 v123, v11, v123
	v_fma_f32 v123, v155, v123, v171
	v_cvt_pk_bf16_f32 v180, v120, v121
	v_cvt_pk_bf16_f32 v181, v122, v123
	global_store_dwordx2 v196, v[180:181], s[10:11] offset:1024
	s_nop 0
	v_mul_f32_e32 v124, v124, v209
	v_mul_f32_e32 v124, v12, v124
	v_fma_f32 v124, v156, v124, v172
	v_mul_f32_e32 v125, v125, v209
	v_mul_f32_e32 v125, v13, v125
	v_fma_f32 v125, v157, v125, v173
	v_mul_f32_e32 v126, v126, v209
	v_mul_f32_e32 v126, v14, v126
	v_fma_f32 v126, v158, v126, v174
	v_mul_f32_e32 v127, v127, v209
	v_mul_f32_e32 v127, v15, v127
	v_fma_f32 v127, v159, v127, v175
	v_cvt_pk_bf16_f32 v180, v124, v125
	v_cvt_pk_bf16_f32 v181, v126, v127
	global_store_dwordx2 v196, v[180:181], s[10:11] offset:1536
	s_nop 0
	v_mul_f32_e32 v128, v128, v210
	v_mul_f32_e32 v128, v0, v128
	v_fma_f32 v128, v144, v128, v160
	v_mul_f32_e32 v129, v129, v210
	v_mul_f32_e32 v129, v1, v129
	v_fma_f32 v129, v145, v129, v161
	v_mul_f32_e32 v130, v130, v210
	v_mul_f32_e32 v130, v2, v130
	v_fma_f32 v130, v146, v130, v162
	v_mul_f32_e32 v131, v131, v210
	v_mul_f32_e32 v131, v3, v131
	v_fma_f32 v131, v147, v131, v163
	v_cvt_pk_bf16_f32 v180, v128, v129
	v_cvt_pk_bf16_f32 v181, v130, v131
	global_store_dwordx2 v196, v[180:181], s[10:11] offset:2048
	s_nop 0
	v_mul_f32_e32 v132, v132, v210
	v_mul_f32_e32 v132, v4, v132
	v_fma_f32 v132, v148, v132, v164
	v_mul_f32_e32 v133, v133, v210
	v_mul_f32_e32 v133, v5, v133
	v_fma_f32 v133, v149, v133, v165
	v_mul_f32_e32 v134, v134, v210
	v_mul_f32_e32 v134, v6, v134
	v_fma_f32 v134, v150, v134, v166
	v_mul_f32_e32 v135, v135, v210
	v_mul_f32_e32 v135, v7, v135
	v_fma_f32 v135, v151, v135, v167
	v_cvt_pk_bf16_f32 v180, v132, v133
	v_cvt_pk_bf16_f32 v181, v134, v135
	global_store_dwordx2 v196, v[180:181], s[10:11] offset:2560
	s_nop 0
	v_mul_f32_e32 v136, v136, v210
	v_mul_f32_e32 v136, v8, v136
	v_fma_f32 v136, v152, v136, v168
	v_mul_f32_e32 v137, v137, v210
	v_mul_f32_e32 v137, v9, v137
	v_fma_f32 v137, v153, v137, v169
	v_mul_f32_e32 v138, v138, v210
	v_mul_f32_e32 v138, v10, v138
	v_fma_f32 v138, v154, v138, v170
	v_mul_f32_e32 v139, v139, v210
	v_mul_f32_e32 v139, v11, v139
	v_fma_f32 v139, v155, v139, v171
	v_cvt_pk_bf16_f32 v180, v136, v137
	v_cvt_pk_bf16_f32 v181, v138, v139
	global_store_dwordx2 v196, v[180:181], s[10:11] offset:3072
	s_nop 0
	v_mul_f32_e32 v140, v140, v210
	v_mul_f32_e32 v140, v12, v140
	v_fma_f32 v140, v156, v140, v172
	v_mul_f32_e32 v141, v141, v210
	v_mul_f32_e32 v141, v13, v141
	v_fma_f32 v141, v157, v141, v173
	v_mul_f32_e32 v142, v142, v210
	v_mul_f32_e32 v142, v14, v142
	v_fma_f32 v142, v158, v142, v174
	v_mul_f32_e32 v143, v143, v210
	v_mul_f32_e32 v143, v15, v143
	v_fma_f32 v143, v159, v143, v175
	v_cvt_pk_bf16_f32 v180, v140, v141
	v_cvt_pk_bf16_f32 v181, v142, v143
	global_store_dwordx2 v196, v[180:181], s[10:11] offset:3584
	s_nop 0

.LBB0_173:
	s_andn2_b64 vcc, exec, s[4:5]
	s_cbranch_vccnz .LBB0_179
	s_sub_i32 s2, s81, 32
	s_cmpk_lt_u32 s81, 0x820
	s_cselect_b32 s11, s2, -1
	s_and_b64 s[2:3], s[0:1], exec
	s_cselect_b32 s2, -1, s11
	s_cmp_lt_i32 s2, 0
	s_cbranch_scc1 .LBB0_179
	v_readfirstlane_b32 s3, v205
	v_lshlrev_b32_e32 v128, 4, v192
	v_lshlrev_b32_e32 v130, 3, v192
	v_mbcnt_hi_u32_b32 v131, -1, v207
	v_readlane_b32 s18, v241, 2
	v_readlane_b32 s19, v241, 3
	v_add_u32_e32 v129, 0x1000, v128
	v_xor_b32_e32 v132, 32, v131
	v_lshlrev_b32_e32 v132, 2, v132
	v_xor_b32_e32 v133, 16, v131
	v_lshlrev_b32_e32 v133, 2, v133
	v_xor_b32_e32 v134, 8, v131
	v_lshlrev_b32_e32 v134, 2, v134
	v_xor_b32_e32 v135, 4, v131
	v_lshlrev_b32_e32 v135, 2, v135
	v_xor_b32_e32 v136, 2, v131
	v_lshlrev_b32_e32 v136, 2, v136
	v_xor_b32_e32 v137, 1, v131
	v_lshlrev_b32_e32 v137, 2, v137
	v_mov_b32_e32 v138, 0x358637bd
	s_mov_b32 s29, 0x800000
	s_lshl_b32 s3, s3, 1
	global_load_dwordx4 v[0:3], v128, s[60:61]
	global_load_dwordx4 v[4:7], v128, s[60:61] offset:1024
	global_load_dwordx4 v[8:11], v128, s[60:61] offset:2048
	global_load_dwordx4 v[12:15], v128, s[60:61] offset:3072
	s_lshl_b32 s4, s2, 4
	s_add_u32 s4, s4, s3
	s_lshl_b32 s5, s4, 12
	s_add_u32 s14, s52, s5
	s_addc_u32 s15, s53, 0
	global_load_dwordx4 v[16:19], v128, s[14:15]
	global_load_dwordx4 v[20:23], v128, s[14:15] offset:1024
	global_load_dwordx4 v[24:27], v128, s[14:15] offset:2048
	global_load_dwordx4 v[28:31], v128, s[14:15] offset:3072
	global_load_dwordx4 v[32:35], v129, s[14:15]
	global_load_dwordx4 v[36:39], v129, s[14:15] offset:1024
	global_load_dwordx4 v[40:43], v129, s[14:15] offset:2048
	global_load_dwordx4 v[44:47], v129, s[14:15] offset:3072
.Lp1x_top0:
	s_lshr_b32 s4, s2, 8
	s_mul_i32 s4, s4, 0x3000
	s_add_u32 s16, s18, s4
	s_addc_u32 s17, s19, 0
	global_load_dwordx4 v[96:99], v128, s[16:17]
	global_load_dwordx4 v[100:103], v128, s[16:17] offset:1024
	global_load_dwordx4 v[104:107], v128, s[16:17] offset:2048
	global_load_dwordx4 v[108:111], v128, s[16:17] offset:3072
	global_load_dwordx4 v[80:83], v129, s[16:17]
	global_load_dwordx4 v[84:87], v129, s[16:17] offset:1024
	global_load_dwordx4 v[88:91], v129, s[16:17] offset:2048
	global_load_dwordx4 v[92:95], v129, s[16:17] offset:3072
	s_lshl_b32 s4, s2, 4
	s_add_u32 s4, s4, s3
	s_lshl_b32 s4, s4, 11
	s_add_u32 s10, s94, s4
	s_addc_u32 s11, s95, 0
	s_add_u32 s12, s2, 0xe0
	s_cmp_lt_u32 s12, 0x800
	s_cbranch_scc0 .Lp1x_last0
	s_lshl_b32 s4, s12, 4
	s_add_u32 s4, s4, s3
	s_lshl_b32 s5, s4, 12
	s_add_u32 s14, s52, s5
	s_addc_u32 s15, s53, 0
	global_load_dwordx4 v[48:51], v128, s[14:15]
	global_load_dwordx4 v[52:55], v128, s[14:15] offset:1024
	global_load_dwordx4 v[56:59], v128, s[14:15] offset:2048
	global_load_dwordx4 v[60:63], v128, s[14:15] offset:3072
	global_load_dwordx4 v[64:67], v129, s[14:15]
	global_load_dwordx4 v[68:71], v129, s[14:15] offset:1024
	global_load_dwordx4 v[72:75], v129, s[14:15] offset:2048
	global_load_dwordx4 v[76:79], v129, s[14:15] offset:3072
	s_waitcnt vmcnt(8)
	v_pk_mul_f32 v[114:115], v[16:17], v[16:17]
	v_pk_fma_f32 v[114:115], v[18:19], v[18:19], v[114:115]
	v_pk_fma_f32 v[114:115], v[20:21], v[20:21], v[114:115]
	v_pk_fma_f32 v[114:115], v[22:23], v[22:23], v[114:115]
	v_pk_fma_f32 v[114:115], v[24:25], v[24:25], v[114:115]
	v_pk_fma_f32 v[114:115], v[26:27], v[26:27], v[114:115]
	v_pk_fma_f32 v[114:115], v[28:29], v[28:29], v[114:115]
	v_pk_fma_f32 v[114:115], v[30:31], v[30:31], v[114:115]
	v_pk_mul_f32 v[116:117], v[32:33], v[32:33]
	v_pk_fma_f32 v[116:117], v[34:35], v[34:35], v[116:117]
	v_pk_fma_f32 v[116:117], v[36:37], v[36:37], v[116:117]
	v_pk_fma_f32 v[116:117], v[38:39], v[38:39], v[116:117]
	v_pk_fma_f32 v[116:117], v[40:41], v[40:41], v[116:117]
	v_pk_fma_f32 v[116:117], v[42:43], v[42:43], v[116:117]
	v_pk_fma_f32 v[116:117], v[44:45], v[44:45], v[116:117]
	v_pk_fma_f32 v[116:117], v[46:47], v[46:47], v[116:117]
	v_add_f32_e32 v112, v114, v115
	v_add_f32_e32 v113, v116, v117
	ds_bpermute_b32 v114, v132, v112
	ds_bpermute_b32 v115, v132, v113
	s_waitcnt lgkmcnt(0)
	v_add_f32_e32 v112, v112, v114
	v_add_f32_e32 v113, v113, v115
	ds_bpermute_b32 v114, v133, v112
	ds_bpermute_b32 v115, v133, v113
	s_waitcnt lgkmcnt(0)
	v_add_f32_e32 v112, v112, v114
	v_add_f32_e32 v113, v113, v115
	ds_bpermute_b32 v114, v134, v112
	ds_bpermute_b32 v115, v134, v113
	s_waitcnt lgkmcnt(0)
	v_add_f32_e32 v112, v112, v114
	v_add_f32_e32 v113, v113, v115
	ds_bpermute_b32 v114, v135, v112
	ds_bpermute_b32 v115, v135, v113
	s_waitcnt lgkmcnt(0)
	v_add_f32_e32 v112, v112, v114
	v_add_f32_e32 v113, v113, v115
	ds_bpermute_b32 v114, v136, v112
	ds_bpermute_b32 v115, v136, v113
	s_waitcnt lgkmcnt(0)
	v_add_f32_e32 v112, v112, v114
	v_add_f32_e32 v113, v113, v115
	ds_bpermute_b32 v114, v137, v112
	ds_bpermute_b32 v115, v137, v113
	s_waitcnt lgkmcnt(0)
	v_add_f32_e32 v112, v112, v114
	v_add_f32_e32 v113, v113, v115
	v_fmamk_f32 v112, v112, 0x3a800000, v138
	v_mul_f32_e32 v114, 0x4b800000, v112
	v_cmp_gt_f32_e32 vcc, s29, v112
	s_nop 1
	v_cndmask_b32_e32 v112, v112, v114, vcc
	v_rsq_f32_e32 v139, v112
	s_nop 0
	v_mul_f32_e32 v114, 0x45800000, v139
	v_cndmask_b32_e32 v139, v139, v114, vcc
	v_fmamk_f32 v113, v113, 0x3a800000, v138
	v_mul_f32_e32 v114, 0x4b800000, v113
	v_cmp_gt_f32_e32 vcc, s29, v113
	s_nop 1
	v_cndmask_b32_e32 v113, v113, v114, vcc
	v_rsq_f32_e32 v140, v113
	s_nop 0
	v_mul_f32_e32 v114, 0x45800000, v140
	v_cndmask_b32_e32 v140, v140, v114, vcc
	v_add_f32_e32 v80, 1.0, v80
	v_add_f32_e32 v81, 1.0, v81
	v_add_f32_e32 v82, 1.0, v82
	v_add_f32_e32 v83, 1.0, v83
	v_add_f32_e32 v84, 1.0, v84
	v_add_f32_e32 v85, 1.0, v85
	v_add_f32_e32 v86, 1.0, v86
	v_add_f32_e32 v87, 1.0, v87
	v_add_f32_e32 v88, 1.0, v88
	v_add_f32_e32 v89, 1.0, v89
	v_add_f32_e32 v90, 1.0, v90
	v_add_f32_e32 v91, 1.0, v91
	v_add_f32_e32 v92, 1.0, v92
	v_add_f32_e32 v93, 1.0, v93
	v_add_f32_e32 v94, 1.0, v94
	v_add_f32_e32 v95, 1.0, v95
	v_mul_f32_e32 v16, v16, v139
	v_mul_f32_e32 v16, v0, v16
	v_fma_f32 v16, v80, v16, v96
	v_mul_f32_e32 v17, v17, v139
	v_mul_f32_e32 v17, v1, v17
	v_fma_f32 v17, v81, v17, v97
	v_mul_f32_e32 v18, v18, v139
	v_mul_f32_e32 v18, v2, v18
	v_fma_f32 v18, v82, v18, v98
	v_mul_f32_e32 v19, v19, v139
	v_mul_f32_e32 v19, v3, v19
	v_fma_f32 v19, v83, v19, v99
	v_cvt_pk_bf16_f32 v116, v16, v17
	v_cvt_pk_bf16_f32 v117, v18, v19
	global_store_dwordx2 v130, v[116:117], s[10:11]
	s_nop 0
	v_mul_f32_e32 v20, v20, v139
	v_mul_f32_e32 v20, v4, v20
	v_fma_f32 v20, v84, v20, v100
	v_mul_f32_e32 v21, v21, v139
	v_mul_f32_e32 v21, v5, v21
	v_fma_f32 v21, v85, v21, v101
	v_mul_f32_e32 v22, v22, v139
	v_mul_f32_e32 v22, v6, v22
	v_fma_f32 v22, v86, v22, v102
	v_mul_f32_e32 v23, v23, v139
	v_mul_f32_e32 v23, v7, v23
	v_fma_f32 v23, v87, v23, v103
	v_cvt_pk_bf16_f32 v116, v20, v21
	v_cvt_pk_bf16_f32 v117, v22, v23
	global_store_dwordx2 v130, v[116:117], s[10:11] offset:512
	s_nop 0
	v_mul_f32_e32 v24, v24, v139
	v_mul_f32_e32 v24, v8, v24
	v_fma_f32 v24, v88, v24, v104
	v_mul_f32_e32 v25, v25, v139
	v_mul_f32_e32 v25, v9, v25
	v_fma_f32 v25, v89, v25, v105
	v_mul_f32_e32 v26, v26, v139
	v_mul_f32_e32 v26, v10, v26
	v_fma_f32 v26, v90, v26, v106
	v_mul_f32_e32 v27, v27, v139
	v_mul_f32_e32 v27, v11, v27
	v_fma_f32 v27, v91, v27, v107
	v_cvt_pk_bf16_f32 v116, v24, v25
	v_cvt_pk_bf16_f32 v117, v26, v27
	global_store_dwordx2 v130, v[116:117], s[10:11] offset:1024
	s_nop 0
	v_mul_f32_e32 v28, v28, v139
	v_mul_f32_e32 v28, v12, v28
	v_fma_f32 v28, v92, v28, v108
	v_mul_f32_e32 v29, v29, v139
	v_mul_f32_e32 v29, v13, v29
	v_fma_f32 v29, v93, v29, v109
	v_mul_f32_e32 v30, v30, v139
	v_mul_f32_e32 v30, v14, v30
	v_fma_f32 v30, v94, v30, v110
	v_mul_f32_e32 v31, v31, v139
	v_mul_f32_e32 v31, v15, v31
	v_fma_f32 v31, v95, v31, v111
	v_cvt_pk_bf16_f32 v116, v28, v29
	v_cvt_pk_bf16_f32 v117, v30, v31
	global_store_dwordx2 v130, v[116:117], s[10:11] offset:1536
	s_nop 0
	v_mul_f32_e32 v32, v32, v140
	v_mul_f32_e32 v32, v0, v32
	v_fma_f32 v32, v80, v32, v96
	v_mul_f32_e32 v33, v33, v140
	v_mul_f32_e32 v33, v1, v33
	v_fma_f32 v33, v81, v33, v97
	v_mul_f32_e32 v34, v34, v140
	v_mul_f32_e32 v34, v2, v34
	v_fma_f32 v34, v82, v34, v98
	v_mul_f32_e32 v35, v35, v140
	v_mul_f32_e32 v35, v3, v35
	v_fma_f32 v35, v83, v35, v99
	v_cvt_pk_bf16_f32 v116, v32, v33
	v_cvt_pk_bf16_f32 v117, v34, v35
	global_store_dwordx2 v130, v[116:117], s[10:11] offset:2048
	s_nop 0
	v_mul_f32_e32 v36, v36, v140
	v_mul_f32_e32 v36, v4, v36
	v_fma_f32 v36, v84, v36, v100
	v_mul_f32_e32 v37, v37, v140
	v_mul_f32_e32 v37, v5, v37
	v_fma_f32 v37, v85, v37, v101
	v_mul_f32_e32 v38, v38, v140
	v_mul_f32_e32 v38, v6, v38
	v_fma_f32 v38, v86, v38, v102
	v_mul_f32_e32 v39, v39, v140
	v_mul_f32_e32 v39, v7, v39
	v_fma_f32 v39, v87, v39, v103
	v_cvt_pk_bf16_f32 v116, v36, v37
	v_cvt_pk_bf16_f32 v117, v38, v39
	global_store_dwordx2 v130, v[116:117], s[10:11] offset:2560
	s_nop 0
	v_mul_f32_e32 v40, v40, v140
	v_mul_f32_e32 v40, v8, v40
	v_fma_f32 v40, v88, v40, v104
	v_mul_f32_e32 v41, v41, v140
	v_mul_f32_e32 v41, v9, v41
	v_fma_f32 v41, v89, v41, v105
	v_mul_f32_e32 v42, v42, v140
	v_mul_f32_e32 v42, v10, v42
	v_fma_f32 v42, v90, v42, v106
	v_mul_f32_e32 v43, v43, v140
	v_mul_f32_e32 v43, v11, v43
	v_fma_f32 v43, v91, v43, v107
	v_cvt_pk_bf16_f32 v116, v40, v41
	v_cvt_pk_bf16_f32 v117, v42, v43
	global_store_dwordx2 v130, v[116:117], s[10:11] offset:3072
	s_nop 0
	v_mul_f32_e32 v44, v44, v140
	v_mul_f32_e32 v44, v12, v44
	v_fma_f32 v44, v92, v44, v108
	v_mul_f32_e32 v45, v45, v140
	v_mul_f32_e32 v45, v13, v45
	v_fma_f32 v45, v93, v45, v109
	v_mul_f32_e32 v46, v46, v140
	v_mul_f32_e32 v46, v14, v46
	v_fma_f32 v46, v94, v46, v110
	v_mul_f32_e32 v47, v47, v140
	v_mul_f32_e32 v47, v15, v47
	v_fma_f32 v47, v95, v47, v111
	v_cvt_pk_bf16_f32 v116, v44, v45
	v_cvt_pk_bf16_f32 v117, v46, v47
	global_store_dwordx2 v130, v[116:117], s[10:11] offset:3584
	s_nop 0
	s_mov_b32 s2, s12
	s_branch .Lp1x_top1
.Lp1x_last0:
	s_waitcnt vmcnt(0)
	v_pk_mul_f32 v[114:115], v[16:17], v[16:17]
	v_pk_fma_f32 v[114:115], v[18:19], v[18:19], v[114:115]
	v_pk_fma_f32 v[114:115], v[20:21], v[20:21], v[114:115]
	v_pk_fma_f32 v[114:115], v[22:23], v[22:23], v[114:115]
	v_pk_fma_f32 v[114:115], v[24:25], v[24:25], v[114:115]
	v_pk_fma_f32 v[114:115], v[26:27], v[26:27], v[114:115]
	v_pk_fma_f32 v[114:115], v[28:29], v[28:29], v[114:115]
	v_pk_fma_f32 v[114:115], v[30:31], v[30:31], v[114:115]
	v_pk_mul_f32 v[116:117], v[32:33], v[32:33]
	v_pk_fma_f32 v[116:117], v[34:35], v[34:35], v[116:117]
	v_pk_fma_f32 v[116:117], v[36:37], v[36:37], v[116:117]
	v_pk_fma_f32 v[116:117], v[38:39], v[38:39], v[116:117]
	v_pk_fma_f32 v[116:117], v[40:41], v[40:41], v[116:117]
	v_pk_fma_f32 v[116:117], v[42:43], v[42:43], v[116:117]
	v_pk_fma_f32 v[116:117], v[44:45], v[44:45], v[116:117]
	v_pk_fma_f32 v[116:117], v[46:47], v[46:47], v[116:117]
	v_add_f32_e32 v112, v114, v115
	v_add_f32_e32 v113, v116, v117
	ds_bpermute_b32 v114, v132, v112
	ds_bpermute_b32 v115, v132, v113
	s_waitcnt lgkmcnt(0)
	v_add_f32_e32 v112, v112, v114
	v_add_f32_e32 v113, v113, v115
	ds_bpermute_b32 v114, v133, v112
	ds_bpermute_b32 v115, v133, v113
	s_waitcnt lgkmcnt(0)
	v_add_f32_e32 v112, v112, v114
	v_add_f32_e32 v113, v113, v115
	ds_bpermute_b32 v114, v134, v112
	ds_bpermute_b32 v115, v134, v113
	s_waitcnt lgkmcnt(0)
	v_add_f32_e32 v112, v112, v114
	v_add_f32_e32 v113, v113, v115
	ds_bpermute_b32 v114, v135, v112
	ds_bpermute_b32 v115, v135, v113
	s_waitcnt lgkmcnt(0)
	v_add_f32_e32 v112, v112, v114
	v_add_f32_e32 v113, v113, v115
	ds_bpermute_b32 v114, v136, v112
	ds_bpermute_b32 v115, v136, v113
	s_waitcnt lgkmcnt(0)
	v_add_f32_e32 v112, v112, v114
	v_add_f32_e32 v113, v113, v115
	ds_bpermute_b32 v114, v137, v112
	ds_bpermute_b32 v115, v137, v113
	s_waitcnt lgkmcnt(0)
	v_add_f32_e32 v112, v112, v114
	v_add_f32_e32 v113, v113, v115
	v_fmamk_f32 v112, v112, 0x3a800000, v138
	v_mul_f32_e32 v114, 0x4b800000, v112
	v_cmp_gt_f32_e32 vcc, s29, v112
	s_nop 1
	v_cndmask_b32_e32 v112, v112, v114, vcc
	v_rsq_f32_e32 v139, v112
	s_nop 0
	v_mul_f32_e32 v114, 0x45800000, v139
	v_cndmask_b32_e32 v139, v139, v114, vcc
	v_fmamk_f32 v113, v113, 0x3a800000, v138
	v_mul_f32_e32 v114, 0x4b800000, v113
	v_cmp_gt_f32_e32 vcc, s29, v113
	s_nop 1
	v_cndmask_b32_e32 v113, v113, v114, vcc
	v_rsq_f32_e32 v140, v113
	s_nop 0
	v_mul_f32_e32 v114, 0x45800000, v140
	v_cndmask_b32_e32 v140, v140, v114, vcc
	v_add_f32_e32 v80, 1.0, v80
	v_add_f32_e32 v81, 1.0, v81
	v_add_f32_e32 v82, 1.0, v82
	v_add_f32_e32 v83, 1.0, v83
	v_add_f32_e32 v84, 1.0, v84
	v_add_f32_e32 v85, 1.0, v85
	v_add_f32_e32 v86, 1.0, v86
	v_add_f32_e32 v87, 1.0, v87
	v_add_f32_e32 v88, 1.0, v88
	v_add_f32_e32 v89, 1.0, v89
	v_add_f32_e32 v90, 1.0, v90
	v_add_f32_e32 v91, 1.0, v91
	v_add_f32_e32 v92, 1.0, v92
	v_add_f32_e32 v93, 1.0, v93
	v_add_f32_e32 v94, 1.0, v94
	v_add_f32_e32 v95, 1.0, v95
	v_mul_f32_e32 v16, v16, v139
	v_mul_f32_e32 v16, v0, v16
	v_fma_f32 v16, v80, v16, v96
	v_mul_f32_e32 v17, v17, v139
	v_mul_f32_e32 v17, v1, v17
	v_fma_f32 v17, v81, v17, v97
	v_mul_f32_e32 v18, v18, v139
	v_mul_f32_e32 v18, v2, v18
	v_fma_f32 v18, v82, v18, v98
	v_mul_f32_e32 v19, v19, v139
	v_mul_f32_e32 v19, v3, v19
	v_fma_f32 v19, v83, v19, v99
	v_cvt_pk_bf16_f32 v116, v16, v17
	v_cvt_pk_bf16_f32 v117, v18, v19
	global_store_dwordx2 v130, v[116:117], s[10:11]
	s_nop 0
	v_mul_f32_e32 v20, v20, v139
	v_mul_f32_e32 v20, v4, v20
	v_fma_f32 v20, v84, v20, v100
	v_mul_f32_e32 v21, v21, v139
	v_mul_f32_e32 v21, v5, v21
	v_fma_f32 v21, v85, v21, v101
	v_mul_f32_e32 v22, v22, v139
	v_mul_f32_e32 v22, v6, v22
	v_fma_f32 v22, v86, v22, v102
	v_mul_f32_e32 v23, v23, v139
	v_mul_f32_e32 v23, v7, v23
	v_fma_f32 v23, v87, v23, v103
	v_cvt_pk_bf16_f32 v116, v20, v21
	v_cvt_pk_bf16_f32 v117, v22, v23
	global_store_dwordx2 v130, v[116:117], s[10:11] offset:512
	s_nop 0
	v_mul_f32_e32 v24, v24, v139
	v_mul_f32_e32 v24, v8, v24
	v_fma_f32 v24, v88, v24, v104
	v_mul_f32_e32 v25, v25, v139
	v_mul_f32_e32 v25, v9, v25
	v_fma_f32 v25, v89, v25, v105
	v_mul_f32_e32 v26, v26, v139
	v_mul_f32_e32 v26, v10, v26
	v_fma_f32 v26, v90, v26, v106
	v_mul_f32_e32 v27, v27, v139
	v_mul_f32_e32 v27, v11, v27
	v_fma_f32 v27, v91, v27, v107
	v_cvt_pk_bf16_f32 v116, v24, v25
	v_cvt_pk_bf16_f32 v117, v26, v27
	global_store_dwordx2 v130, v[116:117], s[10:11] offset:1024
	s_nop 0
	v_mul_f32_e32 v28, v28, v139
	v_mul_f32_e32 v28, v12, v28
	v_fma_f32 v28, v92, v28, v108
	v_mul_f32_e32 v29, v29, v139
	v_mul_f32_e32 v29, v13, v29
	v_fma_f32 v29, v93, v29, v109
	v_mul_f32_e32 v30, v30, v139
	v_mul_f32_e32 v30, v14, v30
	v_fma_f32 v30, v94, v30, v110
	v_mul_f32_e32 v31, v31, v139
	v_mul_f32_e32 v31, v15, v31
	v_fma_f32 v31, v95, v31, v111
	v_cvt_pk_bf16_f32 v116, v28, v29
	v_cvt_pk_bf16_f32 v117, v30, v31
	global_store_dwordx2 v130, v[116:117], s[10:11] offset:1536
	s_nop 0
	v_mul_f32_e32 v32, v32, v140
	v_mul_f32_e32 v32, v0, v32
	v_fma_f32 v32, v80, v32, v96
	v_mul_f32_e32 v33, v33, v140
	v_mul_f32_e32 v33, v1, v33
	v_fma_f32 v33, v81, v33, v97
	v_mul_f32_e32 v34, v34, v140
	v_mul_f32_e32 v34, v2, v34
	v_fma_f32 v34, v82, v34, v98
	v_mul_f32_e32 v35, v35, v140
	v_mul_f32_e32 v35, v3, v35
	v_fma_f32 v35, v83, v35, v99
	v_cvt_pk_bf16_f32 v116, v32, v33
	v_cvt_pk_bf16_f32 v117, v34, v35
	global_store_dwordx2 v130, v[116:117], s[10:11] offset:2048
	s_nop 0
	v_mul_f32_e32 v36, v36, v140
	v_mul_f32_e32 v36, v4, v36
	v_fma_f32 v36, v84, v36, v100
	v_mul_f32_e32 v37, v37, v140
	v_mul_f32_e32 v37, v5, v37
	v_fma_f32 v37, v85, v37, v101
	v_mul_f32_e32 v38, v38, v140
	v_mul_f32_e32 v38, v6, v38
	v_fma_f32 v38, v86, v38, v102
	v_mul_f32_e32 v39, v39, v140
	v_mul_f32_e32 v39, v7, v39
	v_fma_f32 v39, v87, v39, v103
	v_cvt_pk_bf16_f32 v116, v36, v37
	v_cvt_pk_bf16_f32 v117, v38, v39
	global_store_dwordx2 v130, v[116:117], s[10:11] offset:2560
	s_nop 0
	v_mul_f32_e32 v40, v40, v140
	v_mul_f32_e32 v40, v8, v40
	v_fma_f32 v40, v88, v40, v104
	v_mul_f32_e32 v41, v41, v140
	v_mul_f32_e32 v41, v9, v41
	v_fma_f32 v41, v89, v41, v105
	v_mul_f32_e32 v42, v42, v140
	v_mul_f32_e32 v42, v10, v42
	v_fma_f32 v42, v90, v42, v106
	v_mul_f32_e32 v43, v43, v140
	v_mul_f32_e32 v43, v11, v43
	v_fma_f32 v43, v91, v43, v107
	v_cvt_pk_bf16_f32 v116, v40, v41
	v_cvt_pk_bf16_f32 v117, v42, v43
	global_store_dwordx2 v130, v[116:117], s[10:11] offset:3072
	s_nop 0
	v_mul_f32_e32 v44, v44, v140
	v_mul_f32_e32 v44, v12, v44
	v_fma_f32 v44, v92, v44, v108
	v_mul_f32_e32 v45, v45, v140
	v_mul_f32_e32 v45, v13, v45
	v_fma_f32 v45, v93, v45, v109
	v_mul_f32_e32 v46, v46, v140
	v_mul_f32_e32 v46, v14, v46
	v_fma_f32 v46, v94, v46, v110
	v_mul_f32_e32 v47, v47, v140
	v_mul_f32_e32 v47, v15, v47
	v_fma_f32 v47, v95, v47, v111
	v_cvt_pk_bf16_f32 v116, v44, v45
	v_cvt_pk_bf16_f32 v117, v46, v47
	global_store_dwordx2 v130, v[116:117], s[10:11] offset:3584
	s_nop 0
	s_branch .LBB0_179
.Lp1x_top1:
	s_lshr_b32 s4, s2, 8
	s_mul_i32 s4, s4, 0x3000
	s_add_u32 s16, s18, s4
	s_addc_u32 s17, s19, 0
	global_load_dwordx4 v[96:99], v128, s[16:17]
	global_load_dwordx4 v[100:103], v128, s[16:17] offset:1024
	global_load_dwordx4 v[104:107], v128, s[16:17] offset:2048
	global_load_dwordx4 v[108:111], v128, s[16:17] offset:3072
	global_load_dwordx4 v[80:83], v129, s[16:17]
	global_load_dwordx4 v[84:87], v129, s[16:17] offset:1024
	global_load_dwordx4 v[88:91], v129, s[16:17] offset:2048
	global_load_dwordx4 v[92:95], v129, s[16:17] offset:3072
	s_lshl_b32 s4, s2, 4
	s_add_u32 s4, s4, s3
	s_lshl_b32 s4, s4, 11
	s_add_u32 s10, s94, s4
	s_addc_u32 s11, s95, 0
	s_add_u32 s12, s2, 0xe0
	s_cmp_lt_u32 s12, 0x800
	s_cbranch_scc0 .Lp1x_last1
	s_lshl_b32 s4, s12, 4
	s_add_u32 s4, s4, s3
	s_lshl_b32 s5, s4, 12
	s_add_u32 s14, s52, s5
	s_addc_u32 s15, s53, 0
	global_load_dwordx4 v[16:19], v128, s[14:15]
	global_load_dwordx4 v[20:23], v128, s[14:15] offset:1024
	global_load_dwordx4 v[24:27], v128, s[14:15] offset:2048
	global_load_dwordx4 v[28:31], v128, s[14:15] offset:3072
	global_load_dwordx4 v[32:35], v129, s[14:15]
	global_load_dwordx4 v[36:39], v129, s[14:15] offset:1024
	global_load_dwordx4 v[40:43], v129, s[14:15] offset:2048
	global_load_dwordx4 v[44:47], v129, s[14:15] offset:3072
	s_waitcnt vmcnt(8)
	v_pk_mul_f32 v[114:115], v[48:49], v[48:49]
	v_pk_fma_f32 v[114:115], v[50:51], v[50:51], v[114:115]
	v_pk_fma_f32 v[114:115], v[52:53], v[52:53], v[114:115]
	v_pk_fma_f32 v[114:115], v[54:55], v[54:55], v[114:115]
	v_pk_fma_f32 v[114:115], v[56:57], v[56:57], v[114:115]
	v_pk_fma_f32 v[114:115], v[58:59], v[58:59], v[114:115]
	v_pk_fma_f32 v[114:115], v[60:61], v[60:61], v[114:115]
	v_pk_fma_f32 v[114:115], v[62:63], v[62:63], v[114:115]
	v_pk_mul_f32 v[116:117], v[64:65], v[64:65]
	v_pk_fma_f32 v[116:117], v[66:67], v[66:67], v[116:117]
	v_pk_fma_f32 v[116:117], v[68:69], v[68:69], v[116:117]
	v_pk_fma_f32 v[116:117], v[70:71], v[70:71], v[116:117]
	v_pk_fma_f32 v[116:117], v[72:73], v[72:73], v[116:117]
	v_pk_fma_f32 v[116:117], v[74:75], v[74:75], v[116:117]
	v_pk_fma_f32 v[116:117], v[76:77], v[76:77], v[116:117]
	v_pk_fma_f32 v[116:117], v[78:79], v[78:79], v[116:117]
	v_add_f32_e32 v112, v114, v115
	v_add_f32_e32 v113, v116, v117
	ds_bpermute_b32 v114, v132, v112
	ds_bpermute_b32 v115, v132, v113
	s_waitcnt lgkmcnt(0)
	v_add_f32_e32 v112, v112, v114
	v_add_f32_e32 v113, v113, v115
	ds_bpermute_b32 v114, v133, v112
	ds_bpermute_b32 v115, v133, v113
	s_waitcnt lgkmcnt(0)
	v_add_f32_e32 v112, v112, v114
	v_add_f32_e32 v113, v113, v115
	ds_bpermute_b32 v114, v134, v112
	ds_bpermute_b32 v115, v134, v113
	s_waitcnt lgkmcnt(0)
	v_add_f32_e32 v112, v112, v114
	v_add_f32_e32 v113, v113, v115
	ds_bpermute_b32 v114, v135, v112
	ds_bpermute_b32 v115, v135, v113
	s_waitcnt lgkmcnt(0)
	v_add_f32_e32 v112, v112, v114
	v_add_f32_e32 v113, v113, v115
	ds_bpermute_b32 v114, v136, v112
	ds_bpermute_b32 v115, v136, v113
	s_waitcnt lgkmcnt(0)
	v_add_f32_e32 v112, v112, v114
	v_add_f32_e32 v113, v113, v115
	ds_bpermute_b32 v114, v137, v112
	ds_bpermute_b32 v115, v137, v113
	s_waitcnt lgkmcnt(0)
	v_add_f32_e32 v112, v112, v114
	v_add_f32_e32 v113, v113, v115
	v_fmamk_f32 v112, v112, 0x3a800000, v138
	v_mul_f32_e32 v114, 0x4b800000, v112
	v_cmp_gt_f32_e32 vcc, s29, v112
	s_nop 1
	v_cndmask_b32_e32 v112, v112, v114, vcc
	v_rsq_f32_e32 v139, v112
	s_nop 0
	v_mul_f32_e32 v114, 0x45800000, v139
	v_cndmask_b32_e32 v139, v139, v114, vcc
	v_fmamk_f32 v113, v113, 0x3a800000, v138
	v_mul_f32_e32 v114, 0x4b800000, v113
	v_cmp_gt_f32_e32 vcc, s29, v113
	s_nop 1
	v_cndmask_b32_e32 v113, v113, v114, vcc
	v_rsq_f32_e32 v140, v113
	s_nop 0
	v_mul_f32_e32 v114, 0x45800000, v140
	v_cndmask_b32_e32 v140, v140, v114, vcc
	v_add_f32_e32 v80, 1.0, v80
	v_add_f32_e32 v81, 1.0, v81
	v_add_f32_e32 v82, 1.0, v82
	v_add_f32_e32 v83, 1.0, v83
	v_add_f32_e32 v84, 1.0, v84
	v_add_f32_e32 v85, 1.0, v85
	v_add_f32_e32 v86, 1.0, v86
	v_add_f32_e32 v87, 1.0, v87
	v_add_f32_e32 v88, 1.0, v88
	v_add_f32_e32 v89, 1.0, v89
	v_add_f32_e32 v90, 1.0, v90
	v_add_f32_e32 v91, 1.0, v91
	v_add_f32_e32 v92, 1.0, v92
	v_add_f32_e32 v93, 1.0, v93
	v_add_f32_e32 v94, 1.0, v94
	v_add_f32_e32 v95, 1.0, v95
	v_mul_f32_e32 v48, v48, v139
	v_mul_f32_e32 v48, v0, v48
	v_fma_f32 v48, v80, v48, v96
	v_mul_f32_e32 v49, v49, v139
	v_mul_f32_e32 v49, v1, v49
	v_fma_f32 v49, v81, v49, v97
	v_mul_f32_e32 v50, v50, v139
	v_mul_f32_e32 v50, v2, v50
	v_fma_f32 v50, v82, v50, v98
	v_mul_f32_e32 v51, v51, v139
	v_mul_f32_e32 v51, v3, v51
	v_fma_f32 v51, v83, v51, v99
	v_cvt_pk_bf16_f32 v116, v48, v49
	v_cvt_pk_bf16_f32 v117, v50, v51
	global_store_dwordx2 v130, v[116:117], s[10:11]
	s_nop 0
	v_mul_f32_e32 v52, v52, v139
	v_mul_f32_e32 v52, v4, v52
	v_fma_f32 v52, v84, v52, v100
	v_mul_f32_e32 v53, v53, v139
	v_mul_f32_e32 v53, v5, v53
	v_fma_f32 v53, v85, v53, v101
	v_mul_f32_e32 v54, v54, v139
	v_mul_f32_e32 v54, v6, v54
	v_fma_f32 v54, v86, v54, v102
	v_mul_f32_e32 v55, v55, v139
	v_mul_f32_e32 v55, v7, v55
	v_fma_f32 v55, v87, v55, v103
	v_cvt_pk_bf16_f32 v116, v52, v53
	v_cvt_pk_bf16_f32 v117, v54, v55
	global_store_dwordx2 v130, v[116:117], s[10:11] offset:512
	s_nop 0
	v_mul_f32_e32 v56, v56, v139
	v_mul_f32_e32 v56, v8, v56
	v_fma_f32 v56, v88, v56, v104
	v_mul_f32_e32 v57, v57, v139
	v_mul_f32_e32 v57, v9, v57
	v_fma_f32 v57, v89, v57, v105
	v_mul_f32_e32 v58, v58, v139
	v_mul_f32_e32 v58, v10, v58
	v_fma_f32 v58, v90, v58, v106
	v_mul_f32_e32 v59, v59, v139
	v_mul_f32_e32 v59, v11, v59
	v_fma_f32 v59, v91, v59, v107
	v_cvt_pk_bf16_f32 v116, v56, v57
	v_cvt_pk_bf16_f32 v117, v58, v59
	global_store_dwordx2 v130, v[116:117], s[10:11] offset:1024
	s_nop 0
	v_mul_f32_e32 v60, v60, v139
	v_mul_f32_e32 v60, v12, v60
	v_fma_f32 v60, v92, v60, v108
	v_mul_f32_e32 v61, v61, v139
	v_mul_f32_e32 v61, v13, v61
	v_fma_f32 v61, v93, v61, v109
	v_mul_f32_e32 v62, v62, v139
	v_mul_f32_e32 v62, v14, v62
	v_fma_f32 v62, v94, v62, v110
	v_mul_f32_e32 v63, v63, v139
	v_mul_f32_e32 v63, v15, v63
	v_fma_f32 v63, v95, v63, v111
	v_cvt_pk_bf16_f32 v116, v60, v61
	v_cvt_pk_bf16_f32 v117, v62, v63
	global_store_dwordx2 v130, v[116:117], s[10:11] offset:1536
	s_nop 0
	v_mul_f32_e32 v64, v64, v140
	v_mul_f32_e32 v64, v0, v64
	v_fma_f32 v64, v80, v64, v96
	v_mul_f32_e32 v65, v65, v140
	v_mul_f32_e32 v65, v1, v65
	v_fma_f32 v65, v81, v65, v97
	v_mul_f32_e32 v66, v66, v140
	v_mul_f32_e32 v66, v2, v66
	v_fma_f32 v66, v82, v66, v98
	v_mul_f32_e32 v67, v67, v140
	v_mul_f32_e32 v67, v3, v67
	v_fma_f32 v67, v83, v67, v99
	v_cvt_pk_bf16_f32 v116, v64, v65
	v_cvt_pk_bf16_f32 v117, v66, v67
	global_store_dwordx2 v130, v[116:117], s[10:11] offset:2048
	s_nop 0
	v_mul_f32_e32 v68, v68, v140
	v_mul_f32_e32 v68, v4, v68
	v_fma_f32 v68, v84, v68, v100
	v_mul_f32_e32 v69, v69, v140
	v_mul_f32_e32 v69, v5, v69
	v_fma_f32 v69, v85, v69, v101
	v_mul_f32_e32 v70, v70, v140
	v_mul_f32_e32 v70, v6, v70
	v_fma_f32 v70, v86, v70, v102
	v_mul_f32_e32 v71, v71, v140
	v_mul_f32_e32 v71, v7, v71
	v_fma_f32 v71, v87, v71, v103
	v_cvt_pk_bf16_f32 v116, v68, v69
	v_cvt_pk_bf16_f32 v117, v70, v71
	global_store_dwordx2 v130, v[116:117], s[10:11] offset:2560
	s_nop 0
	v_mul_f32_e32 v72, v72, v140
	v_mul_f32_e32 v72, v8, v72
	v_fma_f32 v72, v88, v72, v104
	v_mul_f32_e32 v73, v73, v140
	v_mul_f32_e32 v73, v9, v73
	v_fma_f32 v73, v89, v73, v105
	v_mul_f32_e32 v74, v74, v140
	v_mul_f32_e32 v74, v10, v74
	v_fma_f32 v74, v90, v74, v106
	v_mul_f32_e32 v75, v75, v140
	v_mul_f32_e32 v75, v11, v75
	v_fma_f32 v75, v91, v75, v107
	v_cvt_pk_bf16_f32 v116, v72, v73
	v_cvt_pk_bf16_f32 v117, v74, v75
	global_store_dwordx2 v130, v[116:117], s[10:11] offset:3072
	s_nop 0
	v_mul_f32_e32 v76, v76, v140
	v_mul_f32_e32 v76, v12, v76
	v_fma_f32 v76, v92, v76, v108
	v_mul_f32_e32 v77, v77, v140
	v_mul_f32_e32 v77, v13, v77
	v_fma_f32 v77, v93, v77, v109
	v_mul_f32_e32 v78, v78, v140
	v_mul_f32_e32 v78, v14, v78
	v_fma_f32 v78, v94, v78, v110
	v_mul_f32_e32 v79, v79, v140
	v_mul_f32_e32 v79, v15, v79
	v_fma_f32 v79, v95, v79, v111
	v_cvt_pk_bf16_f32 v116, v76, v77
	v_cvt_pk_bf16_f32 v117, v78, v79
	global_store_dwordx2 v130, v[116:117], s[10:11] offset:3584
	s_nop 0
	s_mov_b32 s2, s12
	s_branch .Lp1x_top0
.Lp1x_last1:
	s_waitcnt vmcnt(0)
	v_pk_mul_f32 v[114:115], v[48:49], v[48:49]
	v_pk_fma_f32 v[114:115], v[50:51], v[50:51], v[114:115]
	v_pk_fma_f32 v[114:115], v[52:53], v[52:53], v[114:115]
	v_pk_fma_f32 v[114:115], v[54:55], v[54:55], v[114:115]
	v_pk_fma_f32 v[114:115], v[56:57], v[56:57], v[114:115]
	v_pk_fma_f32 v[114:115], v[58:59], v[58:59], v[114:115]
	v_pk_fma_f32 v[114:115], v[60:61], v[60:61], v[114:115]
	v_pk_fma_f32 v[114:115], v[62:63], v[62:63], v[114:115]
	v_pk_mul_f32 v[116:117], v[64:65], v[64:65]
	v_pk_fma_f32 v[116:117], v[66:67], v[66:67], v[116:117]
	v_pk_fma_f32 v[116:117], v[68:69], v[68:69], v[116:117]
	v_pk_fma_f32 v[116:117], v[70:71], v[70:71], v[116:117]
	v_pk_fma_f32 v[116:117], v[72:73], v[72:73], v[116:117]
	v_pk_fma_f32 v[116:117], v[74:75], v[74:75], v[116:117]
	v_pk_fma_f32 v[116:117], v[76:77], v[76:77], v[116:117]
	v_pk_fma_f32 v[116:117], v[78:79], v[78:79], v[116:117]
	v_add_f32_e32 v112, v114, v115
	v_add_f32_e32 v113, v116, v117
	ds_bpermute_b32 v114, v132, v112
	ds_bpermute_b32 v115, v132, v113
	s_waitcnt lgkmcnt(0)
	v_add_f32_e32 v112, v112, v114
	v_add_f32_e32 v113, v113, v115
	ds_bpermute_b32 v114, v133, v112
	ds_bpermute_b32 v115, v133, v113
	s_waitcnt lgkmcnt(0)
	v_add_f32_e32 v112, v112, v114
	v_add_f32_e32 v113, v113, v115
	ds_bpermute_b32 v114, v134, v112
	ds_bpermute_b32 v115, v134, v113
	s_waitcnt lgkmcnt(0)
	v_add_f32_e32 v112, v112, v114
	v_add_f32_e32 v113, v113, v115
	ds_bpermute_b32 v114, v135, v112
	ds_bpermute_b32 v115, v135, v113
	s_waitcnt lgkmcnt(0)
	v_add_f32_e32 v112, v112, v114
	v_add_f32_e32 v113, v113, v115
	ds_bpermute_b32 v114, v136, v112
	ds_bpermute_b32 v115, v136, v113
	s_waitcnt lgkmcnt(0)
	v_add_f32_e32 v112, v112, v114
	v_add_f32_e32 v113, v113, v115
	ds_bpermute_b32 v114, v137, v112
	ds_bpermute_b32 v115, v137, v113
	s_waitcnt lgkmcnt(0)
	v_add_f32_e32 v112, v112, v114
	v_add_f32_e32 v113, v113, v115
	v_fmamk_f32 v112, v112, 0x3a800000, v138
	v_mul_f32_e32 v114, 0x4b800000, v112
	v_cmp_gt_f32_e32 vcc, s29, v112
	s_nop 1
	v_cndmask_b32_e32 v112, v112, v114, vcc
	v_rsq_f32_e32 v139, v112
	s_nop 0
	v_mul_f32_e32 v114, 0x45800000, v139
	v_cndmask_b32_e32 v139, v139, v114, vcc
	v_fmamk_f32 v113, v113, 0x3a800000, v138
	v_mul_f32_e32 v114, 0x4b800000, v113
	v_cmp_gt_f32_e32 vcc, s29, v113
	s_nop 1
	v_cndmask_b32_e32 v113, v113, v114, vcc
	v_rsq_f32_e32 v140, v113
	s_nop 0
	v_mul_f32_e32 v114, 0x45800000, v140
	v_cndmask_b32_e32 v140, v140, v114, vcc
	v_add_f32_e32 v80, 1.0, v80
	v_add_f32_e32 v81, 1.0, v81
	v_add_f32_e32 v82, 1.0, v82
	v_add_f32_e32 v83, 1.0, v83
	v_add_f32_e32 v84, 1.0, v84
	v_add_f32_e32 v85, 1.0, v85
	v_add_f32_e32 v86, 1.0, v86
	v_add_f32_e32 v87, 1.0, v87
	v_add_f32_e32 v88, 1.0, v88
	v_add_f32_e32 v89, 1.0, v89
	v_add_f32_e32 v90, 1.0, v90
	v_add_f32_e32 v91, 1.0, v91
	v_add_f32_e32 v92, 1.0, v92
	v_add_f32_e32 v93, 1.0, v93
	v_add_f32_e32 v94, 1.0, v94
	v_add_f32_e32 v95, 1.0, v95
	v_mul_f32_e32 v48, v48, v139
	v_mul_f32_e32 v48, v0, v48
	v_fma_f32 v48, v80, v48, v96
	v_mul_f32_e32 v49, v49, v139
	v_mul_f32_e32 v49, v1, v49
	v_fma_f32 v49, v81, v49, v97
	v_mul_f32_e32 v50, v50, v139
	v_mul_f32_e32 v50, v2, v50
	v_fma_f32 v50, v82, v50, v98
	v_mul_f32_e32 v51, v51, v139
	v_mul_f32_e32 v51, v3, v51
	v_fma_f32 v51, v83, v51, v99
	v_cvt_pk_bf16_f32 v116, v48, v49
	v_cvt_pk_bf16_f32 v117, v50, v51
	global_store_dwordx2 v130, v[116:117], s[10:11]
	s_nop 0
	v_mul_f32_e32 v52, v52, v139
	v_mul_f32_e32 v52, v4, v52
	v_fma_f32 v52, v84, v52, v100
	v_mul_f32_e32 v53, v53, v139
	v_mul_f32_e32 v53, v5, v53
	v_fma_f32 v53, v85, v53, v101
	v_mul_f32_e32 v54, v54, v139
	v_mul_f32_e32 v54, v6, v54
	v_fma_f32 v54, v86, v54, v102
	v_mul_f32_e32 v55, v55, v139
	v_mul_f32_e32 v55, v7, v55
	v_fma_f32 v55, v87, v55, v103
	v_cvt_pk_bf16_f32 v116, v52, v53
	v_cvt_pk_bf16_f32 v117, v54, v55
	global_store_dwordx2 v130, v[116:117], s[10:11] offset:512
	s_nop 0
	v_mul_f32_e32 v56, v56, v139
	v_mul_f32_e32 v56, v8, v56
	v_fma_f32 v56, v88, v56, v104
	v_mul_f32_e32 v57, v57, v139
	v_mul_f32_e32 v57, v9, v57
	v_fma_f32 v57, v89, v57, v105
	v_mul_f32_e32 v58, v58, v139
	v_mul_f32_e32 v58, v10, v58
	v_fma_f32 v58, v90, v58, v106
	v_mul_f32_e32 v59, v59, v139
	v_mul_f32_e32 v59, v11, v59
	v_fma_f32 v59, v91, v59, v107
	v_cvt_pk_bf16_f32 v116, v56, v57
	v_cvt_pk_bf16_f32 v117, v58, v59
	global_store_dwordx2 v130, v[116:117], s[10:11] offset:1024
	s_nop 0
	v_mul_f32_e32 v60, v60, v139
	v_mul_f32_e32 v60, v12, v60
	v_fma_f32 v60, v92, v60, v108
	v_mul_f32_e32 v61, v61, v139
	v_mul_f32_e32 v61, v13, v61
	v_fma_f32 v61, v93, v61, v109
	v_mul_f32_e32 v62, v62, v139
	v_mul_f32_e32 v62, v14, v62
	v_fma_f32 v62, v94, v62, v110
	v_mul_f32_e32 v63, v63, v139
	v_mul_f32_e32 v63, v15, v63
	v_fma_f32 v63, v95, v63, v111
	v_cvt_pk_bf16_f32 v116, v60, v61
	v_cvt_pk_bf16_f32 v117, v62, v63
	global_store_dwordx2 v130, v[116:117], s[10:11] offset:1536
	s_nop 0
	v_mul_f32_e32 v64, v64, v140
	v_mul_f32_e32 v64, v0, v64
	v_fma_f32 v64, v80, v64, v96
	v_mul_f32_e32 v65, v65, v140
	v_mul_f32_e32 v65, v1, v65
	v_fma_f32 v65, v81, v65, v97
	v_mul_f32_e32 v66, v66, v140
	v_mul_f32_e32 v66, v2, v66
	v_fma_f32 v66, v82, v66, v98
	v_mul_f32_e32 v67, v67, v140
	v_mul_f32_e32 v67, v3, v67
	v_fma_f32 v67, v83, v67, v99
	v_cvt_pk_bf16_f32 v116, v64, v65
	v_cvt_pk_bf16_f32 v117, v66, v67
	global_store_dwordx2 v130, v[116:117], s[10:11] offset:2048
	s_nop 0
	v_mul_f32_e32 v68, v68, v140
	v_mul_f32_e32 v68, v4, v68
	v_fma_f32 v68, v84, v68, v100
	v_mul_f32_e32 v69, v69, v140
	v_mul_f32_e32 v69, v5, v69
	v_fma_f32 v69, v85, v69, v101
	v_mul_f32_e32 v70, v70, v140
	v_mul_f32_e32 v70, v6, v70
	v_fma_f32 v70, v86, v70, v102
	v_mul_f32_e32 v71, v71, v140
	v_mul_f32_e32 v71, v7, v71
	v_fma_f32 v71, v87, v71, v103
	v_cvt_pk_bf16_f32 v116, v68, v69
	v_cvt_pk_bf16_f32 v117, v70, v71
	global_store_dwordx2 v130, v[116:117], s[10:11] offset:2560
	s_nop 0
	v_mul_f32_e32 v72, v72, v140
	v_mul_f32_e32 v72, v8, v72
	v_fma_f32 v72, v88, v72, v104
	v_mul_f32_e32 v73, v73, v140
	v_mul_f32_e32 v73, v9, v73
	v_fma_f32 v73, v89, v73, v105
	v_mul_f32_e32 v74, v74, v140
	v_mul_f32_e32 v74, v10, v74
	v_fma_f32 v74, v90, v74, v106
	v_mul_f32_e32 v75, v75, v140
	v_mul_f32_e32 v75, v11, v75
	v_fma_f32 v75, v91, v75, v107
	v_cvt_pk_bf16_f32 v116, v72, v73
	v_cvt_pk_bf16_f32 v117, v74, v75
	global_store_dwordx2 v130, v[116:117], s[10:11] offset:3072
	s_nop 0
	v_mul_f32_e32 v76, v76, v140
	v_mul_f32_e32 v76, v12, v76
	v_fma_f32 v76, v92, v76, v108
	v_mul_f32_e32 v77, v77, v140
	v_mul_f32_e32 v77, v13, v77
	v_fma_f32 v77, v93, v77, v109
	v_mul_f32_e32 v78, v78, v140
	v_mul_f32_e32 v78, v14, v78
	v_fma_f32 v78, v94, v78, v110
	v_mul_f32_e32 v79, v79, v140
	v_mul_f32_e32 v79, v15, v79
	v_fma_f32 v79, v95, v79, v111
	v_cvt_pk_bf16_f32 v116, v76, v77
	v_cvt_pk_bf16_f32 v117, v78, v79
	global_store_dwordx2 v130, v[116:117], s[10:11] offset:3584
	s_nop 0
	s_branch .LBB0_179

.LBB0_251:
	v_mov_b32_e32 v8, v193
	s_andn2_b64 vcc, exec, s[0:1]
	v_readfirstlane_b32 s2, v8
	s_cbranch_vccnz .LBB0_262
	v_lshlrev_b32_e32 v0, 4, v8
	v_add_u32_e32 v1, 0x2000, v0
	v_ashrrev_i32_e32 v2, 31, v1
	v_lshrrev_b32_e32 v2, 22, v2
	v_add_u32_e32 v2, v1, v2
	v_ashrrev_i32_e32 v9, 10, v2
	v_mul_i32_i24_e32 v2, 0x400, v9
	v_sub_u32_e32 v1, v1, v2
	v_lshrrev_b32_e32 v2, 4, v1
	v_bitop3_b32 v1, v2, v1, 32 bitop3:0x6c
	v_ashrrev_i32_e32 v2, 31, v1
	v_lshrrev_b32_e32 v2, 26, v2
	v_add_u32_e32 v2, v1, v2
	v_lshlrev_b32_e32 v3, 3, v9
	v_ashrrev_i32_e32 v10, 6, v2
	v_and_b32_e32 v3, -16, v3
	s_and_b32 s1, s81, 3
	v_add_u32_e32 v3, v10, v3
	s_or_b32 s62, s1, 12
	v_and_b32_e32 v4, 3, v10
	s_mov_b32 s1, 0x1fffe0
	v_lshrrev_b32_e32 v5, 2, v3
	v_lshlrev_b32_e32 v6, 1, v3
	v_and_b32_e32 v2, 0xc0, v2
	v_and_or_b32 v4, v3, s1, v4
	v_and_b32_e32 v5, 4, v5
	v_and_b32_e32 v6, 24, v6
	v_sub_u32_e32 v1, v1, v2
	v_mov_b32_e32 v2, 1
	v_or3_b32 v4, v4, v5, v6
	v_lshlrev_b32_e32 v5, 5, v9
	v_ashrrev_i16_sdwa v1, v2, sext(v1) dst_sel:DWORD dst_unused:UNUSED_PAD src0_sel:DWORD src1_sel:BYTE_0
	v_and_b32_e32 v5, 32, v5
	v_bfe_i32 v11, v1, 0, 16
	v_add_lshl_u32 v1, v5, v11, 1
	v_lshl_add_u32 v128, v4, 11, v1
	v_lshl_add_u32 v130, v3, 11, v1
	v_bfe_i32 v1, v8, 27, 1
	v_lshrrev_b32_e32 v1, 22, v1
	v_add_u32_e32 v1, v0, v1
	v_and_b32_e32 v1, 0xfffffc00, v1
	v_sub_u32_e32 v0, v0, v1
	v_lshrrev_b32_e32 v1, 4, v0
	v_ashrrev_i32_e32 v3, 31, v8
	v_bitop3_b32 v0, v1, v0, 32 bitop3:0x6c
	v_lshrrev_b32_e32 v3, 26, v3
	v_ashrrev_i32_e32 v1, 31, v0
	v_add_u32_e32 v3, v8, v3
	v_lshrrev_b32_e32 v1, 26, v1
	v_ashrrev_i32_e32 v13, 6, v3
	v_add_u32_e32 v1, v0, v1
	v_lshlrev_b32_e32 v3, 3, v13
	v_ashrrev_i32_e32 v12, 6, v1
	v_and_b32_e32 v3, -16, v3
	v_add_u32_e32 v3, v12, v3
	s_ashr_i32 s5, s2, 6
	v_and_b32_e32 v4, 3, v12
	v_lshrrev_b32_e32 v5, 2, v3
	v_lshlrev_b32_e32 v6, 1, v3
	v_and_b32_e32 v1, 0xc0, v1
	v_readlane_b32 s8, v241, 0
	s_ashr_i32 s4, s2, 8
	s_lshl_b32 s0, s5, 10
	s_ashr_i32 s63, s81, 2
	v_and_or_b32 v4, v3, s1, v4
	v_and_b32_e32 v5, 4, v5
	v_and_b32_e32 v6, 24, v6
	v_sub_u32_e32 v0, v0, v1
	s_lshl_b32 s1, s62, 19
	v_readlane_b32 s14, v241, 6
	v_readlane_b32 s22, v241, 14
	v_or3_b32 v4, v4, v5, v6
	v_lshlrev_b32_e32 v5, 5, v13
	v_ashrrev_i16_sdwa v0, v2, sext(v0) dst_sel:DWORD dst_unused:UNUSED_PAD src0_sel:DWORD src1_sel:BYTE_0
	v_readlane_b32 s15, v241, 7
	v_readlane_b32 s23, v241, 15
	s_add_u32 s14, s22, s1
	v_and_b32_e32 v5, 32, v5
	v_bfe_i32 v14, v0, 0, 16
	v_readlane_b32 s10, v241, 2
	s_addc_u32 s15, s23, 0
	s_lshl_b32 s1, s63, 8
	v_add_lshl_u32 v0, v5, v14, 1
	v_readlane_b32 s11, v241, 3
	s_add_i32 s3, s0, 0
	s_add_i32 s10, s1, 0x8000
	v_lshl_add_u32 v132, v4, 11, v0
	s_add_i32 m0, s3, 0x10000
	s_ashr_i32 s11, s10, 31
	global_load_lds_dwordx4 v132, s[14:15]
	s_add_i32 m0, s3, 0x12000
	s_lshl_b64 s[10:11], s[10:11], 11
	s_add_u32 s34, s94, s10
	v_lshl_add_u32 v134, v3, 11, v0
	v_readlane_b32 s12, v241, 4
	global_load_lds_dwordx4 v128, s[14:15]
	s_addc_u32 s35, s95, s11
	s_mov_b32 m0, s3
	s_add_i32 s10, s3, 0x2000
	v_readlane_b32 s13, v241, 5
	global_load_lds_dwordx4 v134, s[34:35]
	s_mov_b32 m0, s10
	s_add_u32 s12, s14, 0x40000
	global_load_lds_dwordx4 v130, s[34:35]
	s_addc_u32 s13, s15, 0
	s_add_i32 m0, s3, 0x14000
	v_mov_b32_e32 v137, 0
	global_load_lds_dwordx4 v132, s[12:13]
	s_add_i32 m0, s3, 0x16000
	v_mov_b32_e32 v133, v137
	global_load_lds_dwordx4 v128, s[12:13]
	s_add_i32 s12, s1, 0x8080
	s_ashr_i32 s13, s12, 31
	s_lshl_b64 s[12:13], s[12:13], 11
	s_add_u32 s44, s94, s12
	s_addc_u32 s45, s95, s13
	s_add_i32 s11, s3, 0x4000
	s_mov_b32 m0, s11
	s_add_i32 s12, s3, 0x6000
	global_load_lds_dwordx4 v134, s[44:45]
	s_mov_b32 m0, s12
	v_mov_b32_e32 v129, v137
	global_load_lds_dwordx4 v130, s[44:45]
	v_mov_b32_e32 v135, v137
	v_mov_b32_e32 v131, v137
	s_mov_b32 s1, 0
	v_lshl_add_u64 v[6:7], s[14:15], 0, v[132:133]
	v_lshl_add_u64 v[4:5], s[14:15], 0, v[128:129]
	v_lshl_add_u64 v[2:3], s[34:35], 0, v[134:135]
	s_cmp_lg_u32 s4, 1
	v_lshl_add_u64 v[0:1], s[34:35], 0, v[130:131]
	v_readlane_b32 s9, v241, 1
	v_readlane_b32 s16, v241, 8
	v_readlane_b32 s17, v241, 9
	v_readlane_b32 s18, v241, 10
	v_readlane_b32 s19, v241, 11
	v_readlane_b32 s20, v241, 12
	v_readlane_b32 s21, v241, 13
	s_cbranch_scc1 .LBB0_255
	s_barrier
